# M7 + multi-row prefetch (4 rows in flight) in P7 xq_row loops and P0 q8_row loop
# baseline (speedup 1.0000x reference)
.Lxqp0_entry:
	s_cmp_lt_i32 s34, 4
	s_cbranch_scc1 .LBB0_212
.Lxqp0_top:
	global_load_dword v104, v115, s[0:1]
	s_add_u32 s98, s0, s8
	s_addc_u32 s99, s1, s9
	global_load_dword v105, v115, s[98:99]
	s_add_u32 s98, s98, s8
	s_addc_u32 s99, s99, s9
	global_load_dword v106, v115, s[98:99]
	s_add_u32 s98, s98, s8
	s_addc_u32 s99, s99, s9
	global_load_dword v107, v115, s[98:99]
	global_load_dwordx4 v[20:23], v[2:3], off offset:-2048 nt
	global_load_dwordx4 v[28:31], v[2:3], off offset:-1024 nt
	global_load_dwordx4 v[36:39], v[2:3], off nt
	global_load_dwordx4 v[42:45], v[2:3], off offset:1024 nt
	v_lshl_add_u64 v[110:111], v[2:3], 0, s[12:13]
	global_load_dwordx4 v[56:59], v[110:111], off offset:-2048 nt
	global_load_dwordx4 v[60:63], v[110:111], off offset:-1024 nt
	global_load_dwordx4 v[64:67], v[110:111], off nt
	global_load_dwordx4 v[68:71], v[110:111], off offset:1024 nt
	v_lshl_add_u64 v[110:111], v[110:111], 0, s[12:13]
	global_load_dwordx4 v[72:75], v[110:111], off offset:-2048 nt
	global_load_dwordx4 v[76:79], v[110:111], off offset:-1024 nt
	global_load_dwordx4 v[80:83], v[110:111], off nt
	global_load_dwordx4 v[84:87], v[110:111], off offset:1024 nt
	v_lshl_add_u64 v[110:111], v[110:111], 0, s[12:13]
	global_load_dwordx4 v[88:91], v[110:111], off offset:-2048 nt
	global_load_dwordx4 v[92:95], v[110:111], off offset:-1024 nt
	global_load_dwordx4 v[96:99], v[110:111], off nt
	global_load_dwordx4 v[100:103], v[110:111], off offset:1024 nt
	s_waitcnt vmcnt(12)
	v_lshlrev_b32_e32 v19, 16, v20
	v_and_b32_e32 v18, 0xffff0000, v20
	v_max_f32_e64 v12, |v18|, |v18|
	v_max_f32_e64 v13, |v19|, |v19|
	v_lshlrev_b32_e32 v17, 16, v21
	v_and_b32_e32 v16, 0xffff0000, v21
	v_max_f32_e32 v12, v13, v12
	v_max_f32_e64 v13, |v16|, |v16|
	v_max_f32_e64 v14, |v17|, |v17|
	v_max_f32_e32 v13, v14, v13
	v_lshlrev_b32_e32 v15, 16, v22
	v_and_b32_e32 v14, 0xffff0000, v22
	v_max3_f32 v20, v12, 0, v13
	v_max_f32_e64 v12, |v14|, |v14|
	v_max_f32_e64 v13, |v15|, |v15|
	v_max_f32_e32 v21, v13, v12
	v_lshlrev_b32_e32 v13, 16, v23
	v_and_b32_e32 v12, 0xffff0000, v23
	v_max_f32_e64 v22, |v12|, |v12|
	v_max_f32_e64 v23, |v13|, |v13|
	v_max_f32_e32 v22, v23, v22
	v_lshlrev_b32_e32 v27, 16, v28
	v_and_b32_e32 v26, 0xffff0000, v28
	v_max3_f32 v20, v20, v21, v22
	v_max_f32_e64 v21, |v26|, |v26|
	v_max_f32_e64 v22, |v27|, |v27|
	v_lshlrev_b32_e32 v25, 16, v29
	v_and_b32_e32 v24, 0xffff0000, v29
	v_max_f32_e32 v21, v22, v21
	v_max_f32_e64 v22, |v24|, |v24|
	v_max_f32_e64 v23, |v25|, |v25|
	v_max_f32_e32 v22, v23, v22
	v_max3_f32 v28, v20, v21, v22
	v_lshlrev_b32_e32 v23, 16, v30
	v_and_b32_e32 v22, 0xffff0000, v30
	v_max_f32_e64 v20, |v22|, |v22|
	v_max_f32_e64 v21, |v23|, |v23|
	v_max_f32_e32 v29, v21, v20
	v_lshlrev_b32_e32 v21, 16, v31
	v_and_b32_e32 v20, 0xffff0000, v31
	v_max_f32_e64 v30, |v20|, |v20|
	v_max_f32_e64 v31, |v21|, |v21|
	v_max_f32_e32 v30, v31, v30
	v_lshlrev_b32_e32 v35, 16, v36
	v_and_b32_e32 v34, 0xffff0000, v36
	v_max3_f32 v28, v28, v29, v30
	v_max_f32_e64 v29, |v34|, |v34|
	v_max_f32_e64 v30, |v35|, |v35|
	v_lshlrev_b32_e32 v33, 16, v37
	v_and_b32_e32 v32, 0xffff0000, v37
	v_max_f32_e32 v29, v30, v29
	v_max_f32_e64 v30, |v32|, |v32|
	v_max_f32_e64 v31, |v33|, |v33|
	v_max_f32_e32 v30, v31, v30
	v_max3_f32 v36, v28, v29, v30
	v_lshlrev_b32_e32 v31, 16, v38
	v_and_b32_e32 v30, 0xffff0000, v38
	v_max_f32_e64 v28, |v30|, |v30|
	v_max_f32_e64 v29, |v31|, |v31|
	v_max_f32_e32 v37, v29, v28
	v_lshlrev_b32_e32 v29, 16, v39
	v_and_b32_e32 v28, 0xffff0000, v39
	v_max_f32_e64 v38, |v28|, |v28|
	v_max_f32_e64 v39, |v29|, |v29|
	v_max_f32_e32 v38, v39, v38
	v_max3_f32 v40, v36, v37, v38
	v_lshlrev_b32_e32 v37, 16, v42
	v_and_b32_e32 v36, 0xffff0000, v42
	v_max_f32_e64 v38, |v36|, |v36|
	v_max_f32_e64 v39, |v37|, |v37|
	v_max_f32_e32 v41, v39, v38
	v_lshlrev_b32_e32 v39, 16, v43
	v_and_b32_e32 v38, 0xffff0000, v43
	v_max_f32_e64 v42, |v38|, |v38|
	v_max_f32_e64 v43, |v39|, |v39|
	v_max_f32_e32 v42, v43, v42
	v_max3_f32 v46, v40, v41, v42
	v_lshlrev_b32_e32 v42, 16, v44
	v_and_b32_e32 v40, 0xffff0000, v44
	v_max_f32_e64 v41, |v40|, |v40|
	v_max_f32_e64 v43, |v42|, |v42|
	v_max_f32_e32 v44, v43, v41
	v_lshlrev_b32_e32 v43, 16, v45
	v_and_b32_e32 v41, 0xffff0000, v45
	v_max_f32_e64 v45, |v41|, |v41|
	v_max_f32_e64 v47, |v43|, |v43|
	v_max_f32_e32 v45, v47, v45
	v_max3_f32 v44, v46, v44, v45
	ds_bpermute_b32 v45, v6, v44
	s_waitcnt lgkmcnt(0)
	v_max_f32_e32 v45, v45, v45
	v_max_f32_e32 v44, v44, v45
	ds_bpermute_b32 v45, v7, v44
	s_waitcnt lgkmcnt(0)
	v_max_f32_e32 v45, v45, v45
	v_max_f32_e32 v44, v44, v45
	ds_bpermute_b32 v45, v8, v44
	s_waitcnt lgkmcnt(0)
	v_max_f32_e32 v45, v45, v45
	v_max_f32_e32 v44, v44, v45
	ds_bpermute_b32 v45, v9, v44
	s_waitcnt lgkmcnt(0)
	v_max_f32_e32 v45, v45, v45
	v_max_f32_e32 v44, v44, v45
	ds_bpermute_b32 v45, v10, v44
	s_waitcnt lgkmcnt(0)
	v_max_f32_e32 v45, v45, v45
	v_max_f32_e32 v44, v44, v45
	ds_bpermute_b32 v45, v11, v44
	s_waitcnt lgkmcnt(0)
	v_max3_f32 v44, v44, v45, s73
	s_and_saveexec_b64 s[10:11], s[36:37]
	s_cbranch_execz .Lxqp0_C0
	v_mov_b32_e32 v45, v104
	v_mul_f32_e32 v46, 0x3c010204, v44
	v_mul_f32_e32 v45, v45, v46
	v_mov_b32_e32 v46, 0x65b2000
	global_store_dword v46, v45, s[0:1]
.Lxqp0_C0:
	s_or_b64 exec, exec, s[10:11]
	v_div_scale_f32 v45, s[10:11], v44, v44, s47
	v_rcp_f32_e32 v46, v45
	v_div_scale_f32 v47, vcc, s47, v44, s47
	s_add_i32 s34, s34, -1
	v_fma_f32 v48, -v45, v46, 1.0
	v_fmac_f32_e32 v46, v48, v46
	v_mul_f32_e32 v48, v47, v46
	v_fma_f32 v49, -v45, v48, v47
	v_fmac_f32_e32 v48, v49, v46
	v_fma_f32 v45, -v45, v48, v47
	v_div_fmas_f32 v45, v45, v46, v48
	v_div_fixup_f32 v44, v45, v44, s47
	v_mul_f32_e32 v18, v44, v18
	v_mul_f32_e32 v17, v44, v17
	v_mul_f32_e32 v19, v44, v19
	v_rndne_f32_e32 v18, v18
	v_rndne_f32_e32 v17, v17
	v_mul_f32_e32 v16, v44, v16
	v_mul_f32_e32 v15, v44, v15
	v_mul_f32_e32 v12, v44, v12
	v_rndne_f32_e32 v19, v19
	v_cvt_i32_f32_e32 v18, v18
	v_cvt_i32_f32_e32 v17, v17
	v_rndne_f32_e32 v16, v16
	v_rndne_f32_e32 v15, v15
	v_rndne_f32_e32 v12, v12
	v_cvt_i32_f32_e32 v19, v19
	v_cvt_i32_f32_e32 v16, v16
	v_cvt_i32_f32_e32 v15, v15
	v_mul_f32_e32 v14, v44, v14
	v_mul_f32_e32 v13, v44, v13
	v_cvt_i32_f32_e32 v12, v12
	v_rndne_f32_e32 v14, v14
	v_rndne_f32_e32 v13, v13
	v_cvt_i32_f32_e32 v45, v14
	v_cvt_i32_f32_e32 v13, v13
	v_med3_i32 v18, v18, s71, v235
	v_med3_i32 v17, v17, s71, v235
	v_med3_i32 v19, v19, s71, v235
	v_lshlrev_b32_e32 v18, 8, v18
	v_lshlrev_b32_e32 v17, 16, v17
	v_med3_i32 v16, v16, s71, v235
	v_med3_i32 v15, v15, s71, v235
	v_med3_i32 v12, v12, s71, v235
	v_and_b32_e32 v17, 0xff0000, v17
	v_lshlrev_b32_e32 v16, 24, v16
	v_perm_b32 v14, v18, v19, s49
	v_perm_b32 v12, v12, v15, s48
	v_mul_f32_e32 v15, v44, v27
	v_or3_b32 v14, v14, v16, v17
	v_med3_i32 v16, v45, s71, v235
	v_med3_i32 v13, v13, s71, v235
	v_rndne_f32_e32 v15, v15
	v_lshlrev_b32_e32 v16, 8, v16
	v_lshlrev_b32_e32 v13, 16, v13
	v_cvt_i32_f32_e32 v17, v15
	v_mul_f32_e32 v15, v44, v26
	v_and_b32_e32 v16, 0xff00, v16
	v_and_b32_e32 v13, 0xff0000, v13
	v_rndne_f32_e32 v15, v15
	v_cvt_i32_f32_e32 v18, v15
	v_or3_b32 v15, v12, v16, v13
	global_store_dwordx2 v[4:5], v[14:15], off offset:-1024
	v_mul_f32_e32 v14, v44, v25
	v_rndne_f32_e32 v14, v14
	v_mul_f32_e32 v15, v44, v24
	v_cvt_i32_f32_e32 v14, v14
	v_rndne_f32_e32 v15, v15
	v_mul_f32_e32 v16, v44, v23
	v_cvt_i32_f32_e32 v15, v15
	v_rndne_f32_e32 v16, v16
	v_cvt_i32_f32_e32 v16, v16
	v_med3_i32 v13, v18, s71, v235
	v_med3_i32 v14, v14, s71, v235
	v_med3_i32 v12, v17, s71, v235
	v_lshlrev_b32_e32 v13, 8, v13
	v_lshlrev_b32_e32 v14, 16, v14
	v_med3_i32 v15, v15, s71, v235
	v_and_b32_e32 v14, 0xff0000, v14
	v_lshlrev_b32_e32 v15, 24, v15
	v_perm_b32 v12, v13, v12, s49
	v_med3_i32 v13, v16, s71, v235
	v_mul_f32_e32 v16, v44, v20
	v_mul_f32_e32 v17, v44, v22
	v_or3_b32 v12, v12, v15, v14
	v_mul_f32_e32 v15, v44, v21
	v_rndne_f32_e32 v16, v16
	v_rndne_f32_e32 v17, v17
	v_rndne_f32_e32 v15, v15
	v_cvt_i32_f32_e32 v16, v16
	v_cvt_i32_f32_e32 v17, v17
	v_cvt_i32_f32_e32 v15, v15
	s_add_u32 s0, s0, s8
	v_med3_i32 v16, v16, s71, v235
	v_med3_i32 v14, v17, s71, v235
	v_med3_i32 v15, v15, s71, v235
	v_perm_b32 v13, v16, v13, s48
	v_mul_f32_e32 v16, v44, v35
	v_lshlrev_b32_e32 v14, 8, v14
	v_lshlrev_b32_e32 v15, 16, v15
	v_rndne_f32_e32 v16, v16
	v_and_b32_e32 v14, 0xff00, v14
	v_and_b32_e32 v15, 0xff0000, v15
	v_cvt_i32_f32_e32 v16, v16
	v_mul_f32_e32 v17, v44, v34
	v_or3_b32 v13, v13, v14, v15
	v_mul_f32_e32 v14, v44, v33
	v_rndne_f32_e32 v17, v17
	v_rndne_f32_e32 v14, v14
	v_mul_f32_e32 v15, v44, v32
	v_cvt_i32_f32_e32 v17, v17
	v_cvt_i32_f32_e32 v14, v14
	v_rndne_f32_e32 v15, v15
	global_store_dwordx2 v[4:5], v[12:13], off offset:-512
	v_med3_i32 v12, v16, s71, v235
	v_cvt_i32_f32_e32 v15, v15
	v_mul_f32_e32 v16, v44, v31
	v_rndne_f32_e32 v16, v16
	v_cvt_i32_f32_e32 v16, v16
	v_med3_i32 v13, v17, s71, v235
	v_med3_i32 v14, v14, s71, v235
	v_lshlrev_b32_e32 v13, 8, v13
	v_lshlrev_b32_e32 v14, 16, v14
	v_med3_i32 v15, v15, s71, v235
	v_and_b32_e32 v14, 0xff0000, v14
	v_lshlrev_b32_e32 v15, 24, v15
	v_perm_b32 v12, v13, v12, s49
	v_mul_f32_e32 v17, v44, v30
	v_or3_b32 v12, v12, v15, v14
	v_med3_i32 v13, v16, s71, v235
	v_mul_f32_e32 v15, v44, v29
	v_mul_f32_e32 v16, v44, v28
	v_rndne_f32_e32 v17, v17
	v_rndne_f32_e32 v15, v15
	v_rndne_f32_e32 v16, v16
	v_cvt_i32_f32_e32 v17, v17
	v_cvt_i32_f32_e32 v15, v15
	v_cvt_i32_f32_e32 v16, v16
	s_addc_u32 s1, s1, s9
	v_med3_i32 v14, v17, s71, v235
	v_med3_i32 v15, v15, s71, v235
	v_med3_i32 v16, v16, s71, v235
	v_lshlrev_b32_e32 v14, 8, v14
	v_lshlrev_b32_e32 v15, 16, v15
	v_perm_b32 v13, v16, v13, s48
	v_mul_f32_e32 v16, v44, v37
	v_and_b32_e32 v14, 0xff00, v14
	v_and_b32_e32 v15, 0xff0000, v15
	v_rndne_f32_e32 v16, v16
	v_cvt_i32_f32_e32 v16, v16
	v_mul_f32_e32 v17, v44, v36
	v_or3_b32 v13, v13, v14, v15
	v_mul_f32_e32 v14, v44, v39
	v_rndne_f32_e32 v17, v17
	v_rndne_f32_e32 v14, v14
	v_mul_f32_e32 v15, v44, v38
	v_cvt_i32_f32_e32 v17, v17
	v_cvt_i32_f32_e32 v14, v14
	v_rndne_f32_e32 v15, v15
	v_cvt_i32_f32_e32 v15, v15
	global_store_dwordx2 v[4:5], v[12:13], off
	v_med3_i32 v12, v16, s71, v235
	v_mul_f32_e32 v16, v44, v42
	v_rndne_f32_e32 v16, v16
	v_med3_i32 v13, v17, s71, v235
	v_med3_i32 v14, v14, s71, v235
	v_cvt_i32_f32_e32 v16, v16
	v_lshlrev_b32_e32 v13, 8, v13
	v_lshlrev_b32_e32 v14, 16, v14
	v_med3_i32 v15, v15, s71, v235
	v_and_b32_e32 v14, 0xff0000, v14
	v_lshlrev_b32_e32 v15, 24, v15
	v_perm_b32 v12, v13, v12, s49
	v_mul_f32_e32 v17, v44, v40
	v_or3_b32 v12, v12, v15, v14
	v_mul_f32_e32 v15, v44, v43
	v_rndne_f32_e32 v17, v17
	v_med3_i32 v13, v16, s71, v235
	v_rndne_f32_e32 v15, v15
	v_mul_f32_e32 v16, v44, v41
	v_cvt_i32_f32_e32 v17, v17
	v_cvt_i32_f32_e32 v15, v15
	v_rndne_f32_e32 v16, v16
	v_cvt_i32_f32_e32 v16, v16
	v_med3_i32 v14, v17, s71, v235
	v_med3_i32 v15, v15, s71, v235
	v_lshlrev_b32_e32 v14, 8, v14
	v_lshlrev_b32_e32 v15, 16, v15
	v_med3_i32 v16, v16, s71, v235
	v_and_b32_e32 v14, 0xff00, v14
	v_and_b32_e32 v15, 0xff0000, v15
	v_perm_b32 v13, v16, v13, s48
	v_or3_b32 v13, v13, v14, v15
	global_store_dwordx2 v[4:5], v[12:13], off offset:512
	v_lshl_add_u64 v[2:3], v[2:3], 0, s[12:13]
	v_lshl_add_u64 v[4:5], v[4:5], 0, s[6:7]
	s_waitcnt vmcnt(12)
	v_mov_b32_e32 v20, v56
	v_mov_b32_e32 v21, v57
	v_mov_b32_e32 v22, v58
	v_mov_b32_e32 v23, v59
	v_mov_b32_e32 v28, v60
	v_mov_b32_e32 v29, v61
	v_mov_b32_e32 v30, v62
	v_mov_b32_e32 v31, v63
	v_mov_b32_e32 v36, v64
	v_mov_b32_e32 v37, v65
	v_mov_b32_e32 v38, v66
	v_mov_b32_e32 v39, v67
	v_mov_b32_e32 v42, v68
	v_mov_b32_e32 v43, v69
	v_mov_b32_e32 v44, v70
	v_mov_b32_e32 v45, v71
	v_lshlrev_b32_e32 v19, 16, v20
	v_and_b32_e32 v18, 0xffff0000, v20
	v_max_f32_e64 v12, |v18|, |v18|
	v_max_f32_e64 v13, |v19|, |v19|
	v_lshlrev_b32_e32 v17, 16, v21
	v_and_b32_e32 v16, 0xffff0000, v21
	v_max_f32_e32 v12, v13, v12
	v_max_f32_e64 v13, |v16|, |v16|
	v_max_f32_e64 v14, |v17|, |v17|
	v_max_f32_e32 v13, v14, v13
	v_lshlrev_b32_e32 v15, 16, v22
	v_and_b32_e32 v14, 0xffff0000, v22
	v_max3_f32 v20, v12, 0, v13
	v_max_f32_e64 v12, |v14|, |v14|
	v_max_f32_e64 v13, |v15|, |v15|
	v_max_f32_e32 v21, v13, v12
	v_lshlrev_b32_e32 v13, 16, v23
	v_and_b32_e32 v12, 0xffff0000, v23
	v_max_f32_e64 v22, |v12|, |v12|
	v_max_f32_e64 v23, |v13|, |v13|
	v_max_f32_e32 v22, v23, v22
	v_lshlrev_b32_e32 v27, 16, v28
	v_and_b32_e32 v26, 0xffff0000, v28
	v_max3_f32 v20, v20, v21, v22
	v_max_f32_e64 v21, |v26|, |v26|
	v_max_f32_e64 v22, |v27|, |v27|
	v_lshlrev_b32_e32 v25, 16, v29
	v_and_b32_e32 v24, 0xffff0000, v29
	v_max_f32_e32 v21, v22, v21
	v_max_f32_e64 v22, |v24|, |v24|
	v_max_f32_e64 v23, |v25|, |v25|
	v_max_f32_e32 v22, v23, v22
	v_max3_f32 v28, v20, v21, v22
	v_lshlrev_b32_e32 v23, 16, v30
	v_and_b32_e32 v22, 0xffff0000, v30
	v_max_f32_e64 v20, |v22|, |v22|
	v_max_f32_e64 v21, |v23|, |v23|
	v_max_f32_e32 v29, v21, v20
	v_lshlrev_b32_e32 v21, 16, v31
	v_and_b32_e32 v20, 0xffff0000, v31
	v_max_f32_e64 v30, |v20|, |v20|
	v_max_f32_e64 v31, |v21|, |v21|
	v_max_f32_e32 v30, v31, v30
	v_lshlrev_b32_e32 v35, 16, v36
	v_and_b32_e32 v34, 0xffff0000, v36
	v_max3_f32 v28, v28, v29, v30
	v_max_f32_e64 v29, |v34|, |v34|
	v_max_f32_e64 v30, |v35|, |v35|
	v_lshlrev_b32_e32 v33, 16, v37
	v_and_b32_e32 v32, 0xffff0000, v37
	v_max_f32_e32 v29, v30, v29
	v_max_f32_e64 v30, |v32|, |v32|
	v_max_f32_e64 v31, |v33|, |v33|
	v_max_f32_e32 v30, v31, v30
	v_max3_f32 v36, v28, v29, v30
	v_lshlrev_b32_e32 v31, 16, v38
	v_and_b32_e32 v30, 0xffff0000, v38
	v_max_f32_e64 v28, |v30|, |v30|
	v_max_f32_e64 v29, |v31|, |v31|
	v_max_f32_e32 v37, v29, v28
	v_lshlrev_b32_e32 v29, 16, v39
	v_and_b32_e32 v28, 0xffff0000, v39
	v_max_f32_e64 v38, |v28|, |v28|
	v_max_f32_e64 v39, |v29|, |v29|
	v_max_f32_e32 v38, v39, v38
	v_max3_f32 v40, v36, v37, v38
	v_lshlrev_b32_e32 v37, 16, v42
	v_and_b32_e32 v36, 0xffff0000, v42
	v_max_f32_e64 v38, |v36|, |v36|
	v_max_f32_e64 v39, |v37|, |v37|
	v_max_f32_e32 v41, v39, v38
	v_lshlrev_b32_e32 v39, 16, v43
	v_and_b32_e32 v38, 0xffff0000, v43
	v_max_f32_e64 v42, |v38|, |v38|
	v_max_f32_e64 v43, |v39|, |v39|
	v_max_f32_e32 v42, v43, v42
	v_max3_f32 v46, v40, v41, v42
	v_lshlrev_b32_e32 v42, 16, v44
	v_and_b32_e32 v40, 0xffff0000, v44
	v_max_f32_e64 v41, |v40|, |v40|
	v_max_f32_e64 v43, |v42|, |v42|
	v_max_f32_e32 v44, v43, v41
	v_lshlrev_b32_e32 v43, 16, v45
	v_and_b32_e32 v41, 0xffff0000, v45
	v_max_f32_e64 v45, |v41|, |v41|
	v_max_f32_e64 v47, |v43|, |v43|
	v_max_f32_e32 v45, v47, v45
	v_max3_f32 v44, v46, v44, v45
	ds_bpermute_b32 v45, v6, v44
	s_waitcnt lgkmcnt(0)
	v_max_f32_e32 v45, v45, v45
	v_max_f32_e32 v44, v44, v45
	ds_bpermute_b32 v45, v7, v44
	s_waitcnt lgkmcnt(0)
	v_max_f32_e32 v45, v45, v45
	v_max_f32_e32 v44, v44, v45
	ds_bpermute_b32 v45, v8, v44
	s_waitcnt lgkmcnt(0)
	v_max_f32_e32 v45, v45, v45
	v_max_f32_e32 v44, v44, v45
	ds_bpermute_b32 v45, v9, v44
	s_waitcnt lgkmcnt(0)
	v_max_f32_e32 v45, v45, v45
	v_max_f32_e32 v44, v44, v45
	ds_bpermute_b32 v45, v10, v44
	s_waitcnt lgkmcnt(0)
	v_max_f32_e32 v45, v45, v45
	v_max_f32_e32 v44, v44, v45
	ds_bpermute_b32 v45, v11, v44
	s_waitcnt lgkmcnt(0)
	v_max3_f32 v44, v44, v45, s73
	s_and_saveexec_b64 s[10:11], s[36:37]
	s_cbranch_execz .Lxqp0_C1
	v_mov_b32_e32 v45, v105
	v_mul_f32_e32 v46, 0x3c010204, v44
	v_mul_f32_e32 v45, v45, v46
	v_mov_b32_e32 v46, 0x65b2000
	global_store_dword v46, v45, s[0:1]
.Lxqp0_C1:
	s_or_b64 exec, exec, s[10:11]
	v_div_scale_f32 v45, s[10:11], v44, v44, s47
	v_rcp_f32_e32 v46, v45
	v_div_scale_f32 v47, vcc, s47, v44, s47
	s_add_i32 s34, s34, -1
	v_fma_f32 v48, -v45, v46, 1.0
	v_fmac_f32_e32 v46, v48, v46
	v_mul_f32_e32 v48, v47, v46
	v_fma_f32 v49, -v45, v48, v47
	v_fmac_f32_e32 v48, v49, v46
	v_fma_f32 v45, -v45, v48, v47
	v_div_fmas_f32 v45, v45, v46, v48
	v_div_fixup_f32 v44, v45, v44, s47
	v_mul_f32_e32 v18, v44, v18
	v_mul_f32_e32 v17, v44, v17
	v_mul_f32_e32 v19, v44, v19
	v_rndne_f32_e32 v18, v18
	v_rndne_f32_e32 v17, v17
	v_mul_f32_e32 v16, v44, v16
	v_mul_f32_e32 v15, v44, v15
	v_mul_f32_e32 v12, v44, v12
	v_rndne_f32_e32 v19, v19
	v_cvt_i32_f32_e32 v18, v18
	v_cvt_i32_f32_e32 v17, v17
	v_rndne_f32_e32 v16, v16
	v_rndne_f32_e32 v15, v15
	v_rndne_f32_e32 v12, v12
	v_cvt_i32_f32_e32 v19, v19
	v_cvt_i32_f32_e32 v16, v16
	v_cvt_i32_f32_e32 v15, v15
	v_mul_f32_e32 v14, v44, v14
	v_mul_f32_e32 v13, v44, v13
	v_cvt_i32_f32_e32 v12, v12
	v_rndne_f32_e32 v14, v14
	v_rndne_f32_e32 v13, v13
	v_cvt_i32_f32_e32 v45, v14
	v_cvt_i32_f32_e32 v13, v13
	v_med3_i32 v18, v18, s71, v235
	v_med3_i32 v17, v17, s71, v235
	v_med3_i32 v19, v19, s71, v235
	v_lshlrev_b32_e32 v18, 8, v18
	v_lshlrev_b32_e32 v17, 16, v17
	v_med3_i32 v16, v16, s71, v235
	v_med3_i32 v15, v15, s71, v235
	v_med3_i32 v12, v12, s71, v235
	v_and_b32_e32 v17, 0xff0000, v17
	v_lshlrev_b32_e32 v16, 24, v16
	v_perm_b32 v14, v18, v19, s49
	v_perm_b32 v12, v12, v15, s48
	v_mul_f32_e32 v15, v44, v27
	v_or3_b32 v14, v14, v16, v17
	v_med3_i32 v16, v45, s71, v235
	v_med3_i32 v13, v13, s71, v235
	v_rndne_f32_e32 v15, v15
	v_lshlrev_b32_e32 v16, 8, v16
	v_lshlrev_b32_e32 v13, 16, v13
	v_cvt_i32_f32_e32 v17, v15
	v_mul_f32_e32 v15, v44, v26
	v_and_b32_e32 v16, 0xff00, v16
	v_and_b32_e32 v13, 0xff0000, v13
	v_rndne_f32_e32 v15, v15
	v_cvt_i32_f32_e32 v18, v15
	v_or3_b32 v15, v12, v16, v13
	global_store_dwordx2 v[4:5], v[14:15], off offset:-1024
	v_mul_f32_e32 v14, v44, v25
	v_rndne_f32_e32 v14, v14
	v_mul_f32_e32 v15, v44, v24
	v_cvt_i32_f32_e32 v14, v14
	v_rndne_f32_e32 v15, v15
	v_mul_f32_e32 v16, v44, v23
	v_cvt_i32_f32_e32 v15, v15
	v_rndne_f32_e32 v16, v16
	v_cvt_i32_f32_e32 v16, v16
	v_med3_i32 v13, v18, s71, v235
	v_med3_i32 v14, v14, s71, v235
	v_med3_i32 v12, v17, s71, v235
	v_lshlrev_b32_e32 v13, 8, v13
	v_lshlrev_b32_e32 v14, 16, v14
	v_med3_i32 v15, v15, s71, v235
	v_and_b32_e32 v14, 0xff0000, v14
	v_lshlrev_b32_e32 v15, 24, v15
	v_perm_b32 v12, v13, v12, s49
	v_med3_i32 v13, v16, s71, v235
	v_mul_f32_e32 v16, v44, v20
	v_mul_f32_e32 v17, v44, v22
	v_or3_b32 v12, v12, v15, v14
	v_mul_f32_e32 v15, v44, v21
	v_rndne_f32_e32 v16, v16
	v_rndne_f32_e32 v17, v17
	v_rndne_f32_e32 v15, v15
	v_cvt_i32_f32_e32 v16, v16
	v_cvt_i32_f32_e32 v17, v17
	v_cvt_i32_f32_e32 v15, v15
	s_add_u32 s0, s0, s8
	v_med3_i32 v16, v16, s71, v235
	v_med3_i32 v14, v17, s71, v235
	v_med3_i32 v15, v15, s71, v235
	v_perm_b32 v13, v16, v13, s48
	v_mul_f32_e32 v16, v44, v35
	v_lshlrev_b32_e32 v14, 8, v14
	v_lshlrev_b32_e32 v15, 16, v15
	v_rndne_f32_e32 v16, v16
	v_and_b32_e32 v14, 0xff00, v14
	v_and_b32_e32 v15, 0xff0000, v15
	v_cvt_i32_f32_e32 v16, v16
	v_mul_f32_e32 v17, v44, v34
	v_or3_b32 v13, v13, v14, v15
	v_mul_f32_e32 v14, v44, v33
	v_rndne_f32_e32 v17, v17
	v_rndne_f32_e32 v14, v14
	v_mul_f32_e32 v15, v44, v32
	v_cvt_i32_f32_e32 v17, v17
	v_cvt_i32_f32_e32 v14, v14
	v_rndne_f32_e32 v15, v15
	global_store_dwordx2 v[4:5], v[12:13], off offset:-512
	v_med3_i32 v12, v16, s71, v235
	v_cvt_i32_f32_e32 v15, v15
	v_mul_f32_e32 v16, v44, v31
	v_rndne_f32_e32 v16, v16
	v_cvt_i32_f32_e32 v16, v16
	v_med3_i32 v13, v17, s71, v235
	v_med3_i32 v14, v14, s71, v235
	v_lshlrev_b32_e32 v13, 8, v13
	v_lshlrev_b32_e32 v14, 16, v14
	v_med3_i32 v15, v15, s71, v235
	v_and_b32_e32 v14, 0xff0000, v14
	v_lshlrev_b32_e32 v15, 24, v15
	v_perm_b32 v12, v13, v12, s49
	v_mul_f32_e32 v17, v44, v30
	v_or3_b32 v12, v12, v15, v14
	v_med3_i32 v13, v16, s71, v235
	v_mul_f32_e32 v15, v44, v29
	v_mul_f32_e32 v16, v44, v28
	v_rndne_f32_e32 v17, v17
	v_rndne_f32_e32 v15, v15
	v_rndne_f32_e32 v16, v16
	v_cvt_i32_f32_e32 v17, v17
	v_cvt_i32_f32_e32 v15, v15
	v_cvt_i32_f32_e32 v16, v16
	s_addc_u32 s1, s1, s9
	v_med3_i32 v14, v17, s71, v235
	v_med3_i32 v15, v15, s71, v235
	v_med3_i32 v16, v16, s71, v235
	v_lshlrev_b32_e32 v14, 8, v14
	v_lshlrev_b32_e32 v15, 16, v15
	v_perm_b32 v13, v16, v13, s48
	v_mul_f32_e32 v16, v44, v37
	v_and_b32_e32 v14, 0xff00, v14
	v_and_b32_e32 v15, 0xff0000, v15
	v_rndne_f32_e32 v16, v16
	v_cvt_i32_f32_e32 v16, v16
	v_mul_f32_e32 v17, v44, v36
	v_or3_b32 v13, v13, v14, v15
	v_mul_f32_e32 v14, v44, v39
	v_rndne_f32_e32 v17, v17
	v_rndne_f32_e32 v14, v14
	v_mul_f32_e32 v15, v44, v38
	v_cvt_i32_f32_e32 v17, v17
	v_cvt_i32_f32_e32 v14, v14
	v_rndne_f32_e32 v15, v15
	v_cvt_i32_f32_e32 v15, v15
	global_store_dwordx2 v[4:5], v[12:13], off
	v_med3_i32 v12, v16, s71, v235
	v_mul_f32_e32 v16, v44, v42
	v_rndne_f32_e32 v16, v16
	v_med3_i32 v13, v17, s71, v235
	v_med3_i32 v14, v14, s71, v235
	v_cvt_i32_f32_e32 v16, v16
	v_lshlrev_b32_e32 v13, 8, v13
	v_lshlrev_b32_e32 v14, 16, v14
	v_med3_i32 v15, v15, s71, v235
	v_and_b32_e32 v14, 0xff0000, v14
	v_lshlrev_b32_e32 v15, 24, v15
	v_perm_b32 v12, v13, v12, s49
	v_mul_f32_e32 v17, v44, v40
	v_or3_b32 v12, v12, v15, v14
	v_mul_f32_e32 v15, v44, v43
	v_rndne_f32_e32 v17, v17
	v_med3_i32 v13, v16, s71, v235
	v_rndne_f32_e32 v15, v15
	v_mul_f32_e32 v16, v44, v41
	v_cvt_i32_f32_e32 v17, v17
	v_cvt_i32_f32_e32 v15, v15
	v_rndne_f32_e32 v16, v16
	v_cvt_i32_f32_e32 v16, v16
	v_med3_i32 v14, v17, s71, v235
	v_med3_i32 v15, v15, s71, v235
	v_lshlrev_b32_e32 v14, 8, v14
	v_lshlrev_b32_e32 v15, 16, v15
	v_med3_i32 v16, v16, s71, v235
	v_and_b32_e32 v14, 0xff00, v14
	v_and_b32_e32 v15, 0xff0000, v15
	v_perm_b32 v13, v16, v13, s48
	v_or3_b32 v13, v13, v14, v15
	global_store_dwordx2 v[4:5], v[12:13], off offset:512
	v_lshl_add_u64 v[2:3], v[2:3], 0, s[12:13]
	v_lshl_add_u64 v[4:5], v[4:5], 0, s[6:7]
	s_waitcnt vmcnt(12)
	v_mov_b32_e32 v20, v72
	v_mov_b32_e32 v21, v73
	v_mov_b32_e32 v22, v74
	v_mov_b32_e32 v23, v75
	v_mov_b32_e32 v28, v76
	v_mov_b32_e32 v29, v77
	v_mov_b32_e32 v30, v78
	v_mov_b32_e32 v31, v79
	v_mov_b32_e32 v36, v80
	v_mov_b32_e32 v37, v81
	v_mov_b32_e32 v38, v82
	v_mov_b32_e32 v39, v83
	v_mov_b32_e32 v42, v84
	v_mov_b32_e32 v43, v85
	v_mov_b32_e32 v44, v86
	v_mov_b32_e32 v45, v87
	v_lshlrev_b32_e32 v19, 16, v20
	v_and_b32_e32 v18, 0xffff0000, v20
	v_max_f32_e64 v12, |v18|, |v18|
	v_max_f32_e64 v13, |v19|, |v19|
	v_lshlrev_b32_e32 v17, 16, v21
	v_and_b32_e32 v16, 0xffff0000, v21
	v_max_f32_e32 v12, v13, v12
	v_max_f32_e64 v13, |v16|, |v16|
	v_max_f32_e64 v14, |v17|, |v17|
	v_max_f32_e32 v13, v14, v13
	v_lshlrev_b32_e32 v15, 16, v22
	v_and_b32_e32 v14, 0xffff0000, v22
	v_max3_f32 v20, v12, 0, v13
	v_max_f32_e64 v12, |v14|, |v14|
	v_max_f32_e64 v13, |v15|, |v15|
	v_max_f32_e32 v21, v13, v12
	v_lshlrev_b32_e32 v13, 16, v23
	v_and_b32_e32 v12, 0xffff0000, v23
	v_max_f32_e64 v22, |v12|, |v12|
	v_max_f32_e64 v23, |v13|, |v13|
	v_max_f32_e32 v22, v23, v22
	v_lshlrev_b32_e32 v27, 16, v28
	v_and_b32_e32 v26, 0xffff0000, v28
	v_max3_f32 v20, v20, v21, v22
	v_max_f32_e64 v21, |v26|, |v26|
	v_max_f32_e64 v22, |v27|, |v27|
	v_lshlrev_b32_e32 v25, 16, v29
	v_and_b32_e32 v24, 0xffff0000, v29
	v_max_f32_e32 v21, v22, v21
	v_max_f32_e64 v22, |v24|, |v24|
	v_max_f32_e64 v23, |v25|, |v25|
	v_max_f32_e32 v22, v23, v22
	v_max3_f32 v28, v20, v21, v22
	v_lshlrev_b32_e32 v23, 16, v30
	v_and_b32_e32 v22, 0xffff0000, v30
	v_max_f32_e64 v20, |v22|, |v22|
	v_max_f32_e64 v21, |v23|, |v23|
	v_max_f32_e32 v29, v21, v20
	v_lshlrev_b32_e32 v21, 16, v31
	v_and_b32_e32 v20, 0xffff0000, v31
	v_max_f32_e64 v30, |v20|, |v20|
	v_max_f32_e64 v31, |v21|, |v21|
	v_max_f32_e32 v30, v31, v30
	v_lshlrev_b32_e32 v35, 16, v36
	v_and_b32_e32 v34, 0xffff0000, v36
	v_max3_f32 v28, v28, v29, v30
	v_max_f32_e64 v29, |v34|, |v34|
	v_max_f32_e64 v30, |v35|, |v35|
	v_lshlrev_b32_e32 v33, 16, v37
	v_and_b32_e32 v32, 0xffff0000, v37
	v_max_f32_e32 v29, v30, v29
	v_max_f32_e64 v30, |v32|, |v32|
	v_max_f32_e64 v31, |v33|, |v33|
	v_max_f32_e32 v30, v31, v30
	v_max3_f32 v36, v28, v29, v30
	v_lshlrev_b32_e32 v31, 16, v38
	v_and_b32_e32 v30, 0xffff0000, v38
	v_max_f32_e64 v28, |v30|, |v30|
	v_max_f32_e64 v29, |v31|, |v31|
	v_max_f32_e32 v37, v29, v28
	v_lshlrev_b32_e32 v29, 16, v39
	v_and_b32_e32 v28, 0xffff0000, v39
	v_max_f32_e64 v38, |v28|, |v28|
	v_max_f32_e64 v39, |v29|, |v29|
	v_max_f32_e32 v38, v39, v38
	v_max3_f32 v40, v36, v37, v38
	v_lshlrev_b32_e32 v37, 16, v42
	v_and_b32_e32 v36, 0xffff0000, v42
	v_max_f32_e64 v38, |v36|, |v36|
	v_max_f32_e64 v39, |v37|, |v37|
	v_max_f32_e32 v41, v39, v38
	v_lshlrev_b32_e32 v39, 16, v43
	v_and_b32_e32 v38, 0xffff0000, v43
	v_max_f32_e64 v42, |v38|, |v38|
	v_max_f32_e64 v43, |v39|, |v39|
	v_max_f32_e32 v42, v43, v42
	v_max3_f32 v46, v40, v41, v42
	v_lshlrev_b32_e32 v42, 16, v44
	v_and_b32_e32 v40, 0xffff0000, v44
	v_max_f32_e64 v41, |v40|, |v40|
	v_max_f32_e64 v43, |v42|, |v42|
	v_max_f32_e32 v44, v43, v41
	v_lshlrev_b32_e32 v43, 16, v45
	v_and_b32_e32 v41, 0xffff0000, v45
	v_max_f32_e64 v45, |v41|, |v41|
	v_max_f32_e64 v47, |v43|, |v43|
	v_max_f32_e32 v45, v47, v45
	v_max3_f32 v44, v46, v44, v45
	ds_bpermute_b32 v45, v6, v44
	s_waitcnt lgkmcnt(0)
	v_max_f32_e32 v45, v45, v45
	v_max_f32_e32 v44, v44, v45
	ds_bpermute_b32 v45, v7, v44
	s_waitcnt lgkmcnt(0)
	v_max_f32_e32 v45, v45, v45
	v_max_f32_e32 v44, v44, v45
	ds_bpermute_b32 v45, v8, v44
	s_waitcnt lgkmcnt(0)
	v_max_f32_e32 v45, v45, v45
	v_max_f32_e32 v44, v44, v45
	ds_bpermute_b32 v45, v9, v44
	s_waitcnt lgkmcnt(0)
	v_max_f32_e32 v45, v45, v45
	v_max_f32_e32 v44, v44, v45
	ds_bpermute_b32 v45, v10, v44
	s_waitcnt lgkmcnt(0)
	v_max_f32_e32 v45, v45, v45
	v_max_f32_e32 v44, v44, v45
	ds_bpermute_b32 v45, v11, v44
	s_waitcnt lgkmcnt(0)
	v_max3_f32 v44, v44, v45, s73
	s_and_saveexec_b64 s[10:11], s[36:37]
	s_cbranch_execz .Lxqp0_C2
	v_mov_b32_e32 v45, v106
	v_mul_f32_e32 v46, 0x3c010204, v44
	v_mul_f32_e32 v45, v45, v46
	v_mov_b32_e32 v46, 0x65b2000
	global_store_dword v46, v45, s[0:1]
.Lxqp0_C2:
	s_or_b64 exec, exec, s[10:11]
	v_div_scale_f32 v45, s[10:11], v44, v44, s47
	v_rcp_f32_e32 v46, v45
	v_div_scale_f32 v47, vcc, s47, v44, s47
	s_add_i32 s34, s34, -1
	v_fma_f32 v48, -v45, v46, 1.0
	v_fmac_f32_e32 v46, v48, v46
	v_mul_f32_e32 v48, v47, v46
	v_fma_f32 v49, -v45, v48, v47
	v_fmac_f32_e32 v48, v49, v46
	v_fma_f32 v45, -v45, v48, v47
	v_div_fmas_f32 v45, v45, v46, v48
	v_div_fixup_f32 v44, v45, v44, s47
	v_mul_f32_e32 v18, v44, v18
	v_mul_f32_e32 v17, v44, v17
	v_mul_f32_e32 v19, v44, v19
	v_rndne_f32_e32 v18, v18
	v_rndne_f32_e32 v17, v17
	v_mul_f32_e32 v16, v44, v16
	v_mul_f32_e32 v15, v44, v15
	v_mul_f32_e32 v12, v44, v12
	v_rndne_f32_e32 v19, v19
	v_cvt_i32_f32_e32 v18, v18
	v_cvt_i32_f32_e32 v17, v17
	v_rndne_f32_e32 v16, v16
	v_rndne_f32_e32 v15, v15
	v_rndne_f32_e32 v12, v12
	v_cvt_i32_f32_e32 v19, v19
	v_cvt_i32_f32_e32 v16, v16
	v_cvt_i32_f32_e32 v15, v15
	v_mul_f32_e32 v14, v44, v14
	v_mul_f32_e32 v13, v44, v13
	v_cvt_i32_f32_e32 v12, v12
	v_rndne_f32_e32 v14, v14
	v_rndne_f32_e32 v13, v13
	v_cvt_i32_f32_e32 v45, v14
	v_cvt_i32_f32_e32 v13, v13
	v_med3_i32 v18, v18, s71, v235
	v_med3_i32 v17, v17, s71, v235
	v_med3_i32 v19, v19, s71, v235
	v_lshlrev_b32_e32 v18, 8, v18
	v_lshlrev_b32_e32 v17, 16, v17
	v_med3_i32 v16, v16, s71, v235
	v_med3_i32 v15, v15, s71, v235
	v_med3_i32 v12, v12, s71, v235
	v_and_b32_e32 v17, 0xff0000, v17
	v_lshlrev_b32_e32 v16, 24, v16
	v_perm_b32 v14, v18, v19, s49
	v_perm_b32 v12, v12, v15, s48
	v_mul_f32_e32 v15, v44, v27
	v_or3_b32 v14, v14, v16, v17
	v_med3_i32 v16, v45, s71, v235
	v_med3_i32 v13, v13, s71, v235
	v_rndne_f32_e32 v15, v15
	v_lshlrev_b32_e32 v16, 8, v16
	v_lshlrev_b32_e32 v13, 16, v13
	v_cvt_i32_f32_e32 v17, v15
	v_mul_f32_e32 v15, v44, v26
	v_and_b32_e32 v16, 0xff00, v16
	v_and_b32_e32 v13, 0xff0000, v13
	v_rndne_f32_e32 v15, v15
	v_cvt_i32_f32_e32 v18, v15
	v_or3_b32 v15, v12, v16, v13
	global_store_dwordx2 v[4:5], v[14:15], off offset:-1024
	v_mul_f32_e32 v14, v44, v25
	v_rndne_f32_e32 v14, v14
	v_mul_f32_e32 v15, v44, v24
	v_cvt_i32_f32_e32 v14, v14
	v_rndne_f32_e32 v15, v15
	v_mul_f32_e32 v16, v44, v23
	v_cvt_i32_f32_e32 v15, v15
	v_rndne_f32_e32 v16, v16
	v_cvt_i32_f32_e32 v16, v16
	v_med3_i32 v13, v18, s71, v235
	v_med3_i32 v14, v14, s71, v235
	v_med3_i32 v12, v17, s71, v235
	v_lshlrev_b32_e32 v13, 8, v13
	v_lshlrev_b32_e32 v14, 16, v14
	v_med3_i32 v15, v15, s71, v235
	v_and_b32_e32 v14, 0xff0000, v14
	v_lshlrev_b32_e32 v15, 24, v15
	v_perm_b32 v12, v13, v12, s49
	v_med3_i32 v13, v16, s71, v235
	v_mul_f32_e32 v16, v44, v20
	v_mul_f32_e32 v17, v44, v22
	v_or3_b32 v12, v12, v15, v14
	v_mul_f32_e32 v15, v44, v21
	v_rndne_f32_e32 v16, v16
	v_rndne_f32_e32 v17, v17
	v_rndne_f32_e32 v15, v15
	v_cvt_i32_f32_e32 v16, v16
	v_cvt_i32_f32_e32 v17, v17
	v_cvt_i32_f32_e32 v15, v15
	s_add_u32 s0, s0, s8
	v_med3_i32 v16, v16, s71, v235
	v_med3_i32 v14, v17, s71, v235
	v_med3_i32 v15, v15, s71, v235
	v_perm_b32 v13, v16, v13, s48
	v_mul_f32_e32 v16, v44, v35
	v_lshlrev_b32_e32 v14, 8, v14
	v_lshlrev_b32_e32 v15, 16, v15
	v_rndne_f32_e32 v16, v16
	v_and_b32_e32 v14, 0xff00, v14
	v_and_b32_e32 v15, 0xff0000, v15
	v_cvt_i32_f32_e32 v16, v16
	v_mul_f32_e32 v17, v44, v34
	v_or3_b32 v13, v13, v14, v15
	v_mul_f32_e32 v14, v44, v33
	v_rndne_f32_e32 v17, v17
	v_rndne_f32_e32 v14, v14
	v_mul_f32_e32 v15, v44, v32
	v_cvt_i32_f32_e32 v17, v17
	v_cvt_i32_f32_e32 v14, v14
	v_rndne_f32_e32 v15, v15
	global_store_dwordx2 v[4:5], v[12:13], off offset:-512
	v_med3_i32 v12, v16, s71, v235
	v_cvt_i32_f32_e32 v15, v15
	v_mul_f32_e32 v16, v44, v31
	v_rndne_f32_e32 v16, v16
	v_cvt_i32_f32_e32 v16, v16
	v_med3_i32 v13, v17, s71, v235
	v_med3_i32 v14, v14, s71, v235
	v_lshlrev_b32_e32 v13, 8, v13
	v_lshlrev_b32_e32 v14, 16, v14
	v_med3_i32 v15, v15, s71, v235
	v_and_b32_e32 v14, 0xff0000, v14
	v_lshlrev_b32_e32 v15, 24, v15
	v_perm_b32 v12, v13, v12, s49
	v_mul_f32_e32 v17, v44, v30
	v_or3_b32 v12, v12, v15, v14
	v_med3_i32 v13, v16, s71, v235
	v_mul_f32_e32 v15, v44, v29
	v_mul_f32_e32 v16, v44, v28
	v_rndne_f32_e32 v17, v17
	v_rndne_f32_e32 v15, v15
	v_rndne_f32_e32 v16, v16
	v_cvt_i32_f32_e32 v17, v17
	v_cvt_i32_f32_e32 v15, v15
	v_cvt_i32_f32_e32 v16, v16
	s_addc_u32 s1, s1, s9
	v_med3_i32 v14, v17, s71, v235
	v_med3_i32 v15, v15, s71, v235
	v_med3_i32 v16, v16, s71, v235
	v_lshlrev_b32_e32 v14, 8, v14
	v_lshlrev_b32_e32 v15, 16, v15
	v_perm_b32 v13, v16, v13, s48
	v_mul_f32_e32 v16, v44, v37
	v_and_b32_e32 v14, 0xff00, v14
	v_and_b32_e32 v15, 0xff0000, v15
	v_rndne_f32_e32 v16, v16
	v_cvt_i32_f32_e32 v16, v16
	v_mul_f32_e32 v17, v44, v36
	v_or3_b32 v13, v13, v14, v15
	v_mul_f32_e32 v14, v44, v39
	v_rndne_f32_e32 v17, v17
	v_rndne_f32_e32 v14, v14
	v_mul_f32_e32 v15, v44, v38
	v_cvt_i32_f32_e32 v17, v17
	v_cvt_i32_f32_e32 v14, v14
	v_rndne_f32_e32 v15, v15
	v_cvt_i32_f32_e32 v15, v15
	global_store_dwordx2 v[4:5], v[12:13], off
	v_med3_i32 v12, v16, s71, v235
	v_mul_f32_e32 v16, v44, v42
	v_rndne_f32_e32 v16, v16
	v_med3_i32 v13, v17, s71, v235
	v_med3_i32 v14, v14, s71, v235
	v_cvt_i32_f32_e32 v16, v16
	v_lshlrev_b32_e32 v13, 8, v13
	v_lshlrev_b32_e32 v14, 16, v14
	v_med3_i32 v15, v15, s71, v235
	v_and_b32_e32 v14, 0xff0000, v14
	v_lshlrev_b32_e32 v15, 24, v15
	v_perm_b32 v12, v13, v12, s49
	v_mul_f32_e32 v17, v44, v40
	v_or3_b32 v12, v12, v15, v14
	v_mul_f32_e32 v15, v44, v43
	v_rndne_f32_e32 v17, v17
	v_med3_i32 v13, v16, s71, v235
	v_rndne_f32_e32 v15, v15
	v_mul_f32_e32 v16, v44, v41
	v_cvt_i32_f32_e32 v17, v17
	v_cvt_i32_f32_e32 v15, v15
	v_rndne_f32_e32 v16, v16
	v_cvt_i32_f32_e32 v16, v16
	v_med3_i32 v14, v17, s71, v235
	v_med3_i32 v15, v15, s71, v235
	v_lshlrev_b32_e32 v14, 8, v14
	v_lshlrev_b32_e32 v15, 16, v15
	v_med3_i32 v16, v16, s71, v235
	v_and_b32_e32 v14, 0xff00, v14
	v_and_b32_e32 v15, 0xff0000, v15
	v_perm_b32 v13, v16, v13, s48
	v_or3_b32 v13, v13, v14, v15
	global_store_dwordx2 v[4:5], v[12:13], off offset:512
	v_lshl_add_u64 v[2:3], v[2:3], 0, s[12:13]
	v_lshl_add_u64 v[4:5], v[4:5], 0, s[6:7]
	s_waitcnt vmcnt(12)
	v_mov_b32_e32 v20, v88
	v_mov_b32_e32 v21, v89
	v_mov_b32_e32 v22, v90
	v_mov_b32_e32 v23, v91
	v_mov_b32_e32 v28, v92
	v_mov_b32_e32 v29, v93
	v_mov_b32_e32 v30, v94
	v_mov_b32_e32 v31, v95
	v_mov_b32_e32 v36, v96
	v_mov_b32_e32 v37, v97
	v_mov_b32_e32 v38, v98
	v_mov_b32_e32 v39, v99
	v_mov_b32_e32 v42, v100
	v_mov_b32_e32 v43, v101
	v_mov_b32_e32 v44, v102
	v_mov_b32_e32 v45, v103
	v_lshlrev_b32_e32 v19, 16, v20
	v_and_b32_e32 v18, 0xffff0000, v20
	v_max_f32_e64 v12, |v18|, |v18|
	v_max_f32_e64 v13, |v19|, |v19|
	v_lshlrev_b32_e32 v17, 16, v21
	v_and_b32_e32 v16, 0xffff0000, v21
	v_max_f32_e32 v12, v13, v12
	v_max_f32_e64 v13, |v16|, |v16|
	v_max_f32_e64 v14, |v17|, |v17|
	v_max_f32_e32 v13, v14, v13
	v_lshlrev_b32_e32 v15, 16, v22
	v_and_b32_e32 v14, 0xffff0000, v22
	v_max3_f32 v20, v12, 0, v13
	v_max_f32_e64 v12, |v14|, |v14|
	v_max_f32_e64 v13, |v15|, |v15|
	v_max_f32_e32 v21, v13, v12
	v_lshlrev_b32_e32 v13, 16, v23
	v_and_b32_e32 v12, 0xffff0000, v23
	v_max_f32_e64 v22, |v12|, |v12|
	v_max_f32_e64 v23, |v13|, |v13|
	v_max_f32_e32 v22, v23, v22
	v_lshlrev_b32_e32 v27, 16, v28
	v_and_b32_e32 v26, 0xffff0000, v28
	v_max3_f32 v20, v20, v21, v22
	v_max_f32_e64 v21, |v26|, |v26|
	v_max_f32_e64 v22, |v27|, |v27|
	v_lshlrev_b32_e32 v25, 16, v29
	v_and_b32_e32 v24, 0xffff0000, v29
	v_max_f32_e32 v21, v22, v21
	v_max_f32_e64 v22, |v24|, |v24|
	v_max_f32_e64 v23, |v25|, |v25|
	v_max_f32_e32 v22, v23, v22
	v_max3_f32 v28, v20, v21, v22
	v_lshlrev_b32_e32 v23, 16, v30
	v_and_b32_e32 v22, 0xffff0000, v30
	v_max_f32_e64 v20, |v22|, |v22|
	v_max_f32_e64 v21, |v23|, |v23|
	v_max_f32_e32 v29, v21, v20
	v_lshlrev_b32_e32 v21, 16, v31
	v_and_b32_e32 v20, 0xffff0000, v31
	v_max_f32_e64 v30, |v20|, |v20|
	v_max_f32_e64 v31, |v21|, |v21|
	v_max_f32_e32 v30, v31, v30
	v_lshlrev_b32_e32 v35, 16, v36
	v_and_b32_e32 v34, 0xffff0000, v36
	v_max3_f32 v28, v28, v29, v30
	v_max_f32_e64 v29, |v34|, |v34|
	v_max_f32_e64 v30, |v35|, |v35|
	v_lshlrev_b32_e32 v33, 16, v37
	v_and_b32_e32 v32, 0xffff0000, v37
	v_max_f32_e32 v29, v30, v29
	v_max_f32_e64 v30, |v32|, |v32|
	v_max_f32_e64 v31, |v33|, |v33|
	v_max_f32_e32 v30, v31, v30
	v_max3_f32 v36, v28, v29, v30
	v_lshlrev_b32_e32 v31, 16, v38
	v_and_b32_e32 v30, 0xffff0000, v38
	v_max_f32_e64 v28, |v30|, |v30|
	v_max_f32_e64 v29, |v31|, |v31|
	v_max_f32_e32 v37, v29, v28
	v_lshlrev_b32_e32 v29, 16, v39
	v_and_b32_e32 v28, 0xffff0000, v39
	v_max_f32_e64 v38, |v28|, |v28|
	v_max_f32_e64 v39, |v29|, |v29|
	v_max_f32_e32 v38, v39, v38
	v_max3_f32 v40, v36, v37, v38
	v_lshlrev_b32_e32 v37, 16, v42
	v_and_b32_e32 v36, 0xffff0000, v42
	v_max_f32_e64 v38, |v36|, |v36|
	v_max_f32_e64 v39, |v37|, |v37|
	v_max_f32_e32 v41, v39, v38
	v_lshlrev_b32_e32 v39, 16, v43
	v_and_b32_e32 v38, 0xffff0000, v43
	v_max_f32_e64 v42, |v38|, |v38|
	v_max_f32_e64 v43, |v39|, |v39|
	v_max_f32_e32 v42, v43, v42
	v_max3_f32 v46, v40, v41, v42
	v_lshlrev_b32_e32 v42, 16, v44
	v_and_b32_e32 v40, 0xffff0000, v44
	v_max_f32_e64 v41, |v40|, |v40|
	v_max_f32_e64 v43, |v42|, |v42|
	v_max_f32_e32 v44, v43, v41
	v_lshlrev_b32_e32 v43, 16, v45
	v_and_b32_e32 v41, 0xffff0000, v45
	v_max_f32_e64 v45, |v41|, |v41|
	v_max_f32_e64 v47, |v43|, |v43|
	v_max_f32_e32 v45, v47, v45
	v_max3_f32 v44, v46, v44, v45
	ds_bpermute_b32 v45, v6, v44
	s_waitcnt lgkmcnt(0)
	v_max_f32_e32 v45, v45, v45
	v_max_f32_e32 v44, v44, v45
	ds_bpermute_b32 v45, v7, v44
	s_waitcnt lgkmcnt(0)
	v_max_f32_e32 v45, v45, v45
	v_max_f32_e32 v44, v44, v45
	ds_bpermute_b32 v45, v8, v44
	s_waitcnt lgkmcnt(0)
	v_max_f32_e32 v45, v45, v45
	v_max_f32_e32 v44, v44, v45
	ds_bpermute_b32 v45, v9, v44
	s_waitcnt lgkmcnt(0)
	v_max_f32_e32 v45, v45, v45
	v_max_f32_e32 v44, v44, v45
	ds_bpermute_b32 v45, v10, v44
	s_waitcnt lgkmcnt(0)
	v_max_f32_e32 v45, v45, v45
	v_max_f32_e32 v44, v44, v45
	ds_bpermute_b32 v45, v11, v44
	s_waitcnt lgkmcnt(0)
	v_max3_f32 v44, v44, v45, s73
	s_and_saveexec_b64 s[10:11], s[36:37]
	s_cbranch_execz .Lxqp0_C3
	v_mov_b32_e32 v45, v107
	v_mul_f32_e32 v46, 0x3c010204, v44
	v_mul_f32_e32 v45, v45, v46
	v_mov_b32_e32 v46, 0x65b2000
	global_store_dword v46, v45, s[0:1]
.Lxqp0_C3:
	s_or_b64 exec, exec, s[10:11]
	v_div_scale_f32 v45, s[10:11], v44, v44, s47
	v_rcp_f32_e32 v46, v45
	v_div_scale_f32 v47, vcc, s47, v44, s47
	s_add_i32 s34, s34, -1
	v_fma_f32 v48, -v45, v46, 1.0
	v_fmac_f32_e32 v46, v48, v46
	v_mul_f32_e32 v48, v47, v46
	v_fma_f32 v49, -v45, v48, v47
	v_fmac_f32_e32 v48, v49, v46
	v_fma_f32 v45, -v45, v48, v47
	v_div_fmas_f32 v45, v45, v46, v48
	v_div_fixup_f32 v44, v45, v44, s47
	v_mul_f32_e32 v18, v44, v18
	v_mul_f32_e32 v17, v44, v17
	v_mul_f32_e32 v19, v44, v19
	v_rndne_f32_e32 v18, v18
	v_rndne_f32_e32 v17, v17
	v_mul_f32_e32 v16, v44, v16
	v_mul_f32_e32 v15, v44, v15
	v_mul_f32_e32 v12, v44, v12
	v_rndne_f32_e32 v19, v19
	v_cvt_i32_f32_e32 v18, v18
	v_cvt_i32_f32_e32 v17, v17
	v_rndne_f32_e32 v16, v16
	v_rndne_f32_e32 v15, v15
	v_rndne_f32_e32 v12, v12
	v_cvt_i32_f32_e32 v19, v19
	v_cvt_i32_f32_e32 v16, v16
	v_cvt_i32_f32_e32 v15, v15
	v_mul_f32_e32 v14, v44, v14
	v_mul_f32_e32 v13, v44, v13
	v_cvt_i32_f32_e32 v12, v12
	v_rndne_f32_e32 v14, v14
	v_rndne_f32_e32 v13, v13
	v_cvt_i32_f32_e32 v45, v14
	v_cvt_i32_f32_e32 v13, v13
	v_med3_i32 v18, v18, s71, v235
	v_med3_i32 v17, v17, s71, v235
	v_med3_i32 v19, v19, s71, v235
	v_lshlrev_b32_e32 v18, 8, v18
	v_lshlrev_b32_e32 v17, 16, v17
	v_med3_i32 v16, v16, s71, v235
	v_med3_i32 v15, v15, s71, v235
	v_med3_i32 v12, v12, s71, v235
	v_and_b32_e32 v17, 0xff0000, v17
	v_lshlrev_b32_e32 v16, 24, v16
	v_perm_b32 v14, v18, v19, s49
	v_perm_b32 v12, v12, v15, s48
	v_mul_f32_e32 v15, v44, v27
	v_or3_b32 v14, v14, v16, v17
	v_med3_i32 v16, v45, s71, v235
	v_med3_i32 v13, v13, s71, v235
	v_rndne_f32_e32 v15, v15
	v_lshlrev_b32_e32 v16, 8, v16
	v_lshlrev_b32_e32 v13, 16, v13
	v_cvt_i32_f32_e32 v17, v15
	v_mul_f32_e32 v15, v44, v26
	v_and_b32_e32 v16, 0xff00, v16
	v_and_b32_e32 v13, 0xff0000, v13
	v_rndne_f32_e32 v15, v15
	v_cvt_i32_f32_e32 v18, v15
	v_or3_b32 v15, v12, v16, v13
	global_store_dwordx2 v[4:5], v[14:15], off offset:-1024
	v_mul_f32_e32 v14, v44, v25
	v_rndne_f32_e32 v14, v14
	v_mul_f32_e32 v15, v44, v24
	v_cvt_i32_f32_e32 v14, v14
	v_rndne_f32_e32 v15, v15
	v_mul_f32_e32 v16, v44, v23
	v_cvt_i32_f32_e32 v15, v15
	v_rndne_f32_e32 v16, v16
	v_cvt_i32_f32_e32 v16, v16
	v_med3_i32 v13, v18, s71, v235
	v_med3_i32 v14, v14, s71, v235
	v_med3_i32 v12, v17, s71, v235
	v_lshlrev_b32_e32 v13, 8, v13
	v_lshlrev_b32_e32 v14, 16, v14
	v_med3_i32 v15, v15, s71, v235
	v_and_b32_e32 v14, 0xff0000, v14
	v_lshlrev_b32_e32 v15, 24, v15
	v_perm_b32 v12, v13, v12, s49
	v_med3_i32 v13, v16, s71, v235
	v_mul_f32_e32 v16, v44, v20
	v_mul_f32_e32 v17, v44, v22
	v_or3_b32 v12, v12, v15, v14
	v_mul_f32_e32 v15, v44, v21
	v_rndne_f32_e32 v16, v16
	v_rndne_f32_e32 v17, v17
	v_rndne_f32_e32 v15, v15
	v_cvt_i32_f32_e32 v16, v16
	v_cvt_i32_f32_e32 v17, v17
	v_cvt_i32_f32_e32 v15, v15
	s_add_u32 s0, s0, s8
	v_med3_i32 v16, v16, s71, v235
	v_med3_i32 v14, v17, s71, v235
	v_med3_i32 v15, v15, s71, v235
	v_perm_b32 v13, v16, v13, s48
	v_mul_f32_e32 v16, v44, v35
	v_lshlrev_b32_e32 v14, 8, v14
	v_lshlrev_b32_e32 v15, 16, v15
	v_rndne_f32_e32 v16, v16
	v_and_b32_e32 v14, 0xff00, v14
	v_and_b32_e32 v15, 0xff0000, v15
	v_cvt_i32_f32_e32 v16, v16
	v_mul_f32_e32 v17, v44, v34
	v_or3_b32 v13, v13, v14, v15
	v_mul_f32_e32 v14, v44, v33
	v_rndne_f32_e32 v17, v17
	v_rndne_f32_e32 v14, v14
	v_mul_f32_e32 v15, v44, v32
	v_cvt_i32_f32_e32 v17, v17
	v_cvt_i32_f32_e32 v14, v14
	v_rndne_f32_e32 v15, v15
	global_store_dwordx2 v[4:5], v[12:13], off offset:-512
	v_med3_i32 v12, v16, s71, v235
	v_cvt_i32_f32_e32 v15, v15
	v_mul_f32_e32 v16, v44, v31
	v_rndne_f32_e32 v16, v16
	v_cvt_i32_f32_e32 v16, v16
	v_med3_i32 v13, v17, s71, v235
	v_med3_i32 v14, v14, s71, v235
	v_lshlrev_b32_e32 v13, 8, v13
	v_lshlrev_b32_e32 v14, 16, v14
	v_med3_i32 v15, v15, s71, v235
	v_and_b32_e32 v14, 0xff0000, v14
	v_lshlrev_b32_e32 v15, 24, v15
	v_perm_b32 v12, v13, v12, s49
	v_mul_f32_e32 v17, v44, v30
	v_or3_b32 v12, v12, v15, v14
	v_med3_i32 v13, v16, s71, v235
	v_mul_f32_e32 v15, v44, v29
	v_mul_f32_e32 v16, v44, v28
	v_rndne_f32_e32 v17, v17
	v_rndne_f32_e32 v15, v15
	v_rndne_f32_e32 v16, v16
	v_cvt_i32_f32_e32 v17, v17
	v_cvt_i32_f32_e32 v15, v15
	v_cvt_i32_f32_e32 v16, v16
	s_addc_u32 s1, s1, s9
	v_med3_i32 v14, v17, s71, v235
	v_med3_i32 v15, v15, s71, v235
	v_med3_i32 v16, v16, s71, v235
	v_lshlrev_b32_e32 v14, 8, v14
	v_lshlrev_b32_e32 v15, 16, v15
	v_perm_b32 v13, v16, v13, s48
	v_mul_f32_e32 v16, v44, v37
	v_and_b32_e32 v14, 0xff00, v14
	v_and_b32_e32 v15, 0xff0000, v15
	v_rndne_f32_e32 v16, v16
	v_cvt_i32_f32_e32 v16, v16
	v_mul_f32_e32 v17, v44, v36
	v_or3_b32 v13, v13, v14, v15
	v_mul_f32_e32 v14, v44, v39
	v_rndne_f32_e32 v17, v17
	v_rndne_f32_e32 v14, v14
	v_mul_f32_e32 v15, v44, v38
	v_cvt_i32_f32_e32 v17, v17
	v_cvt_i32_f32_e32 v14, v14
	v_rndne_f32_e32 v15, v15
	v_cvt_i32_f32_e32 v15, v15
	global_store_dwordx2 v[4:5], v[12:13], off
	v_med3_i32 v12, v16, s71, v235
	v_mul_f32_e32 v16, v44, v42
	v_rndne_f32_e32 v16, v16
	v_med3_i32 v13, v17, s71, v235
	v_med3_i32 v14, v14, s71, v235
	v_cvt_i32_f32_e32 v16, v16
	v_lshlrev_b32_e32 v13, 8, v13
	v_lshlrev_b32_e32 v14, 16, v14
	v_med3_i32 v15, v15, s71, v235
	v_and_b32_e32 v14, 0xff0000, v14
	v_lshlrev_b32_e32 v15, 24, v15
	v_perm_b32 v12, v13, v12, s49
	v_mul_f32_e32 v17, v44, v40
	v_or3_b32 v12, v12, v15, v14
	v_mul_f32_e32 v15, v44, v43
	v_rndne_f32_e32 v17, v17
	v_med3_i32 v13, v16, s71, v235
	v_rndne_f32_e32 v15, v15
	v_mul_f32_e32 v16, v44, v41
	v_cvt_i32_f32_e32 v17, v17
	v_cvt_i32_f32_e32 v15, v15
	v_rndne_f32_e32 v16, v16
	v_cvt_i32_f32_e32 v16, v16
	v_med3_i32 v14, v17, s71, v235
	v_med3_i32 v15, v15, s71, v235
	v_lshlrev_b32_e32 v14, 8, v14
	v_lshlrev_b32_e32 v15, 16, v15
	v_med3_i32 v16, v16, s71, v235
	v_and_b32_e32 v14, 0xff00, v14
	v_and_b32_e32 v15, 0xff0000, v15
	v_perm_b32 v13, v16, v13, s48
	v_or3_b32 v13, v13, v14, v15
	global_store_dwordx2 v[4:5], v[12:13], off offset:512
	v_lshl_add_u64 v[2:3], v[2:3], 0, s[12:13]
	v_lshl_add_u64 v[4:5], v[4:5], 0, s[6:7]
	s_cmp_lt_i32 s34, 4
	s_cbranch_scc0 .Lxqp0_top
	s_cmp_eq_u32 s34, 0
	s_cbranch_scc1 .LBB0_214
	s_branch .LBB0_212

.Lxqa_entry:
	s_cmp_lt_i32 s1, 4
	s_cbranch_scc1 .LBB0_1025

.Lxqa_l0:
	s_or_b64 exec, exec, s[20:21]
	v_lshl_add_u64 v[110:111], v[20:21], 0, s[16:17]
	v_lshl_add_u64 v[112:113], v[18:19], 0, s[14:15]
	global_load_dwordx4 v[56:59], v[110:111], off offset:-2048
	global_load_dwordx4 v[60:63], v[110:111], off offset:-1024
	global_load_dwordx4 v[64:67], v[110:111], off
	global_load_dwordx4 v[68:71], v[110:111], off offset:1024
	v_mov_b32_e32 v72, 0
	s_and_saveexec_b64 s[20:21], s[36:37]
	s_cbranch_execz .Lxqa_l1
	global_load_dword v72, v[112:113], off
.Lxqa_l1:
	s_or_b64 exec, exec, s[20:21]
	v_lshl_add_u64 v[110:111], v[110:111], 0, s[16:17]
	v_lshl_add_u64 v[112:113], v[112:113], 0, s[14:15]
	global_load_dwordx4 v[74:77], v[110:111], off offset:-2048
	global_load_dwordx4 v[78:81], v[110:111], off offset:-1024
	global_load_dwordx4 v[82:85], v[110:111], off
	global_load_dwordx4 v[86:89], v[110:111], off offset:1024
	v_mov_b32_e32 v90, 0
	s_and_saveexec_b64 s[20:21], s[36:37]
	s_cbranch_execz .Lxqa_l2
	global_load_dword v90, v[112:113], off
.Lxqa_l2:
	s_or_b64 exec, exec, s[20:21]
	v_lshl_add_u64 v[110:111], v[110:111], 0, s[16:17]
	v_lshl_add_u64 v[112:113], v[112:113], 0, s[14:15]
	global_load_dwordx4 v[92:95], v[110:111], off offset:-2048
	global_load_dwordx4 v[96:99], v[110:111], off offset:-1024
	global_load_dwordx4 v[100:103], v[110:111], off
	global_load_dwordx4 v[104:107], v[110:111], off offset:1024
	v_mov_b32_e32 v108, 0
	s_and_saveexec_b64 s[20:21], s[36:37]
	s_cbranch_execz .Lxqa_l3
	global_load_dword v108, v[112:113], off
.Lxqa_l3:
	s_or_b64 exec, exec, s[20:21]
	s_waitcnt vmcnt(12)
	v_lshlrev_b32_e32 v48, 16, v14
	v_and_b32_e32 v47, 0xffff0000, v14
	v_max_f32_e64 v14, |v47|, |v47|
	v_max_f32_e64 v31, |v48|, |v48|
	v_lshlrev_b32_e32 v46, 16, v15
	v_and_b32_e32 v45, 0xffff0000, v15
	v_max_f32_e32 v14, v31, v14
	v_max_f32_e64 v15, |v45|, |v45|
	v_max_f32_e64 v31, |v46|, |v46|
	v_max_f32_e32 v15, v31, v15
	v_lshlrev_b32_e32 v44, 16, v16
	v_and_b32_e32 v43, 0xffff0000, v16
	v_max3_f32 v14, v14, 0, v15
	v_max_f32_e64 v15, |v43|, |v43|
	v_max_f32_e64 v16, |v44|, |v44|
	v_lshlrev_b32_e32 v41, 16, v17
	v_and_b32_e32 v40, 0xffff0000, v17
	v_max_f32_e32 v15, v16, v15
	v_max_f32_e64 v16, |v40|, |v40|
	v_max_f32_e64 v17, |v41|, |v41|
	v_max_f32_e32 v16, v17, v16
	v_lshlrev_b32_e32 v39, 16, v10
	v_and_b32_e32 v38, 0xffff0000, v10
	v_max3_f32 v14, v14, v15, v16
	v_max_f32_e64 v10, |v38|, |v38|
	v_max_f32_e64 v15, |v39|, |v39|
	v_lshlrev_b32_e32 v37, 16, v11
	v_and_b32_e32 v36, 0xffff0000, v11
	v_max_f32_e32 v10, v15, v10
	v_max_f32_e64 v11, |v36|, |v36|
	v_max_f32_e64 v15, |v37|, |v37|
	v_max_f32_e32 v11, v15, v11
	v_lshlrev_b32_e32 v35, 16, v12
	v_and_b32_e32 v34, 0xffff0000, v12
	v_max3_f32 v10, v14, v10, v11
	v_max_f32_e64 v11, |v34|, |v34|
	v_max_f32_e64 v12, |v35|, |v35|
	v_lshlrev_b32_e32 v33, 16, v13
	v_and_b32_e32 v32, 0xffff0000, v13
	v_max_f32_e32 v11, v12, v11
	v_max_f32_e64 v12, |v32|, |v32|
	v_max_f32_e64 v13, |v33|, |v33|
	v_max_f32_e32 v12, v13, v12
	v_lshlrev_b32_e32 v31, 16, v6
	v_and_b32_e32 v17, 0xffff0000, v6
	v_max3_f32 v10, v10, v11, v12
	v_max_f32_e64 v6, |v17|, |v17|
	v_max_f32_e64 v11, |v31|, |v31|
	v_lshlrev_b32_e32 v16, 16, v7
	v_and_b32_e32 v15, 0xffff0000, v7
	v_max_f32_e32 v6, v11, v6
	v_max_f32_e64 v7, |v15|, |v15|
	v_max_f32_e64 v11, |v16|, |v16|
	v_max_f32_e32 v7, v11, v7
	v_lshlrev_b32_e32 v14, 16, v8
	v_and_b32_e32 v13, 0xffff0000, v8
	v_max3_f32 v6, v10, v6, v7
	v_max_f32_e64 v7, |v13|, |v13|
	v_max_f32_e64 v8, |v14|, |v14|
	v_lshlrev_b32_e32 v12, 16, v9
	v_and_b32_e32 v11, 0xffff0000, v9
	v_max_f32_e32 v7, v8, v7
	v_max_f32_e64 v8, |v11|, |v11|
	v_max_f32_e64 v9, |v12|, |v12|
	v_max_f32_e32 v8, v9, v8
	v_lshlrev_b32_e32 v10, 16, v2
	v_and_b32_e32 v9, 0xffff0000, v2
	v_max3_f32 v6, v6, v7, v8
	v_max_f32_e64 v2, |v9|, |v9|
	v_max_f32_e64 v7, |v10|, |v10|
	v_max_f32_e32 v2, v7, v2
	v_lshlrev_b32_e32 v8, 16, v3
	v_and_b32_e32 v7, 0xffff0000, v3
	v_max_f32_e64 v3, |v7|, |v7|
	v_max_f32_e64 v50, |v8|, |v8|
	v_max_f32_e32 v3, v50, v3
	v_max3_f32 v50, v6, v2, v3
	v_lshlrev_b32_e32 v6, 16, v4
	v_and_b32_e32 v4, 0xffff0000, v4
	v_max_f32_e64 v2, |v4|, |v4|
	v_max_f32_e64 v3, |v6|, |v6|
	v_max_f32_e32 v51, v3, v2
	v_lshlrev_b32_e32 v3, 16, v5
	v_and_b32_e32 v2, 0xffff0000, v5
	v_max_f32_e64 v5, |v2|, |v2|
	v_max_f32_e64 v52, |v3|, |v3|
	v_max_f32_e32 v5, v52, v5
	v_max3_f32 v5, v50, v51, v5
	ds_bpermute_b32 v50, v25, v5
	s_waitcnt lgkmcnt(0)
	v_max_f32_e32 v50, v50, v50
	v_max_f32_e32 v5, v5, v50
	ds_bpermute_b32 v50, v25, v49
	ds_bpermute_b32 v51, v26, v5
	s_waitcnt lgkmcnt(1)
	v_add_f32_e32 v49, v49, v50
	s_waitcnt lgkmcnt(0)
	v_max_f32_e32 v50, v51, v51
	ds_bpermute_b32 v51, v26, v49
	v_max_f32_e32 v5, v5, v50
	ds_bpermute_b32 v50, v27, v5
	s_waitcnt lgkmcnt(1)
	v_add_f32_e32 v49, v49, v51
	ds_bpermute_b32 v51, v27, v49
	s_waitcnt lgkmcnt(1)
	v_max_f32_e32 v50, v50, v50
	v_max_f32_e32 v5, v5, v50
	ds_bpermute_b32 v50, v28, v5
	s_waitcnt lgkmcnt(1)
	v_add_f32_e32 v49, v49, v51
	ds_bpermute_b32 v51, v28, v49
	s_waitcnt lgkmcnt(1)
	v_max_f32_e32 v50, v50, v50
	v_max_f32_e32 v5, v5, v50
	ds_bpermute_b32 v50, v29, v5
	s_waitcnt lgkmcnt(1)
	v_add_f32_e32 v49, v49, v51
	ds_bpermute_b32 v51, v29, v49
	s_waitcnt lgkmcnt(1)
	v_max_f32_e32 v50, v50, v50
	v_max_f32_e32 v5, v5, v50
	s_waitcnt lgkmcnt(0)
	v_add_f32_e32 v49, v49, v51
	ds_bpermute_b32 v51, v30, v5
	ds_bpermute_b32 v50, v30, v49
	s_waitcnt lgkmcnt(1)
	v_max3_f32 v5, v5, v51, s73
	s_and_saveexec_b64 s[20:21], s[38:39]
	s_cbranch_execz .Lxqa_C0
	s_waitcnt lgkmcnt(0)
	v_add_f32_e32 v49, v49, v50
	v_fmamk_f32 v49, v49, 0x3a000000, v1
	v_mul_f32_e32 v50, 0x4f800000, v49
	v_cmp_gt_f32_e32 vcc, s70, v49
	s_nop 1
	v_cndmask_b32_e32 v49, v49, v50, vcc
	v_sqrt_f32_e32 v50, v49
	s_nop 0
	v_add_u32_e32 v51, -1, v50
	v_fma_f32 v53, -v51, v50, v49
	v_add_u32_e32 v52, 1, v50
	v_cmp_ge_f32_e64 s[40:41], 0, v53
	s_nop 1
	v_cndmask_b32_e64 v51, v50, v51, s[40:41]
	v_fma_f32 v50, -v52, v50, v49
	v_cmp_lt_f32_e64 s[40:41], 0, v50
	s_nop 1
	v_cndmask_b32_e64 v50, v51, v52, s[40:41]
	v_mul_f32_e32 v51, 0x37800000, v50
	v_cndmask_b32_e32 v50, v50, v51, vcc
	v_cmp_class_f32_e32 vcc, v49, v226
	s_nop 1
	v_cndmask_b32_e32 v49, v50, v49, vcc
	v_div_scale_f32 v50, s[26:27], v49, v49, 1.0
	v_rcp_f32_e32 v51, v50
	s_nop 0
	v_fma_f32 v52, -v50, v51, 1.0
	v_fmac_f32_e32 v51, v52, v51
	v_div_scale_f32 v52, vcc, 1.0, v49, 1.0
	v_mul_f32_e32 v53, v52, v51
	v_fma_f32 v54, -v50, v53, v52
	v_fmac_f32_e32 v53, v54, v51
	v_fma_f32 v50, -v50, v53, v52
	v_div_fmas_f32 v50, v50, v51, v53
	v_div_fixup_f32 v49, v50, v49, 1.0
	v_mul_f32_e32 v50, 0x3c010204, v5
	v_mul_f32_e32 v49, v50, v49
	global_store_dword v115, v49, s[10:11]
.Lxqa_C0:
	s_or_b64 exec, exec, s[20:21]
	v_div_scale_f32 v49, s[20:21], v5, v5, s47
	s_waitcnt lgkmcnt(0)
	v_rcp_f32_e32 v50, v49
	v_div_scale_f32 v51, vcc, s47, v5, s47
	s_add_i32 s1, s1, -1
	v_fma_f32 v52, -v49, v50, 1.0
	v_fmac_f32_e32 v50, v52, v50
	v_mul_f32_e32 v52, v51, v50
	v_fma_f32 v53, -v49, v52, v51
	v_fmac_f32_e32 v52, v53, v50
	v_fma_f32 v49, -v49, v52, v51
	v_div_fmas_f32 v49, v49, v50, v52
	v_div_fixup_f32 v5, v49, v5, s47
	v_mul_f32_e32 v47, v5, v47
	v_mul_f32_e32 v46, v5, v46
	v_mul_f32_e32 v48, v5, v48
	v_rndne_f32_e32 v47, v47
	v_rndne_f32_e32 v46, v46
	v_mul_f32_e32 v45, v5, v45
	v_rndne_f32_e32 v48, v48
	v_cvt_i32_f32_e32 v47, v47
	v_cvt_i32_f32_e32 v46, v46
	v_rndne_f32_e32 v45, v45
	v_mul_f32_e32 v43, v5, v43
	v_mul_f32_e32 v41, v5, v41
	v_cvt_i32_f32_e32 v48, v48
	v_cvt_i32_f32_e32 v45, v45
	v_mul_f32_e32 v44, v5, v44
	v_rndne_f32_e32 v43, v43
	v_rndne_f32_e32 v41, v41
	v_mul_f32_e32 v40, v5, v40
	v_rndne_f32_e32 v44, v44
	v_cvt_i32_f32_e32 v43, v43
	v_cvt_i32_f32_e32 v41, v41
	v_rndne_f32_e32 v40, v40
	v_cvt_i32_f32_e32 v49, v44
	v_cvt_i32_f32_e32 v40, v40
	v_med3_i32 v47, v47, s71, v235
	v_med3_i32 v46, v46, s71, v235
	v_mul_f32_e32 v38, v5, v38
	v_mul_f32_e32 v37, v5, v37
	v_med3_i32 v48, v48, s71, v235
	v_lshlrev_b32_e32 v47, 8, v47
	v_lshlrev_b32_e32 v46, 16, v46
	v_med3_i32 v45, v45, s71, v235
	v_mul_f32_e32 v39, v5, v39
	v_rndne_f32_e32 v38, v38
	v_rndne_f32_e32 v37, v37
	v_mul_f32_e32 v36, v5, v36
	v_and_b32_e32 v46, 0xff0000, v46
	v_lshlrev_b32_e32 v45, 24, v45
	v_perm_b32 v44, v47, v48, s49
	v_med3_i32 v43, v43, s71, v235
	v_med3_i32 v41, v41, s71, v235
	v_rndne_f32_e32 v39, v39
	v_cvt_i32_f32_e32 v38, v38
	v_cvt_i32_f32_e32 v37, v37
	v_rndne_f32_e32 v36, v36
	v_or3_b32 v44, v44, v45, v46
	v_med3_i32 v45, v49, s71, v235
	v_lshlrev_b32_e32 v43, 8, v43
	v_lshlrev_b32_e32 v41, 16, v41
	v_med3_i32 v40, v40, s71, v235
	v_cvt_i32_f32_e32 v39, v39
	v_cvt_i32_f32_e32 v36, v36
	v_mul_f32_e32 v34, v5, v34
	v_mul_f32_e32 v33, v5, v33
	v_and_b32_e32 v43, 0xff00, v43
	v_and_b32_e32 v41, 0xff0000, v41
	v_perm_b32 v40, v40, v45, s48
	v_mul_f32_e32 v35, v5, v35
	v_rndne_f32_e32 v34, v34
	v_rndne_f32_e32 v33, v33
	v_mul_f32_e32 v32, v5, v32
	v_or3_b32 v45, v40, v43, v41
	v_rndne_f32_e32 v35, v35
	v_cvt_i32_f32_e32 v40, v34
	v_cvt_i32_f32_e32 v33, v33
	v_rndne_f32_e32 v32, v32
	v_med3_i32 v38, v38, s71, v235
	v_med3_i32 v37, v37, s71, v235
	v_cvt_i32_f32_e32 v35, v35
	v_cvt_i32_f32_e32 v32, v32
	v_med3_i32 v39, v39, s71, v235
	v_lshlrev_b32_e32 v38, 8, v38
	v_lshlrev_b32_e32 v37, 16, v37
	v_med3_i32 v36, v36, s71, v235
	v_mul_f32_e32 v17, v5, v17
	v_mul_f32_e32 v16, v5, v16
	v_and_b32_e32 v37, 0xff0000, v37
	v_lshlrev_b32_e32 v36, 24, v36
	v_perm_b32 v34, v38, v39, s49
	v_mul_f32_e32 v31, v5, v31
	v_rndne_f32_e32 v17, v17
	v_rndne_f32_e32 v16, v16
	v_mul_f32_e32 v15, v5, v15
	v_or3_b32 v34, v34, v36, v37
	v_med3_i32 v36, v40, s71, v235
	v_med3_i32 v33, v33, s71, v235
	v_rndne_f32_e32 v31, v31
	v_cvt_i32_f32_e32 v17, v17
	v_cvt_i32_f32_e32 v16, v16
	v_rndne_f32_e32 v15, v15
	v_mul_f32_e32 v13, v5, v13
	v_mul_f32_e32 v12, v5, v12
	v_med3_i32 v35, v35, s71, v235
	v_lshlrev_b32_e32 v36, 8, v36
	v_lshlrev_b32_e32 v33, 16, v33
	v_med3_i32 v32, v32, s71, v235
	v_cvt_i32_f32_e32 v31, v31
	v_cvt_i32_f32_e32 v15, v15
	v_mul_f32_e32 v14, v5, v14
	v_rndne_f32_e32 v13, v13
	v_rndne_f32_e32 v12, v12
	v_mul_f32_e32 v11, v5, v11
	v_and_b32_e32 v36, 0xff00, v36
	v_and_b32_e32 v33, 0xff0000, v33
	v_perm_b32 v32, v32, v35, s48
	v_rndne_f32_e32 v14, v14
	v_cvt_i32_f32_e32 v13, v13
	v_cvt_i32_f32_e32 v12, v12
	v_rndne_f32_e32 v11, v11
	v_or3_b32 v35, v32, v36, v33
	v_cvt_i32_f32_e32 v32, v14
	v_cvt_i32_f32_e32 v11, v11
	v_med3_i32 v17, v17, s71, v235
	v_med3_i32 v16, v16, s71, v235
	v_mul_f32_e32 v9, v5, v9
	v_mul_f32_e32 v8, v5, v8
	v_med3_i32 v31, v31, s71, v235
	v_lshlrev_b32_e32 v17, 8, v17
	v_lshlrev_b32_e32 v16, 16, v16
	v_med3_i32 v15, v15, s71, v235
	v_mul_f32_e32 v10, v5, v10
	v_rndne_f32_e32 v9, v9
	v_rndne_f32_e32 v8, v8
	v_mul_f32_e32 v7, v5, v7
	v_and_b32_e32 v16, 0xff0000, v16
	v_lshlrev_b32_e32 v15, 24, v15
	v_perm_b32 v14, v17, v31, s49
	v_med3_i32 v13, v13, s71, v235
	v_med3_i32 v12, v12, s71, v235
	v_rndne_f32_e32 v10, v10
	v_cvt_i32_f32_e32 v9, v9
	v_cvt_i32_f32_e32 v8, v8
	v_rndne_f32_e32 v7, v7
	v_or3_b32 v14, v14, v15, v16
	v_med3_i32 v15, v32, s71, v235
	v_lshlrev_b32_e32 v13, 8, v13
	v_lshlrev_b32_e32 v12, 16, v12
	v_med3_i32 v11, v11, s71, v235
	v_cvt_i32_f32_e32 v10, v10
	v_cvt_i32_f32_e32 v7, v7
	v_mul_f32_e32 v4, v5, v4
	v_mul_f32_e32 v3, v5, v3
	v_and_b32_e32 v13, 0xff00, v13
	v_and_b32_e32 v12, 0xff0000, v12
	v_perm_b32 v11, v11, v15, s48
	v_mul_f32_e32 v6, v5, v6
	v_rndne_f32_e32 v4, v4
	v_rndne_f32_e32 v3, v3
	v_mul_f32_e32 v2, v5, v2
	v_or3_b32 v15, v11, v13, v12
	v_rndne_f32_e32 v6, v6
	v_cvt_i32_f32_e32 v11, v4
	v_cvt_i32_f32_e32 v3, v3
	v_rndne_f32_e32 v2, v2
	v_med3_i32 v9, v9, s71, v235
	v_med3_i32 v8, v8, s71, v235
	v_cvt_i32_f32_e32 v6, v6
	v_cvt_i32_f32_e32 v2, v2
	v_med3_i32 v10, v10, s71, v235
	v_lshlrev_b32_e32 v9, 8, v9
	v_lshlrev_b32_e32 v8, 16, v8
	v_med3_i32 v7, v7, s71, v235
	v_and_b32_e32 v8, 0xff0000, v8
	v_lshlrev_b32_e32 v7, 24, v7
	v_perm_b32 v4, v9, v10, s49
	v_or3_b32 v4, v4, v7, v8
	v_med3_i32 v7, v11, s71, v235
	v_med3_i32 v3, v3, s71, v235
	v_med3_i32 v6, v6, s71, v235
	v_lshlrev_b32_e32 v7, 8, v7
	v_lshlrev_b32_e32 v3, 16, v3
	v_med3_i32 v2, v2, s71, v235
	v_and_b32_e32 v7, 0xff00, v7
	v_and_b32_e32 v3, 0xff0000, v3
	v_perm_b32 v2, v2, v6, s48
	s_add_u32 s10, s10, s12
	v_or3_b32 v5, v2, v7, v3
	s_addc_u32 s11, s11, s13
	global_store_dwordx2 v[22:23], v[44:45], off offset:-1024
	global_store_dwordx2 v[22:23], v[34:35], off offset:-512
	global_store_dwordx2 v[22:23], v[14:15], off
	global_store_dwordx2 v[22:23], v[4:5], off offset:512
	v_lshl_add_u64 v[18:19], v[18:19], 0, s[14:15]
	v_lshl_add_u64 v[20:21], v[20:21], 0, s[16:17]
	v_lshl_add_u64 v[22:23], v[22:23], 0, s[18:19]
	s_waitcnt vmcnt(12)
	v_mov_b32_e32 v14, v56
	v_mov_b32_e32 v15, v57
	v_mov_b32_e32 v16, v58
	v_mov_b32_e32 v17, v59
	v_mov_b32_e32 v10, v60
	v_mov_b32_e32 v11, v61
	v_mov_b32_e32 v12, v62
	v_mov_b32_e32 v13, v63
	v_mov_b32_e32 v6, v64
	v_mov_b32_e32 v7, v65
	v_mov_b32_e32 v8, v66
	v_mov_b32_e32 v9, v67
	v_mov_b32_e32 v2, v68
	v_mov_b32_e32 v3, v69
	v_mov_b32_e32 v4, v70
	v_mov_b32_e32 v5, v71
	v_mov_b32_e32 v49, v72
	v_lshlrev_b32_e32 v48, 16, v14
	v_and_b32_e32 v47, 0xffff0000, v14
	v_max_f32_e64 v14, |v47|, |v47|
	v_max_f32_e64 v31, |v48|, |v48|
	v_lshlrev_b32_e32 v46, 16, v15
	v_and_b32_e32 v45, 0xffff0000, v15
	v_max_f32_e32 v14, v31, v14
	v_max_f32_e64 v15, |v45|, |v45|
	v_max_f32_e64 v31, |v46|, |v46|
	v_max_f32_e32 v15, v31, v15
	v_lshlrev_b32_e32 v44, 16, v16
	v_and_b32_e32 v43, 0xffff0000, v16
	v_max3_f32 v14, v14, 0, v15
	v_max_f32_e64 v15, |v43|, |v43|
	v_max_f32_e64 v16, |v44|, |v44|
	v_lshlrev_b32_e32 v41, 16, v17
	v_and_b32_e32 v40, 0xffff0000, v17
	v_max_f32_e32 v15, v16, v15
	v_max_f32_e64 v16, |v40|, |v40|
	v_max_f32_e64 v17, |v41|, |v41|
	v_max_f32_e32 v16, v17, v16
	v_lshlrev_b32_e32 v39, 16, v10
	v_and_b32_e32 v38, 0xffff0000, v10
	v_max3_f32 v14, v14, v15, v16
	v_max_f32_e64 v10, |v38|, |v38|
	v_max_f32_e64 v15, |v39|, |v39|
	v_lshlrev_b32_e32 v37, 16, v11
	v_and_b32_e32 v36, 0xffff0000, v11
	v_max_f32_e32 v10, v15, v10
	v_max_f32_e64 v11, |v36|, |v36|
	v_max_f32_e64 v15, |v37|, |v37|
	v_max_f32_e32 v11, v15, v11
	v_lshlrev_b32_e32 v35, 16, v12
	v_and_b32_e32 v34, 0xffff0000, v12
	v_max3_f32 v10, v14, v10, v11
	v_max_f32_e64 v11, |v34|, |v34|
	v_max_f32_e64 v12, |v35|, |v35|
	v_lshlrev_b32_e32 v33, 16, v13
	v_and_b32_e32 v32, 0xffff0000, v13
	v_max_f32_e32 v11, v12, v11
	v_max_f32_e64 v12, |v32|, |v32|
	v_max_f32_e64 v13, |v33|, |v33|
	v_max_f32_e32 v12, v13, v12
	v_lshlrev_b32_e32 v31, 16, v6
	v_and_b32_e32 v17, 0xffff0000, v6
	v_max3_f32 v10, v10, v11, v12
	v_max_f32_e64 v6, |v17|, |v17|
	v_max_f32_e64 v11, |v31|, |v31|
	v_lshlrev_b32_e32 v16, 16, v7
	v_and_b32_e32 v15, 0xffff0000, v7
	v_max_f32_e32 v6, v11, v6
	v_max_f32_e64 v7, |v15|, |v15|
	v_max_f32_e64 v11, |v16|, |v16|
	v_max_f32_e32 v7, v11, v7
	v_lshlrev_b32_e32 v14, 16, v8
	v_and_b32_e32 v13, 0xffff0000, v8
	v_max3_f32 v6, v10, v6, v7
	v_max_f32_e64 v7, |v13|, |v13|
	v_max_f32_e64 v8, |v14|, |v14|
	v_lshlrev_b32_e32 v12, 16, v9
	v_and_b32_e32 v11, 0xffff0000, v9
	v_max_f32_e32 v7, v8, v7
	v_max_f32_e64 v8, |v11|, |v11|
	v_max_f32_e64 v9, |v12|, |v12|
	v_max_f32_e32 v8, v9, v8
	v_lshlrev_b32_e32 v10, 16, v2
	v_and_b32_e32 v9, 0xffff0000, v2
	v_max3_f32 v6, v6, v7, v8
	v_max_f32_e64 v2, |v9|, |v9|
	v_max_f32_e64 v7, |v10|, |v10|
	v_max_f32_e32 v2, v7, v2
	v_lshlrev_b32_e32 v8, 16, v3
	v_and_b32_e32 v7, 0xffff0000, v3
	v_max_f32_e64 v3, |v7|, |v7|
	v_max_f32_e64 v50, |v8|, |v8|
	v_max_f32_e32 v3, v50, v3
	v_max3_f32 v50, v6, v2, v3
	v_lshlrev_b32_e32 v6, 16, v4
	v_and_b32_e32 v4, 0xffff0000, v4
	v_max_f32_e64 v2, |v4|, |v4|
	v_max_f32_e64 v3, |v6|, |v6|
	v_max_f32_e32 v51, v3, v2
	v_lshlrev_b32_e32 v3, 16, v5
	v_and_b32_e32 v2, 0xffff0000, v5
	v_max_f32_e64 v5, |v2|, |v2|
	v_max_f32_e64 v52, |v3|, |v3|
	v_max_f32_e32 v5, v52, v5
	v_max3_f32 v5, v50, v51, v5
	ds_bpermute_b32 v50, v25, v5
	s_waitcnt lgkmcnt(0)
	v_max_f32_e32 v50, v50, v50
	v_max_f32_e32 v5, v5, v50
	ds_bpermute_b32 v50, v25, v49
	ds_bpermute_b32 v51, v26, v5
	s_waitcnt lgkmcnt(1)
	v_add_f32_e32 v49, v49, v50
	s_waitcnt lgkmcnt(0)
	v_max_f32_e32 v50, v51, v51
	ds_bpermute_b32 v51, v26, v49
	v_max_f32_e32 v5, v5, v50
	ds_bpermute_b32 v50, v27, v5
	s_waitcnt lgkmcnt(1)
	v_add_f32_e32 v49, v49, v51
	ds_bpermute_b32 v51, v27, v49
	s_waitcnt lgkmcnt(1)
	v_max_f32_e32 v50, v50, v50
	v_max_f32_e32 v5, v5, v50
	ds_bpermute_b32 v50, v28, v5
	s_waitcnt lgkmcnt(1)
	v_add_f32_e32 v49, v49, v51
	ds_bpermute_b32 v51, v28, v49
	s_waitcnt lgkmcnt(1)
	v_max_f32_e32 v50, v50, v50
	v_max_f32_e32 v5, v5, v50
	ds_bpermute_b32 v50, v29, v5
	s_waitcnt lgkmcnt(1)
	v_add_f32_e32 v49, v49, v51
	ds_bpermute_b32 v51, v29, v49
	s_waitcnt lgkmcnt(1)
	v_max_f32_e32 v50, v50, v50
	v_max_f32_e32 v5, v5, v50
	s_waitcnt lgkmcnt(0)
	v_add_f32_e32 v49, v49, v51
	ds_bpermute_b32 v51, v30, v5
	ds_bpermute_b32 v50, v30, v49
	s_waitcnt lgkmcnt(1)
	v_max3_f32 v5, v5, v51, s73
	s_and_saveexec_b64 s[20:21], s[38:39]
	s_cbranch_execz .Lxqa_C1
	s_waitcnt lgkmcnt(0)
	v_add_f32_e32 v49, v49, v50
	v_fmamk_f32 v49, v49, 0x3a000000, v1
	v_mul_f32_e32 v50, 0x4f800000, v49
	v_cmp_gt_f32_e32 vcc, s70, v49
	s_nop 1
	v_cndmask_b32_e32 v49, v49, v50, vcc
	v_sqrt_f32_e32 v50, v49
	s_nop 0
	v_add_u32_e32 v51, -1, v50
	v_fma_f32 v53, -v51, v50, v49
	v_add_u32_e32 v52, 1, v50
	v_cmp_ge_f32_e64 s[40:41], 0, v53
	s_nop 1
	v_cndmask_b32_e64 v51, v50, v51, s[40:41]
	v_fma_f32 v50, -v52, v50, v49
	v_cmp_lt_f32_e64 s[40:41], 0, v50
	s_nop 1
	v_cndmask_b32_e64 v50, v51, v52, s[40:41]
	v_mul_f32_e32 v51, 0x37800000, v50
	v_cndmask_b32_e32 v50, v50, v51, vcc
	v_cmp_class_f32_e32 vcc, v49, v226
	s_nop 1
	v_cndmask_b32_e32 v49, v50, v49, vcc
	v_div_scale_f32 v50, s[26:27], v49, v49, 1.0
	v_rcp_f32_e32 v51, v50
	s_nop 0
	v_fma_f32 v52, -v50, v51, 1.0
	v_fmac_f32_e32 v51, v52, v51
	v_div_scale_f32 v52, vcc, 1.0, v49, 1.0
	v_mul_f32_e32 v53, v52, v51
	v_fma_f32 v54, -v50, v53, v52
	v_fmac_f32_e32 v53, v54, v51
	v_fma_f32 v50, -v50, v53, v52
	v_div_fmas_f32 v50, v50, v51, v53
	v_div_fixup_f32 v49, v50, v49, 1.0
	v_mul_f32_e32 v50, 0x3c010204, v5
	v_mul_f32_e32 v49, v50, v49
	global_store_dword v115, v49, s[10:11]
.Lxqa_C1:
	s_or_b64 exec, exec, s[20:21]
	v_div_scale_f32 v49, s[20:21], v5, v5, s47
	s_waitcnt lgkmcnt(0)
	v_rcp_f32_e32 v50, v49
	v_div_scale_f32 v51, vcc, s47, v5, s47
	s_add_i32 s1, s1, -1
	v_fma_f32 v52, -v49, v50, 1.0
	v_fmac_f32_e32 v50, v52, v50
	v_mul_f32_e32 v52, v51, v50
	v_fma_f32 v53, -v49, v52, v51
	v_fmac_f32_e32 v52, v53, v50
	v_fma_f32 v49, -v49, v52, v51
	v_div_fmas_f32 v49, v49, v50, v52
	v_div_fixup_f32 v5, v49, v5, s47
	v_mul_f32_e32 v47, v5, v47
	v_mul_f32_e32 v46, v5, v46
	v_mul_f32_e32 v48, v5, v48
	v_rndne_f32_e32 v47, v47
	v_rndne_f32_e32 v46, v46
	v_mul_f32_e32 v45, v5, v45
	v_rndne_f32_e32 v48, v48
	v_cvt_i32_f32_e32 v47, v47
	v_cvt_i32_f32_e32 v46, v46
	v_rndne_f32_e32 v45, v45
	v_mul_f32_e32 v43, v5, v43
	v_mul_f32_e32 v41, v5, v41
	v_cvt_i32_f32_e32 v48, v48
	v_cvt_i32_f32_e32 v45, v45
	v_mul_f32_e32 v44, v5, v44
	v_rndne_f32_e32 v43, v43
	v_rndne_f32_e32 v41, v41
	v_mul_f32_e32 v40, v5, v40
	v_rndne_f32_e32 v44, v44
	v_cvt_i32_f32_e32 v43, v43
	v_cvt_i32_f32_e32 v41, v41
	v_rndne_f32_e32 v40, v40
	v_cvt_i32_f32_e32 v49, v44
	v_cvt_i32_f32_e32 v40, v40
	v_med3_i32 v47, v47, s71, v235
	v_med3_i32 v46, v46, s71, v235
	v_mul_f32_e32 v38, v5, v38
	v_mul_f32_e32 v37, v5, v37
	v_med3_i32 v48, v48, s71, v235
	v_lshlrev_b32_e32 v47, 8, v47
	v_lshlrev_b32_e32 v46, 16, v46
	v_med3_i32 v45, v45, s71, v235
	v_mul_f32_e32 v39, v5, v39
	v_rndne_f32_e32 v38, v38
	v_rndne_f32_e32 v37, v37
	v_mul_f32_e32 v36, v5, v36
	v_and_b32_e32 v46, 0xff0000, v46
	v_lshlrev_b32_e32 v45, 24, v45
	v_perm_b32 v44, v47, v48, s49
	v_med3_i32 v43, v43, s71, v235
	v_med3_i32 v41, v41, s71, v235
	v_rndne_f32_e32 v39, v39
	v_cvt_i32_f32_e32 v38, v38
	v_cvt_i32_f32_e32 v37, v37
	v_rndne_f32_e32 v36, v36
	v_or3_b32 v44, v44, v45, v46
	v_med3_i32 v45, v49, s71, v235
	v_lshlrev_b32_e32 v43, 8, v43
	v_lshlrev_b32_e32 v41, 16, v41
	v_med3_i32 v40, v40, s71, v235
	v_cvt_i32_f32_e32 v39, v39
	v_cvt_i32_f32_e32 v36, v36
	v_mul_f32_e32 v34, v5, v34
	v_mul_f32_e32 v33, v5, v33
	v_and_b32_e32 v43, 0xff00, v43
	v_and_b32_e32 v41, 0xff0000, v41
	v_perm_b32 v40, v40, v45, s48
	v_mul_f32_e32 v35, v5, v35
	v_rndne_f32_e32 v34, v34
	v_rndne_f32_e32 v33, v33
	v_mul_f32_e32 v32, v5, v32
	v_or3_b32 v45, v40, v43, v41
	v_rndne_f32_e32 v35, v35
	v_cvt_i32_f32_e32 v40, v34
	v_cvt_i32_f32_e32 v33, v33
	v_rndne_f32_e32 v32, v32
	v_med3_i32 v38, v38, s71, v235
	v_med3_i32 v37, v37, s71, v235
	v_cvt_i32_f32_e32 v35, v35
	v_cvt_i32_f32_e32 v32, v32
	v_med3_i32 v39, v39, s71, v235
	v_lshlrev_b32_e32 v38, 8, v38
	v_lshlrev_b32_e32 v37, 16, v37
	v_med3_i32 v36, v36, s71, v235
	v_mul_f32_e32 v17, v5, v17
	v_mul_f32_e32 v16, v5, v16
	v_and_b32_e32 v37, 0xff0000, v37
	v_lshlrev_b32_e32 v36, 24, v36
	v_perm_b32 v34, v38, v39, s49
	v_mul_f32_e32 v31, v5, v31
	v_rndne_f32_e32 v17, v17
	v_rndne_f32_e32 v16, v16
	v_mul_f32_e32 v15, v5, v15
	v_or3_b32 v34, v34, v36, v37
	v_med3_i32 v36, v40, s71, v235
	v_med3_i32 v33, v33, s71, v235
	v_rndne_f32_e32 v31, v31
	v_cvt_i32_f32_e32 v17, v17
	v_cvt_i32_f32_e32 v16, v16
	v_rndne_f32_e32 v15, v15
	v_mul_f32_e32 v13, v5, v13
	v_mul_f32_e32 v12, v5, v12
	v_med3_i32 v35, v35, s71, v235
	v_lshlrev_b32_e32 v36, 8, v36
	v_lshlrev_b32_e32 v33, 16, v33
	v_med3_i32 v32, v32, s71, v235
	v_cvt_i32_f32_e32 v31, v31
	v_cvt_i32_f32_e32 v15, v15
	v_mul_f32_e32 v14, v5, v14
	v_rndne_f32_e32 v13, v13
	v_rndne_f32_e32 v12, v12
	v_mul_f32_e32 v11, v5, v11
	v_and_b32_e32 v36, 0xff00, v36
	v_and_b32_e32 v33, 0xff0000, v33
	v_perm_b32 v32, v32, v35, s48
	v_rndne_f32_e32 v14, v14
	v_cvt_i32_f32_e32 v13, v13
	v_cvt_i32_f32_e32 v12, v12
	v_rndne_f32_e32 v11, v11
	v_or3_b32 v35, v32, v36, v33
	v_cvt_i32_f32_e32 v32, v14
	v_cvt_i32_f32_e32 v11, v11
	v_med3_i32 v17, v17, s71, v235
	v_med3_i32 v16, v16, s71, v235
	v_mul_f32_e32 v9, v5, v9
	v_mul_f32_e32 v8, v5, v8
	v_med3_i32 v31, v31, s71, v235
	v_lshlrev_b32_e32 v17, 8, v17
	v_lshlrev_b32_e32 v16, 16, v16
	v_med3_i32 v15, v15, s71, v235
	v_mul_f32_e32 v10, v5, v10
	v_rndne_f32_e32 v9, v9
	v_rndne_f32_e32 v8, v8
	v_mul_f32_e32 v7, v5, v7
	v_and_b32_e32 v16, 0xff0000, v16
	v_lshlrev_b32_e32 v15, 24, v15
	v_perm_b32 v14, v17, v31, s49
	v_med3_i32 v13, v13, s71, v235
	v_med3_i32 v12, v12, s71, v235
	v_rndne_f32_e32 v10, v10
	v_cvt_i32_f32_e32 v9, v9
	v_cvt_i32_f32_e32 v8, v8
	v_rndne_f32_e32 v7, v7
	v_or3_b32 v14, v14, v15, v16
	v_med3_i32 v15, v32, s71, v235
	v_lshlrev_b32_e32 v13, 8, v13
	v_lshlrev_b32_e32 v12, 16, v12
	v_med3_i32 v11, v11, s71, v235
	v_cvt_i32_f32_e32 v10, v10
	v_cvt_i32_f32_e32 v7, v7
	v_mul_f32_e32 v4, v5, v4
	v_mul_f32_e32 v3, v5, v3
	v_and_b32_e32 v13, 0xff00, v13
	v_and_b32_e32 v12, 0xff0000, v12
	v_perm_b32 v11, v11, v15, s48
	v_mul_f32_e32 v6, v5, v6
	v_rndne_f32_e32 v4, v4
	v_rndne_f32_e32 v3, v3
	v_mul_f32_e32 v2, v5, v2
	v_or3_b32 v15, v11, v13, v12
	v_rndne_f32_e32 v6, v6
	v_cvt_i32_f32_e32 v11, v4
	v_cvt_i32_f32_e32 v3, v3
	v_rndne_f32_e32 v2, v2
	v_med3_i32 v9, v9, s71, v235
	v_med3_i32 v8, v8, s71, v235
	v_cvt_i32_f32_e32 v6, v6
	v_cvt_i32_f32_e32 v2, v2
	v_med3_i32 v10, v10, s71, v235
	v_lshlrev_b32_e32 v9, 8, v9
	v_lshlrev_b32_e32 v8, 16, v8
	v_med3_i32 v7, v7, s71, v235
	v_and_b32_e32 v8, 0xff0000, v8
	v_lshlrev_b32_e32 v7, 24, v7
	v_perm_b32 v4, v9, v10, s49
	v_or3_b32 v4, v4, v7, v8
	v_med3_i32 v7, v11, s71, v235
	v_med3_i32 v3, v3, s71, v235
	v_med3_i32 v6, v6, s71, v235
	v_lshlrev_b32_e32 v7, 8, v7
	v_lshlrev_b32_e32 v3, 16, v3
	v_med3_i32 v2, v2, s71, v235
	v_and_b32_e32 v7, 0xff00, v7
	v_and_b32_e32 v3, 0xff0000, v3
	v_perm_b32 v2, v2, v6, s48
	s_add_u32 s10, s10, s12
	v_or3_b32 v5, v2, v7, v3
	s_addc_u32 s11, s11, s13
	global_store_dwordx2 v[22:23], v[44:45], off offset:-1024
	global_store_dwordx2 v[22:23], v[34:35], off offset:-512
	global_store_dwordx2 v[22:23], v[14:15], off
	global_store_dwordx2 v[22:23], v[4:5], off offset:512
	v_lshl_add_u64 v[18:19], v[18:19], 0, s[14:15]
	v_lshl_add_u64 v[20:21], v[20:21], 0, s[16:17]
	v_lshl_add_u64 v[22:23], v[22:23], 0, s[18:19]
	s_waitcnt vmcnt(12)
	v_mov_b32_e32 v14, v74
	v_mov_b32_e32 v15, v75
	v_mov_b32_e32 v16, v76
	v_mov_b32_e32 v17, v77
	v_mov_b32_e32 v10, v78
	v_mov_b32_e32 v11, v79
	v_mov_b32_e32 v12, v80
	v_mov_b32_e32 v13, v81
	v_mov_b32_e32 v6, v82
	v_mov_b32_e32 v7, v83
	v_mov_b32_e32 v8, v84
	v_mov_b32_e32 v9, v85
	v_mov_b32_e32 v2, v86
	v_mov_b32_e32 v3, v87
	v_mov_b32_e32 v4, v88
	v_mov_b32_e32 v5, v89
	v_mov_b32_e32 v49, v90
	v_lshlrev_b32_e32 v48, 16, v14
	v_and_b32_e32 v47, 0xffff0000, v14
	v_max_f32_e64 v14, |v47|, |v47|
	v_max_f32_e64 v31, |v48|, |v48|
	v_lshlrev_b32_e32 v46, 16, v15
	v_and_b32_e32 v45, 0xffff0000, v15
	v_max_f32_e32 v14, v31, v14
	v_max_f32_e64 v15, |v45|, |v45|
	v_max_f32_e64 v31, |v46|, |v46|
	v_max_f32_e32 v15, v31, v15
	v_lshlrev_b32_e32 v44, 16, v16
	v_and_b32_e32 v43, 0xffff0000, v16
	v_max3_f32 v14, v14, 0, v15
	v_max_f32_e64 v15, |v43|, |v43|
	v_max_f32_e64 v16, |v44|, |v44|
	v_lshlrev_b32_e32 v41, 16, v17
	v_and_b32_e32 v40, 0xffff0000, v17
	v_max_f32_e32 v15, v16, v15
	v_max_f32_e64 v16, |v40|, |v40|
	v_max_f32_e64 v17, |v41|, |v41|
	v_max_f32_e32 v16, v17, v16
	v_lshlrev_b32_e32 v39, 16, v10
	v_and_b32_e32 v38, 0xffff0000, v10
	v_max3_f32 v14, v14, v15, v16
	v_max_f32_e64 v10, |v38|, |v38|
	v_max_f32_e64 v15, |v39|, |v39|
	v_lshlrev_b32_e32 v37, 16, v11
	v_and_b32_e32 v36, 0xffff0000, v11
	v_max_f32_e32 v10, v15, v10
	v_max_f32_e64 v11, |v36|, |v36|
	v_max_f32_e64 v15, |v37|, |v37|
	v_max_f32_e32 v11, v15, v11
	v_lshlrev_b32_e32 v35, 16, v12
	v_and_b32_e32 v34, 0xffff0000, v12
	v_max3_f32 v10, v14, v10, v11
	v_max_f32_e64 v11, |v34|, |v34|
	v_max_f32_e64 v12, |v35|, |v35|
	v_lshlrev_b32_e32 v33, 16, v13
	v_and_b32_e32 v32, 0xffff0000, v13
	v_max_f32_e32 v11, v12, v11
	v_max_f32_e64 v12, |v32|, |v32|
	v_max_f32_e64 v13, |v33|, |v33|
	v_max_f32_e32 v12, v13, v12
	v_lshlrev_b32_e32 v31, 16, v6
	v_and_b32_e32 v17, 0xffff0000, v6
	v_max3_f32 v10, v10, v11, v12
	v_max_f32_e64 v6, |v17|, |v17|
	v_max_f32_e64 v11, |v31|, |v31|
	v_lshlrev_b32_e32 v16, 16, v7
	v_and_b32_e32 v15, 0xffff0000, v7
	v_max_f32_e32 v6, v11, v6
	v_max_f32_e64 v7, |v15|, |v15|
	v_max_f32_e64 v11, |v16|, |v16|
	v_max_f32_e32 v7, v11, v7
	v_lshlrev_b32_e32 v14, 16, v8
	v_and_b32_e32 v13, 0xffff0000, v8
	v_max3_f32 v6, v10, v6, v7
	v_max_f32_e64 v7, |v13|, |v13|
	v_max_f32_e64 v8, |v14|, |v14|
	v_lshlrev_b32_e32 v12, 16, v9
	v_and_b32_e32 v11, 0xffff0000, v9
	v_max_f32_e32 v7, v8, v7
	v_max_f32_e64 v8, |v11|, |v11|
	v_max_f32_e64 v9, |v12|, |v12|
	v_max_f32_e32 v8, v9, v8
	v_lshlrev_b32_e32 v10, 16, v2
	v_and_b32_e32 v9, 0xffff0000, v2
	v_max3_f32 v6, v6, v7, v8
	v_max_f32_e64 v2, |v9|, |v9|
	v_max_f32_e64 v7, |v10|, |v10|
	v_max_f32_e32 v2, v7, v2
	v_lshlrev_b32_e32 v8, 16, v3
	v_and_b32_e32 v7, 0xffff0000, v3
	v_max_f32_e64 v3, |v7|, |v7|
	v_max_f32_e64 v50, |v8|, |v8|
	v_max_f32_e32 v3, v50, v3
	v_max3_f32 v50, v6, v2, v3
	v_lshlrev_b32_e32 v6, 16, v4
	v_and_b32_e32 v4, 0xffff0000, v4
	v_max_f32_e64 v2, |v4|, |v4|
	v_max_f32_e64 v3, |v6|, |v6|
	v_max_f32_e32 v51, v3, v2
	v_lshlrev_b32_e32 v3, 16, v5
	v_and_b32_e32 v2, 0xffff0000, v5
	v_max_f32_e64 v5, |v2|, |v2|
	v_max_f32_e64 v52, |v3|, |v3|
	v_max_f32_e32 v5, v52, v5
	v_max3_f32 v5, v50, v51, v5
	ds_bpermute_b32 v50, v25, v5
	s_waitcnt lgkmcnt(0)
	v_max_f32_e32 v50, v50, v50
	v_max_f32_e32 v5, v5, v50
	ds_bpermute_b32 v50, v25, v49
	ds_bpermute_b32 v51, v26, v5
	s_waitcnt lgkmcnt(1)
	v_add_f32_e32 v49, v49, v50
	s_waitcnt lgkmcnt(0)
	v_max_f32_e32 v50, v51, v51
	ds_bpermute_b32 v51, v26, v49
	v_max_f32_e32 v5, v5, v50
	ds_bpermute_b32 v50, v27, v5
	s_waitcnt lgkmcnt(1)
	v_add_f32_e32 v49, v49, v51
	ds_bpermute_b32 v51, v27, v49
	s_waitcnt lgkmcnt(1)
	v_max_f32_e32 v50, v50, v50
	v_max_f32_e32 v5, v5, v50
	ds_bpermute_b32 v50, v28, v5
	s_waitcnt lgkmcnt(1)
	v_add_f32_e32 v49, v49, v51
	ds_bpermute_b32 v51, v28, v49
	s_waitcnt lgkmcnt(1)
	v_max_f32_e32 v50, v50, v50
	v_max_f32_e32 v5, v5, v50
	ds_bpermute_b32 v50, v29, v5
	s_waitcnt lgkmcnt(1)
	v_add_f32_e32 v49, v49, v51
	ds_bpermute_b32 v51, v29, v49
	s_waitcnt lgkmcnt(1)
	v_max_f32_e32 v50, v50, v50
	v_max_f32_e32 v5, v5, v50
	s_waitcnt lgkmcnt(0)
	v_add_f32_e32 v49, v49, v51
	ds_bpermute_b32 v51, v30, v5
	ds_bpermute_b32 v50, v30, v49
	s_waitcnt lgkmcnt(1)
	v_max3_f32 v5, v5, v51, s73
	s_and_saveexec_b64 s[20:21], s[38:39]
	s_cbranch_execz .Lxqa_C2
	s_waitcnt lgkmcnt(0)
	v_add_f32_e32 v49, v49, v50
	v_fmamk_f32 v49, v49, 0x3a000000, v1
	v_mul_f32_e32 v50, 0x4f800000, v49
	v_cmp_gt_f32_e32 vcc, s70, v49
	s_nop 1
	v_cndmask_b32_e32 v49, v49, v50, vcc
	v_sqrt_f32_e32 v50, v49
	s_nop 0
	v_add_u32_e32 v51, -1, v50
	v_fma_f32 v53, -v51, v50, v49
	v_add_u32_e32 v52, 1, v50
	v_cmp_ge_f32_e64 s[40:41], 0, v53
	s_nop 1
	v_cndmask_b32_e64 v51, v50, v51, s[40:41]
	v_fma_f32 v50, -v52, v50, v49
	v_cmp_lt_f32_e64 s[40:41], 0, v50
	s_nop 1
	v_cndmask_b32_e64 v50, v51, v52, s[40:41]
	v_mul_f32_e32 v51, 0x37800000, v50
	v_cndmask_b32_e32 v50, v50, v51, vcc
	v_cmp_class_f32_e32 vcc, v49, v226
	s_nop 1
	v_cndmask_b32_e32 v49, v50, v49, vcc
	v_div_scale_f32 v50, s[26:27], v49, v49, 1.0
	v_rcp_f32_e32 v51, v50
	s_nop 0
	v_fma_f32 v52, -v50, v51, 1.0
	v_fmac_f32_e32 v51, v52, v51
	v_div_scale_f32 v52, vcc, 1.0, v49, 1.0
	v_mul_f32_e32 v53, v52, v51
	v_fma_f32 v54, -v50, v53, v52
	v_fmac_f32_e32 v53, v54, v51
	v_fma_f32 v50, -v50, v53, v52
	v_div_fmas_f32 v50, v50, v51, v53
	v_div_fixup_f32 v49, v50, v49, 1.0
	v_mul_f32_e32 v50, 0x3c010204, v5
	v_mul_f32_e32 v49, v50, v49
	global_store_dword v115, v49, s[10:11]
.Lxqa_C2:
	s_or_b64 exec, exec, s[20:21]
	v_div_scale_f32 v49, s[20:21], v5, v5, s47
	s_waitcnt lgkmcnt(0)
	v_rcp_f32_e32 v50, v49
	v_div_scale_f32 v51, vcc, s47, v5, s47
	s_add_i32 s1, s1, -1
	v_fma_f32 v52, -v49, v50, 1.0
	v_fmac_f32_e32 v50, v52, v50
	v_mul_f32_e32 v52, v51, v50
	v_fma_f32 v53, -v49, v52, v51
	v_fmac_f32_e32 v52, v53, v50
	v_fma_f32 v49, -v49, v52, v51
	v_div_fmas_f32 v49, v49, v50, v52
	v_div_fixup_f32 v5, v49, v5, s47
	v_mul_f32_e32 v47, v5, v47
	v_mul_f32_e32 v46, v5, v46
	v_mul_f32_e32 v48, v5, v48
	v_rndne_f32_e32 v47, v47
	v_rndne_f32_e32 v46, v46
	v_mul_f32_e32 v45, v5, v45
	v_rndne_f32_e32 v48, v48
	v_cvt_i32_f32_e32 v47, v47
	v_cvt_i32_f32_e32 v46, v46
	v_rndne_f32_e32 v45, v45
	v_mul_f32_e32 v43, v5, v43
	v_mul_f32_e32 v41, v5, v41
	v_cvt_i32_f32_e32 v48, v48
	v_cvt_i32_f32_e32 v45, v45
	v_mul_f32_e32 v44, v5, v44
	v_rndne_f32_e32 v43, v43
	v_rndne_f32_e32 v41, v41
	v_mul_f32_e32 v40, v5, v40
	v_rndne_f32_e32 v44, v44
	v_cvt_i32_f32_e32 v43, v43
	v_cvt_i32_f32_e32 v41, v41
	v_rndne_f32_e32 v40, v40
	v_cvt_i32_f32_e32 v49, v44
	v_cvt_i32_f32_e32 v40, v40
	v_med3_i32 v47, v47, s71, v235
	v_med3_i32 v46, v46, s71, v235
	v_mul_f32_e32 v38, v5, v38
	v_mul_f32_e32 v37, v5, v37
	v_med3_i32 v48, v48, s71, v235
	v_lshlrev_b32_e32 v47, 8, v47
	v_lshlrev_b32_e32 v46, 16, v46
	v_med3_i32 v45, v45, s71, v235
	v_mul_f32_e32 v39, v5, v39
	v_rndne_f32_e32 v38, v38
	v_rndne_f32_e32 v37, v37
	v_mul_f32_e32 v36, v5, v36
	v_and_b32_e32 v46, 0xff0000, v46
	v_lshlrev_b32_e32 v45, 24, v45
	v_perm_b32 v44, v47, v48, s49
	v_med3_i32 v43, v43, s71, v235
	v_med3_i32 v41, v41, s71, v235
	v_rndne_f32_e32 v39, v39
	v_cvt_i32_f32_e32 v38, v38
	v_cvt_i32_f32_e32 v37, v37
	v_rndne_f32_e32 v36, v36
	v_or3_b32 v44, v44, v45, v46
	v_med3_i32 v45, v49, s71, v235
	v_lshlrev_b32_e32 v43, 8, v43
	v_lshlrev_b32_e32 v41, 16, v41
	v_med3_i32 v40, v40, s71, v235
	v_cvt_i32_f32_e32 v39, v39
	v_cvt_i32_f32_e32 v36, v36
	v_mul_f32_e32 v34, v5, v34
	v_mul_f32_e32 v33, v5, v33
	v_and_b32_e32 v43, 0xff00, v43
	v_and_b32_e32 v41, 0xff0000, v41
	v_perm_b32 v40, v40, v45, s48
	v_mul_f32_e32 v35, v5, v35
	v_rndne_f32_e32 v34, v34
	v_rndne_f32_e32 v33, v33
	v_mul_f32_e32 v32, v5, v32
	v_or3_b32 v45, v40, v43, v41
	v_rndne_f32_e32 v35, v35
	v_cvt_i32_f32_e32 v40, v34
	v_cvt_i32_f32_e32 v33, v33
	v_rndne_f32_e32 v32, v32
	v_med3_i32 v38, v38, s71, v235
	v_med3_i32 v37, v37, s71, v235
	v_cvt_i32_f32_e32 v35, v35
	v_cvt_i32_f32_e32 v32, v32
	v_med3_i32 v39, v39, s71, v235
	v_lshlrev_b32_e32 v38, 8, v38
	v_lshlrev_b32_e32 v37, 16, v37
	v_med3_i32 v36, v36, s71, v235
	v_mul_f32_e32 v17, v5, v17
	v_mul_f32_e32 v16, v5, v16
	v_and_b32_e32 v37, 0xff0000, v37
	v_lshlrev_b32_e32 v36, 24, v36
	v_perm_b32 v34, v38, v39, s49
	v_mul_f32_e32 v31, v5, v31
	v_rndne_f32_e32 v17, v17
	v_rndne_f32_e32 v16, v16
	v_mul_f32_e32 v15, v5, v15
	v_or3_b32 v34, v34, v36, v37
	v_med3_i32 v36, v40, s71, v235
	v_med3_i32 v33, v33, s71, v235
	v_rndne_f32_e32 v31, v31
	v_cvt_i32_f32_e32 v17, v17
	v_cvt_i32_f32_e32 v16, v16
	v_rndne_f32_e32 v15, v15
	v_mul_f32_e32 v13, v5, v13
	v_mul_f32_e32 v12, v5, v12
	v_med3_i32 v35, v35, s71, v235
	v_lshlrev_b32_e32 v36, 8, v36
	v_lshlrev_b32_e32 v33, 16, v33
	v_med3_i32 v32, v32, s71, v235
	v_cvt_i32_f32_e32 v31, v31
	v_cvt_i32_f32_e32 v15, v15
	v_mul_f32_e32 v14, v5, v14
	v_rndne_f32_e32 v13, v13
	v_rndne_f32_e32 v12, v12
	v_mul_f32_e32 v11, v5, v11
	v_and_b32_e32 v36, 0xff00, v36
	v_and_b32_e32 v33, 0xff0000, v33
	v_perm_b32 v32, v32, v35, s48
	v_rndne_f32_e32 v14, v14
	v_cvt_i32_f32_e32 v13, v13
	v_cvt_i32_f32_e32 v12, v12
	v_rndne_f32_e32 v11, v11
	v_or3_b32 v35, v32, v36, v33
	v_cvt_i32_f32_e32 v32, v14
	v_cvt_i32_f32_e32 v11, v11
	v_med3_i32 v17, v17, s71, v235
	v_med3_i32 v16, v16, s71, v235
	v_mul_f32_e32 v9, v5, v9
	v_mul_f32_e32 v8, v5, v8
	v_med3_i32 v31, v31, s71, v235
	v_lshlrev_b32_e32 v17, 8, v17
	v_lshlrev_b32_e32 v16, 16, v16
	v_med3_i32 v15, v15, s71, v235
	v_mul_f32_e32 v10, v5, v10
	v_rndne_f32_e32 v9, v9
	v_rndne_f32_e32 v8, v8
	v_mul_f32_e32 v7, v5, v7
	v_and_b32_e32 v16, 0xff0000, v16
	v_lshlrev_b32_e32 v15, 24, v15
	v_perm_b32 v14, v17, v31, s49
	v_med3_i32 v13, v13, s71, v235
	v_med3_i32 v12, v12, s71, v235
	v_rndne_f32_e32 v10, v10
	v_cvt_i32_f32_e32 v9, v9
	v_cvt_i32_f32_e32 v8, v8
	v_rndne_f32_e32 v7, v7
	v_or3_b32 v14, v14, v15, v16
	v_med3_i32 v15, v32, s71, v235
	v_lshlrev_b32_e32 v13, 8, v13
	v_lshlrev_b32_e32 v12, 16, v12
	v_med3_i32 v11, v11, s71, v235
	v_cvt_i32_f32_e32 v10, v10
	v_cvt_i32_f32_e32 v7, v7
	v_mul_f32_e32 v4, v5, v4
	v_mul_f32_e32 v3, v5, v3
	v_and_b32_e32 v13, 0xff00, v13
	v_and_b32_e32 v12, 0xff0000, v12
	v_perm_b32 v11, v11, v15, s48
	v_mul_f32_e32 v6, v5, v6
	v_rndne_f32_e32 v4, v4
	v_rndne_f32_e32 v3, v3
	v_mul_f32_e32 v2, v5, v2
	v_or3_b32 v15, v11, v13, v12
	v_rndne_f32_e32 v6, v6
	v_cvt_i32_f32_e32 v11, v4
	v_cvt_i32_f32_e32 v3, v3
	v_rndne_f32_e32 v2, v2
	v_med3_i32 v9, v9, s71, v235
	v_med3_i32 v8, v8, s71, v235
	v_cvt_i32_f32_e32 v6, v6
	v_cvt_i32_f32_e32 v2, v2
	v_med3_i32 v10, v10, s71, v235
	v_lshlrev_b32_e32 v9, 8, v9
	v_lshlrev_b32_e32 v8, 16, v8
	v_med3_i32 v7, v7, s71, v235
	v_and_b32_e32 v8, 0xff0000, v8
	v_lshlrev_b32_e32 v7, 24, v7
	v_perm_b32 v4, v9, v10, s49
	v_or3_b32 v4, v4, v7, v8
	v_med3_i32 v7, v11, s71, v235
	v_med3_i32 v3, v3, s71, v235
	v_med3_i32 v6, v6, s71, v235
	v_lshlrev_b32_e32 v7, 8, v7
	v_lshlrev_b32_e32 v3, 16, v3
	v_med3_i32 v2, v2, s71, v235
	v_and_b32_e32 v7, 0xff00, v7
	v_and_b32_e32 v3, 0xff0000, v3
	v_perm_b32 v2, v2, v6, s48
	s_add_u32 s10, s10, s12
	v_or3_b32 v5, v2, v7, v3
	s_addc_u32 s11, s11, s13
	global_store_dwordx2 v[22:23], v[44:45], off offset:-1024
	global_store_dwordx2 v[22:23], v[34:35], off offset:-512
	global_store_dwordx2 v[22:23], v[14:15], off
	global_store_dwordx2 v[22:23], v[4:5], off offset:512
	v_lshl_add_u64 v[18:19], v[18:19], 0, s[14:15]
	v_lshl_add_u64 v[20:21], v[20:21], 0, s[16:17]
	v_lshl_add_u64 v[22:23], v[22:23], 0, s[18:19]
	s_waitcnt vmcnt(12)
	v_mov_b32_e32 v14, v92
	v_mov_b32_e32 v15, v93
	v_mov_b32_e32 v16, v94
	v_mov_b32_e32 v17, v95
	v_mov_b32_e32 v10, v96
	v_mov_b32_e32 v11, v97
	v_mov_b32_e32 v12, v98
	v_mov_b32_e32 v13, v99
	v_mov_b32_e32 v6, v100
	v_mov_b32_e32 v7, v101
	v_mov_b32_e32 v8, v102
	v_mov_b32_e32 v9, v103
	v_mov_b32_e32 v2, v104
	v_mov_b32_e32 v3, v105
	v_mov_b32_e32 v4, v106
	v_mov_b32_e32 v5, v107
	v_mov_b32_e32 v49, v108
	v_lshlrev_b32_e32 v48, 16, v14
	v_and_b32_e32 v47, 0xffff0000, v14
	v_max_f32_e64 v14, |v47|, |v47|
	v_max_f32_e64 v31, |v48|, |v48|
	v_lshlrev_b32_e32 v46, 16, v15
	v_and_b32_e32 v45, 0xffff0000, v15
	v_max_f32_e32 v14, v31, v14
	v_max_f32_e64 v15, |v45|, |v45|
	v_max_f32_e64 v31, |v46|, |v46|
	v_max_f32_e32 v15, v31, v15
	v_lshlrev_b32_e32 v44, 16, v16
	v_and_b32_e32 v43, 0xffff0000, v16
	v_max3_f32 v14, v14, 0, v15
	v_max_f32_e64 v15, |v43|, |v43|
	v_max_f32_e64 v16, |v44|, |v44|
	v_lshlrev_b32_e32 v41, 16, v17
	v_and_b32_e32 v40, 0xffff0000, v17
	v_max_f32_e32 v15, v16, v15
	v_max_f32_e64 v16, |v40|, |v40|
	v_max_f32_e64 v17, |v41|, |v41|
	v_max_f32_e32 v16, v17, v16
	v_lshlrev_b32_e32 v39, 16, v10
	v_and_b32_e32 v38, 0xffff0000, v10
	v_max3_f32 v14, v14, v15, v16
	v_max_f32_e64 v10, |v38|, |v38|
	v_max_f32_e64 v15, |v39|, |v39|
	v_lshlrev_b32_e32 v37, 16, v11
	v_and_b32_e32 v36, 0xffff0000, v11
	v_max_f32_e32 v10, v15, v10
	v_max_f32_e64 v11, |v36|, |v36|
	v_max_f32_e64 v15, |v37|, |v37|
	v_max_f32_e32 v11, v15, v11
	v_lshlrev_b32_e32 v35, 16, v12
	v_and_b32_e32 v34, 0xffff0000, v12
	v_max3_f32 v10, v14, v10, v11
	v_max_f32_e64 v11, |v34|, |v34|
	v_max_f32_e64 v12, |v35|, |v35|
	v_lshlrev_b32_e32 v33, 16, v13
	v_and_b32_e32 v32, 0xffff0000, v13
	v_max_f32_e32 v11, v12, v11
	v_max_f32_e64 v12, |v32|, |v32|
	v_max_f32_e64 v13, |v33|, |v33|
	v_max_f32_e32 v12, v13, v12
	v_lshlrev_b32_e32 v31, 16, v6
	v_and_b32_e32 v17, 0xffff0000, v6
	v_max3_f32 v10, v10, v11, v12
	v_max_f32_e64 v6, |v17|, |v17|
	v_max_f32_e64 v11, |v31|, |v31|
	v_lshlrev_b32_e32 v16, 16, v7
	v_and_b32_e32 v15, 0xffff0000, v7
	v_max_f32_e32 v6, v11, v6
	v_max_f32_e64 v7, |v15|, |v15|
	v_max_f32_e64 v11, |v16|, |v16|
	v_max_f32_e32 v7, v11, v7
	v_lshlrev_b32_e32 v14, 16, v8
	v_and_b32_e32 v13, 0xffff0000, v8
	v_max3_f32 v6, v10, v6, v7
	v_max_f32_e64 v7, |v13|, |v13|
	v_max_f32_e64 v8, |v14|, |v14|
	v_lshlrev_b32_e32 v12, 16, v9
	v_and_b32_e32 v11, 0xffff0000, v9
	v_max_f32_e32 v7, v8, v7
	v_max_f32_e64 v8, |v11|, |v11|
	v_max_f32_e64 v9, |v12|, |v12|
	v_max_f32_e32 v8, v9, v8
	v_lshlrev_b32_e32 v10, 16, v2
	v_and_b32_e32 v9, 0xffff0000, v2
	v_max3_f32 v6, v6, v7, v8
	v_max_f32_e64 v2, |v9|, |v9|
	v_max_f32_e64 v7, |v10|, |v10|
	v_max_f32_e32 v2, v7, v2
	v_lshlrev_b32_e32 v8, 16, v3
	v_and_b32_e32 v7, 0xffff0000, v3
	v_max_f32_e64 v3, |v7|, |v7|
	v_max_f32_e64 v50, |v8|, |v8|
	v_max_f32_e32 v3, v50, v3
	v_max3_f32 v50, v6, v2, v3
	v_lshlrev_b32_e32 v6, 16, v4
	v_and_b32_e32 v4, 0xffff0000, v4
	v_max_f32_e64 v2, |v4|, |v4|
	v_max_f32_e64 v3, |v6|, |v6|
	v_max_f32_e32 v51, v3, v2
	v_lshlrev_b32_e32 v3, 16, v5
	v_and_b32_e32 v2, 0xffff0000, v5
	v_max_f32_e64 v5, |v2|, |v2|
	v_max_f32_e64 v52, |v3|, |v3|
	v_max_f32_e32 v5, v52, v5
	v_max3_f32 v5, v50, v51, v5
	ds_bpermute_b32 v50, v25, v5
	s_waitcnt lgkmcnt(0)
	v_max_f32_e32 v50, v50, v50
	v_max_f32_e32 v5, v5, v50
	ds_bpermute_b32 v50, v25, v49
	ds_bpermute_b32 v51, v26, v5
	s_waitcnt lgkmcnt(1)
	v_add_f32_e32 v49, v49, v50
	s_waitcnt lgkmcnt(0)
	v_max_f32_e32 v50, v51, v51
	ds_bpermute_b32 v51, v26, v49
	v_max_f32_e32 v5, v5, v50
	ds_bpermute_b32 v50, v27, v5
	s_waitcnt lgkmcnt(1)
	v_add_f32_e32 v49, v49, v51
	ds_bpermute_b32 v51, v27, v49
	s_waitcnt lgkmcnt(1)
	v_max_f32_e32 v50, v50, v50
	v_max_f32_e32 v5, v5, v50
	ds_bpermute_b32 v50, v28, v5
	s_waitcnt lgkmcnt(1)
	v_add_f32_e32 v49, v49, v51
	ds_bpermute_b32 v51, v28, v49
	s_waitcnt lgkmcnt(1)
	v_max_f32_e32 v50, v50, v50
	v_max_f32_e32 v5, v5, v50
	ds_bpermute_b32 v50, v29, v5
	s_waitcnt lgkmcnt(1)
	v_add_f32_e32 v49, v49, v51
	ds_bpermute_b32 v51, v29, v49
	s_waitcnt lgkmcnt(1)
	v_max_f32_e32 v50, v50, v50
	v_max_f32_e32 v5, v5, v50
	s_waitcnt lgkmcnt(0)
	v_add_f32_e32 v49, v49, v51
	ds_bpermute_b32 v51, v30, v5
	ds_bpermute_b32 v50, v30, v49
	s_waitcnt lgkmcnt(1)
	v_max3_f32 v5, v5, v51, s73
	s_and_saveexec_b64 s[20:21], s[38:39]
	s_cbranch_execz .Lxqa_C3
	s_waitcnt lgkmcnt(0)
	v_add_f32_e32 v49, v49, v50
	v_fmamk_f32 v49, v49, 0x3a000000, v1
	v_mul_f32_e32 v50, 0x4f800000, v49
	v_cmp_gt_f32_e32 vcc, s70, v49
	s_nop 1
	v_cndmask_b32_e32 v49, v49, v50, vcc
	v_sqrt_f32_e32 v50, v49
	s_nop 0
	v_add_u32_e32 v51, -1, v50
	v_fma_f32 v53, -v51, v50, v49
	v_add_u32_e32 v52, 1, v50
	v_cmp_ge_f32_e64 s[40:41], 0, v53
	s_nop 1
	v_cndmask_b32_e64 v51, v50, v51, s[40:41]
	v_fma_f32 v50, -v52, v50, v49
	v_cmp_lt_f32_e64 s[40:41], 0, v50
	s_nop 1
	v_cndmask_b32_e64 v50, v51, v52, s[40:41]
	v_mul_f32_e32 v51, 0x37800000, v50
	v_cndmask_b32_e32 v50, v50, v51, vcc
	v_cmp_class_f32_e32 vcc, v49, v226
	s_nop 1
	v_cndmask_b32_e32 v49, v50, v49, vcc
	v_div_scale_f32 v50, s[26:27], v49, v49, 1.0
	v_rcp_f32_e32 v51, v50
	s_nop 0
	v_fma_f32 v52, -v50, v51, 1.0
	v_fmac_f32_e32 v51, v52, v51
	v_div_scale_f32 v52, vcc, 1.0, v49, 1.0
	v_mul_f32_e32 v53, v52, v51
	v_fma_f32 v54, -v50, v53, v52
	v_fmac_f32_e32 v53, v54, v51
	v_fma_f32 v50, -v50, v53, v52
	v_div_fmas_f32 v50, v50, v51, v53
	v_div_fixup_f32 v49, v50, v49, 1.0
	v_mul_f32_e32 v50, 0x3c010204, v5
	v_mul_f32_e32 v49, v50, v49
	global_store_dword v115, v49, s[10:11]
.Lxqa_C3:
	s_or_b64 exec, exec, s[20:21]
	v_div_scale_f32 v49, s[20:21], v5, v5, s47
	s_waitcnt lgkmcnt(0)
	v_rcp_f32_e32 v50, v49
	v_div_scale_f32 v51, vcc, s47, v5, s47
	s_add_i32 s1, s1, -1
	v_fma_f32 v52, -v49, v50, 1.0
	v_fmac_f32_e32 v50, v52, v50
	v_mul_f32_e32 v52, v51, v50
	v_fma_f32 v53, -v49, v52, v51
	v_fmac_f32_e32 v52, v53, v50
	v_fma_f32 v49, -v49, v52, v51
	v_div_fmas_f32 v49, v49, v50, v52
	v_div_fixup_f32 v5, v49, v5, s47
	v_mul_f32_e32 v47, v5, v47
	v_mul_f32_e32 v46, v5, v46
	v_mul_f32_e32 v48, v5, v48
	v_rndne_f32_e32 v47, v47
	v_rndne_f32_e32 v46, v46
	v_mul_f32_e32 v45, v5, v45
	v_rndne_f32_e32 v48, v48
	v_cvt_i32_f32_e32 v47, v47
	v_cvt_i32_f32_e32 v46, v46
	v_rndne_f32_e32 v45, v45
	v_mul_f32_e32 v43, v5, v43
	v_mul_f32_e32 v41, v5, v41
	v_cvt_i32_f32_e32 v48, v48
	v_cvt_i32_f32_e32 v45, v45
	v_mul_f32_e32 v44, v5, v44
	v_rndne_f32_e32 v43, v43
	v_rndne_f32_e32 v41, v41
	v_mul_f32_e32 v40, v5, v40
	v_rndne_f32_e32 v44, v44
	v_cvt_i32_f32_e32 v43, v43
	v_cvt_i32_f32_e32 v41, v41
	v_rndne_f32_e32 v40, v40
	v_cvt_i32_f32_e32 v49, v44
	v_cvt_i32_f32_e32 v40, v40
	v_med3_i32 v47, v47, s71, v235
	v_med3_i32 v46, v46, s71, v235
	v_mul_f32_e32 v38, v5, v38
	v_mul_f32_e32 v37, v5, v37
	v_med3_i32 v48, v48, s71, v235
	v_lshlrev_b32_e32 v47, 8, v47
	v_lshlrev_b32_e32 v46, 16, v46
	v_med3_i32 v45, v45, s71, v235
	v_mul_f32_e32 v39, v5, v39
	v_rndne_f32_e32 v38, v38
	v_rndne_f32_e32 v37, v37
	v_mul_f32_e32 v36, v5, v36
	v_and_b32_e32 v46, 0xff0000, v46
	v_lshlrev_b32_e32 v45, 24, v45
	v_perm_b32 v44, v47, v48, s49
	v_med3_i32 v43, v43, s71, v235
	v_med3_i32 v41, v41, s71, v235
	v_rndne_f32_e32 v39, v39
	v_cvt_i32_f32_e32 v38, v38
	v_cvt_i32_f32_e32 v37, v37
	v_rndne_f32_e32 v36, v36
	v_or3_b32 v44, v44, v45, v46
	v_med3_i32 v45, v49, s71, v235
	v_lshlrev_b32_e32 v43, 8, v43
	v_lshlrev_b32_e32 v41, 16, v41
	v_med3_i32 v40, v40, s71, v235
	v_cvt_i32_f32_e32 v39, v39
	v_cvt_i32_f32_e32 v36, v36
	v_mul_f32_e32 v34, v5, v34
	v_mul_f32_e32 v33, v5, v33
	v_and_b32_e32 v43, 0xff00, v43
	v_and_b32_e32 v41, 0xff0000, v41
	v_perm_b32 v40, v40, v45, s48
	v_mul_f32_e32 v35, v5, v35
	v_rndne_f32_e32 v34, v34
	v_rndne_f32_e32 v33, v33
	v_mul_f32_e32 v32, v5, v32
	v_or3_b32 v45, v40, v43, v41
	v_rndne_f32_e32 v35, v35
	v_cvt_i32_f32_e32 v40, v34
	v_cvt_i32_f32_e32 v33, v33
	v_rndne_f32_e32 v32, v32
	v_med3_i32 v38, v38, s71, v235
	v_med3_i32 v37, v37, s71, v235
	v_cvt_i32_f32_e32 v35, v35
	v_cvt_i32_f32_e32 v32, v32
	v_med3_i32 v39, v39, s71, v235
	v_lshlrev_b32_e32 v38, 8, v38
	v_lshlrev_b32_e32 v37, 16, v37
	v_med3_i32 v36, v36, s71, v235
	v_mul_f32_e32 v17, v5, v17
	v_mul_f32_e32 v16, v5, v16
	v_and_b32_e32 v37, 0xff0000, v37
	v_lshlrev_b32_e32 v36, 24, v36
	v_perm_b32 v34, v38, v39, s49
	v_mul_f32_e32 v31, v5, v31
	v_rndne_f32_e32 v17, v17
	v_rndne_f32_e32 v16, v16
	v_mul_f32_e32 v15, v5, v15
	v_or3_b32 v34, v34, v36, v37
	v_med3_i32 v36, v40, s71, v235
	v_med3_i32 v33, v33, s71, v235
	v_rndne_f32_e32 v31, v31
	v_cvt_i32_f32_e32 v17, v17
	v_cvt_i32_f32_e32 v16, v16
	v_rndne_f32_e32 v15, v15
	v_mul_f32_e32 v13, v5, v13
	v_mul_f32_e32 v12, v5, v12
	v_med3_i32 v35, v35, s71, v235
	v_lshlrev_b32_e32 v36, 8, v36
	v_lshlrev_b32_e32 v33, 16, v33
	v_med3_i32 v32, v32, s71, v235
	v_cvt_i32_f32_e32 v31, v31
	v_cvt_i32_f32_e32 v15, v15
	v_mul_f32_e32 v14, v5, v14
	v_rndne_f32_e32 v13, v13
	v_rndne_f32_e32 v12, v12
	v_mul_f32_e32 v11, v5, v11
	v_and_b32_e32 v36, 0xff00, v36
	v_and_b32_e32 v33, 0xff0000, v33
	v_perm_b32 v32, v32, v35, s48
	v_rndne_f32_e32 v14, v14
	v_cvt_i32_f32_e32 v13, v13
	v_cvt_i32_f32_e32 v12, v12
	v_rndne_f32_e32 v11, v11
	v_or3_b32 v35, v32, v36, v33
	v_cvt_i32_f32_e32 v32, v14
	v_cvt_i32_f32_e32 v11, v11
	v_med3_i32 v17, v17, s71, v235
	v_med3_i32 v16, v16, s71, v235
	v_mul_f32_e32 v9, v5, v9
	v_mul_f32_e32 v8, v5, v8
	v_med3_i32 v31, v31, s71, v235
	v_lshlrev_b32_e32 v17, 8, v17
	v_lshlrev_b32_e32 v16, 16, v16
	v_med3_i32 v15, v15, s71, v235
	v_mul_f32_e32 v10, v5, v10
	v_rndne_f32_e32 v9, v9
	v_rndne_f32_e32 v8, v8
	v_mul_f32_e32 v7, v5, v7
	v_and_b32_e32 v16, 0xff0000, v16
	v_lshlrev_b32_e32 v15, 24, v15
	v_perm_b32 v14, v17, v31, s49
	v_med3_i32 v13, v13, s71, v235
	v_med3_i32 v12, v12, s71, v235
	v_rndne_f32_e32 v10, v10
	v_cvt_i32_f32_e32 v9, v9
	v_cvt_i32_f32_e32 v8, v8
	v_rndne_f32_e32 v7, v7
	v_or3_b32 v14, v14, v15, v16
	v_med3_i32 v15, v32, s71, v235
	v_lshlrev_b32_e32 v13, 8, v13
	v_lshlrev_b32_e32 v12, 16, v12
	v_med3_i32 v11, v11, s71, v235
	v_cvt_i32_f32_e32 v10, v10
	v_cvt_i32_f32_e32 v7, v7
	v_mul_f32_e32 v4, v5, v4
	v_mul_f32_e32 v3, v5, v3
	v_and_b32_e32 v13, 0xff00, v13
	v_and_b32_e32 v12, 0xff0000, v12
	v_perm_b32 v11, v11, v15, s48
	v_mul_f32_e32 v6, v5, v6
	v_rndne_f32_e32 v4, v4
	v_rndne_f32_e32 v3, v3
	v_mul_f32_e32 v2, v5, v2
	v_or3_b32 v15, v11, v13, v12
	v_rndne_f32_e32 v6, v6
	v_cvt_i32_f32_e32 v11, v4
	v_cvt_i32_f32_e32 v3, v3
	v_rndne_f32_e32 v2, v2
	v_med3_i32 v9, v9, s71, v235
	v_med3_i32 v8, v8, s71, v235
	v_cvt_i32_f32_e32 v6, v6
	v_cvt_i32_f32_e32 v2, v2
	v_med3_i32 v10, v10, s71, v235
	v_lshlrev_b32_e32 v9, 8, v9
	v_lshlrev_b32_e32 v8, 16, v8
	v_med3_i32 v7, v7, s71, v235
	v_and_b32_e32 v8, 0xff0000, v8
	v_lshlrev_b32_e32 v7, 24, v7
	v_perm_b32 v4, v9, v10, s49
	v_or3_b32 v4, v4, v7, v8
	v_med3_i32 v7, v11, s71, v235
	v_med3_i32 v3, v3, s71, v235
	v_med3_i32 v6, v6, s71, v235
	v_lshlrev_b32_e32 v7, 8, v7
	v_lshlrev_b32_e32 v3, 16, v3
	v_med3_i32 v2, v2, s71, v235
	v_and_b32_e32 v7, 0xff00, v7
	v_and_b32_e32 v3, 0xff0000, v3
	v_perm_b32 v2, v2, v6, s48
	s_add_u32 s10, s10, s12
	v_or3_b32 v5, v2, v7, v3
	s_addc_u32 s11, s11, s13
	global_store_dwordx2 v[22:23], v[44:45], off offset:-1024
	global_store_dwordx2 v[22:23], v[34:35], off offset:-512
	global_store_dwordx2 v[22:23], v[14:15], off
	global_store_dwordx2 v[22:23], v[4:5], off offset:512
	v_lshl_add_u64 v[18:19], v[18:19], 0, s[14:15]
	v_lshl_add_u64 v[20:21], v[20:21], 0, s[16:17]
	v_lshl_add_u64 v[22:23], v[22:23], 0, s[18:19]
	s_cmp_lt_i32 s1, 4
	s_cbranch_scc0 .Lxqa_top
	s_cmp_eq_u32 s1, 0
	s_cbranch_scc1 .LBB0_1031
	s_branch .LBB0_1025

.Lxqb_entry:
	s_cmp_lt_i32 s22, 4
	s_cbranch_scc1 .LBB0_1038

.Lxqb_l0:
	s_or_b64 exec, exec, s[6:7]
	v_lshl_add_u64 v[110:111], v[20:21], 0, s[14:15]
	v_lshl_add_u64 v[112:113], v[18:19], 0, s[12:13]
	global_load_dwordx4 v[56:59], v[110:111], off offset:-2048
	global_load_dwordx4 v[60:63], v[110:111], off offset:-1024
	global_load_dwordx4 v[64:67], v[110:111], off
	global_load_dwordx4 v[68:71], v[110:111], off offset:1024
	v_mov_b32_e32 v72, 0
	s_and_saveexec_b64 s[6:7], s[36:37]
	s_cbranch_execz .Lxqb_l1
	global_load_dword v72, v[112:113], off
.Lxqb_l1:
	s_or_b64 exec, exec, s[6:7]
	v_lshl_add_u64 v[110:111], v[110:111], 0, s[14:15]
	v_lshl_add_u64 v[112:113], v[112:113], 0, s[12:13]
	global_load_dwordx4 v[74:77], v[110:111], off offset:-2048
	global_load_dwordx4 v[78:81], v[110:111], off offset:-1024
	global_load_dwordx4 v[82:85], v[110:111], off
	global_load_dwordx4 v[86:89], v[110:111], off offset:1024
	v_mov_b32_e32 v90, 0
	s_and_saveexec_b64 s[6:7], s[36:37]
	s_cbranch_execz .Lxqb_l2
	global_load_dword v90, v[112:113], off
.Lxqb_l2:
	s_or_b64 exec, exec, s[6:7]
	v_lshl_add_u64 v[110:111], v[110:111], 0, s[14:15]
	v_lshl_add_u64 v[112:113], v[112:113], 0, s[12:13]
	global_load_dwordx4 v[92:95], v[110:111], off offset:-2048
	global_load_dwordx4 v[96:99], v[110:111], off offset:-1024
	global_load_dwordx4 v[100:103], v[110:111], off
	global_load_dwordx4 v[104:107], v[110:111], off offset:1024
	v_mov_b32_e32 v108, 0
	s_and_saveexec_b64 s[6:7], s[36:37]
	s_cbranch_execz .Lxqb_l3
	global_load_dword v108, v[112:113], off
.Lxqb_l3:
	s_or_b64 exec, exec, s[6:7]
	s_waitcnt vmcnt(12)
	v_lshlrev_b32_e32 v46, 16, v14
	v_and_b32_e32 v45, 0xffff0000, v14
	v_max_f32_e64 v14, |v45|, |v45|
	v_max_f32_e64 v30, |v46|, |v46|
	v_lshlrev_b32_e32 v44, 16, v15
	v_and_b32_e32 v43, 0xffff0000, v15
	v_max_f32_e32 v14, v30, v14
	v_max_f32_e64 v15, |v43|, |v43|
	v_max_f32_e64 v30, |v44|, |v44|
	v_max_f32_e32 v15, v30, v15
	v_lshlrev_b32_e32 v42, 16, v16
	v_and_b32_e32 v41, 0xffff0000, v16
	v_max3_f32 v14, v14, 0, v15
	v_max_f32_e64 v15, |v41|, |v41|
	v_max_f32_e64 v16, |v42|, |v42|
	v_lshlrev_b32_e32 v40, 16, v17
	v_and_b32_e32 v39, 0xffff0000, v17
	v_max_f32_e32 v15, v16, v15
	v_max_f32_e64 v16, |v39|, |v39|
	v_max_f32_e64 v17, |v40|, |v40|
	v_max_f32_e32 v16, v17, v16
	v_lshlrev_b32_e32 v38, 16, v10
	v_and_b32_e32 v37, 0xffff0000, v10
	v_max3_f32 v14, v14, v15, v16
	v_max_f32_e64 v10, |v37|, |v37|
	v_max_f32_e64 v15, |v38|, |v38|
	v_lshlrev_b32_e32 v36, 16, v11
	v_and_b32_e32 v35, 0xffff0000, v11
	v_max_f32_e32 v10, v15, v10
	v_max_f32_e64 v11, |v35|, |v35|
	v_max_f32_e64 v15, |v36|, |v36|
	v_max_f32_e32 v11, v15, v11
	v_lshlrev_b32_e32 v34, 16, v12
	v_and_b32_e32 v33, 0xffff0000, v12
	v_max3_f32 v10, v14, v10, v11
	v_max_f32_e64 v11, |v33|, |v33|
	v_max_f32_e64 v12, |v34|, |v34|
	v_lshlrev_b32_e32 v32, 16, v13
	v_and_b32_e32 v31, 0xffff0000, v13
	v_max_f32_e32 v11, v12, v11
	v_max_f32_e64 v12, |v31|, |v31|
	v_max_f32_e64 v13, |v32|, |v32|
	v_max_f32_e32 v12, v13, v12
	v_lshlrev_b32_e32 v30, 16, v6
	v_and_b32_e32 v17, 0xffff0000, v6
	v_max3_f32 v10, v10, v11, v12
	v_max_f32_e64 v6, |v17|, |v17|
	v_max_f32_e64 v11, |v30|, |v30|
	v_lshlrev_b32_e32 v16, 16, v7
	v_and_b32_e32 v15, 0xffff0000, v7
	v_max_f32_e32 v6, v11, v6
	v_max_f32_e64 v7, |v15|, |v15|
	v_max_f32_e64 v11, |v16|, |v16|
	v_max_f32_e32 v7, v11, v7
	v_lshlrev_b32_e32 v14, 16, v8
	v_and_b32_e32 v13, 0xffff0000, v8
	v_max3_f32 v6, v10, v6, v7
	v_max_f32_e64 v7, |v13|, |v13|
	v_max_f32_e64 v8, |v14|, |v14|
	v_lshlrev_b32_e32 v12, 16, v9
	v_and_b32_e32 v11, 0xffff0000, v9
	v_max_f32_e32 v7, v8, v7
	v_max_f32_e64 v8, |v11|, |v11|
	v_max_f32_e64 v9, |v12|, |v12|
	v_max_f32_e32 v8, v9, v8
	v_lshlrev_b32_e32 v10, 16, v2
	v_and_b32_e32 v9, 0xffff0000, v2
	v_max3_f32 v6, v6, v7, v8
	v_max_f32_e64 v2, |v9|, |v9|
	v_max_f32_e64 v7, |v10|, |v10|
	v_max_f32_e32 v2, v7, v2
	v_lshlrev_b32_e32 v8, 16, v3
	v_and_b32_e32 v7, 0xffff0000, v3
	v_max_f32_e64 v3, |v7|, |v7|
	v_max_f32_e64 v48, |v8|, |v8|
	v_max_f32_e32 v3, v48, v3
	v_max3_f32 v48, v6, v2, v3
	v_lshlrev_b32_e32 v6, 16, v4
	v_and_b32_e32 v4, 0xffff0000, v4
	v_max_f32_e64 v2, |v4|, |v4|
	v_max_f32_e64 v3, |v6|, |v6|
	v_max_f32_e32 v49, v3, v2
	v_lshlrev_b32_e32 v3, 16, v5
	v_and_b32_e32 v2, 0xffff0000, v5
	v_max_f32_e64 v5, |v2|, |v2|
	v_max_f32_e64 v50, |v3|, |v3|
	v_max_f32_e32 v5, v50, v5
	v_max3_f32 v5, v48, v49, v5
	ds_bpermute_b32 v48, v24, v5
	s_waitcnt lgkmcnt(0)
	v_max_f32_e32 v48, v48, v48
	v_max_f32_e32 v5, v5, v48
	ds_bpermute_b32 v48, v24, v47
	ds_bpermute_b32 v49, v25, v5
	s_waitcnt lgkmcnt(1)
	v_add_f32_e32 v47, v47, v48
	s_waitcnt lgkmcnt(0)
	v_max_f32_e32 v48, v49, v49
	ds_bpermute_b32 v49, v25, v47
	v_max_f32_e32 v5, v5, v48
	ds_bpermute_b32 v48, v26, v5
	s_waitcnt lgkmcnt(1)
	v_add_f32_e32 v47, v47, v49
	ds_bpermute_b32 v49, v26, v47
	s_waitcnt lgkmcnt(1)
	v_max_f32_e32 v48, v48, v48
	v_max_f32_e32 v5, v5, v48
	ds_bpermute_b32 v48, v27, v5
	s_waitcnt lgkmcnt(1)
	v_add_f32_e32 v47, v47, v49
	ds_bpermute_b32 v49, v27, v47
	s_waitcnt lgkmcnt(1)
	v_max_f32_e32 v48, v48, v48
	v_max_f32_e32 v5, v5, v48
	ds_bpermute_b32 v48, v28, v5
	s_waitcnt lgkmcnt(1)
	v_add_f32_e32 v47, v47, v49
	ds_bpermute_b32 v49, v28, v47
	s_waitcnt lgkmcnt(1)
	v_max_f32_e32 v48, v48, v48
	v_max_f32_e32 v5, v5, v48
	s_waitcnt lgkmcnt(0)
	v_add_f32_e32 v47, v47, v49
	ds_bpermute_b32 v49, v29, v5
	ds_bpermute_b32 v48, v29, v47
	s_waitcnt lgkmcnt(1)
	v_max3_f32 v5, v5, v49, s73
	s_and_saveexec_b64 s[6:7], s[38:39]
	s_cbranch_execz .Lxqb_C0
	s_waitcnt lgkmcnt(0)
	v_add_f32_e32 v47, v47, v48
	v_fmamk_f32 v47, v47, 0x3a000000, v1
	v_mul_f32_e32 v48, 0x4f800000, v47
	v_cmp_gt_f32_e32 vcc, s70, v47
	s_nop 1
	v_cndmask_b32_e32 v47, v47, v48, vcc
	v_sqrt_f32_e32 v48, v47
	s_nop 0
	v_add_u32_e32 v49, -1, v48
	v_fma_f32 v51, -v49, v48, v47
	v_add_u32_e32 v50, 1, v48
	v_cmp_ge_f32_e64 s[40:41], 0, v51
	s_nop 1
	v_cndmask_b32_e64 v49, v48, v49, s[40:41]
	v_fma_f32 v48, -v50, v48, v47
	v_cmp_lt_f32_e64 s[40:41], 0, v48
	s_nop 1
	v_cndmask_b32_e64 v48, v49, v50, s[40:41]
	v_mul_f32_e32 v49, 0x37800000, v48
	v_cndmask_b32_e32 v48, v48, v49, vcc
	v_cmp_class_f32_e32 vcc, v47, v226
	s_nop 1
	v_cndmask_b32_e32 v47, v48, v47, vcc
	v_div_scale_f32 v48, s[16:17], v47, v47, 1.0
	v_rcp_f32_e32 v49, v48
	s_nop 0
	v_fma_f32 v50, -v48, v49, 1.0
	v_fmac_f32_e32 v49, v50, v49
	v_div_scale_f32 v50, vcc, 1.0, v47, 1.0
	v_mul_f32_e32 v51, v50, v49
	v_fma_f32 v52, -v48, v51, v50
	v_fmac_f32_e32 v51, v52, v49
	v_fma_f32 v48, -v48, v51, v50
	v_div_fmas_f32 v48, v48, v49, v51
	v_div_fixup_f32 v47, v48, v47, 1.0
	v_mul_f32_e32 v48, 0x3c010204, v5
	v_mul_f32_e32 v47, v48, v47
	global_store_dword v115, v47, s[8:9]
.Lxqb_C0:
	s_or_b64 exec, exec, s[6:7]
	v_div_scale_f32 v47, s[6:7], v5, v5, s47
	s_waitcnt lgkmcnt(0)
	v_rcp_f32_e32 v48, v47
	v_div_scale_f32 v49, vcc, s47, v5, s47
	s_add_i32 s22, s22, -1
	v_fma_f32 v50, -v47, v48, 1.0
	v_fmac_f32_e32 v48, v50, v48
	v_mul_f32_e32 v50, v49, v48
	v_fma_f32 v51, -v47, v50, v49
	v_fmac_f32_e32 v50, v51, v48
	v_fma_f32 v47, -v47, v50, v49
	v_div_fmas_f32 v47, v47, v48, v50
	v_div_fixup_f32 v5, v47, v5, s47
	v_mul_f32_e32 v45, v5, v45
	v_mul_f32_e32 v44, v5, v44
	v_mul_f32_e32 v46, v5, v46
	v_rndne_f32_e32 v45, v45
	v_rndne_f32_e32 v44, v44
	v_mul_f32_e32 v43, v5, v43
	v_rndne_f32_e32 v46, v46
	v_cvt_i32_f32_e32 v45, v45
	v_cvt_i32_f32_e32 v44, v44
	v_rndne_f32_e32 v43, v43
	v_mul_f32_e32 v41, v5, v41
	v_mul_f32_e32 v40, v5, v40
	v_cvt_i32_f32_e32 v46, v46
	v_cvt_i32_f32_e32 v43, v43
	v_mul_f32_e32 v42, v5, v42
	v_rndne_f32_e32 v41, v41
	v_rndne_f32_e32 v40, v40
	v_mul_f32_e32 v39, v5, v39
	v_rndne_f32_e32 v42, v42
	v_cvt_i32_f32_e32 v41, v41
	v_cvt_i32_f32_e32 v40, v40
	v_rndne_f32_e32 v39, v39
	v_cvt_i32_f32_e32 v47, v42
	v_cvt_i32_f32_e32 v39, v39
	v_med3_i32 v45, v45, s71, v235
	v_med3_i32 v44, v44, s71, v235
	v_mul_f32_e32 v37, v5, v37
	v_mul_f32_e32 v36, v5, v36
	v_med3_i32 v46, v46, s71, v235
	v_lshlrev_b32_e32 v45, 8, v45
	v_lshlrev_b32_e32 v44, 16, v44
	v_med3_i32 v43, v43, s71, v235
	v_mul_f32_e32 v38, v5, v38
	v_rndne_f32_e32 v37, v37
	v_rndne_f32_e32 v36, v36
	v_mul_f32_e32 v35, v5, v35
	v_and_b32_e32 v44, 0xff0000, v44
	v_lshlrev_b32_e32 v43, 24, v43
	v_perm_b32 v42, v45, v46, s49
	v_med3_i32 v41, v41, s71, v235
	v_med3_i32 v40, v40, s71, v235
	v_rndne_f32_e32 v38, v38
	v_cvt_i32_f32_e32 v37, v37
	v_cvt_i32_f32_e32 v36, v36
	v_rndne_f32_e32 v35, v35
	v_mul_f32_e32 v33, v5, v33
	v_mul_f32_e32 v32, v5, v32
	v_or3_b32 v42, v42, v43, v44
	v_med3_i32 v43, v47, s71, v235
	v_lshlrev_b32_e32 v41, 8, v41
	v_lshlrev_b32_e32 v40, 16, v40
	v_med3_i32 v39, v39, s71, v235
	v_cvt_i32_f32_e32 v38, v38
	v_cvt_i32_f32_e32 v35, v35
	v_mul_f32_e32 v34, v5, v34
	v_rndne_f32_e32 v33, v33
	v_rndne_f32_e32 v32, v32
	v_mul_f32_e32 v31, v5, v31
	v_and_b32_e32 v41, 0xff00, v41
	v_and_b32_e32 v40, 0xff0000, v40
	v_perm_b32 v39, v39, v43, s48
	v_rndne_f32_e32 v34, v34
	v_cvt_i32_f32_e32 v33, v33
	v_cvt_i32_f32_e32 v32, v32
	v_rndne_f32_e32 v31, v31
	v_or3_b32 v43, v39, v41, v40
	v_cvt_i32_f32_e32 v39, v34
	v_cvt_i32_f32_e32 v31, v31
	v_med3_i32 v37, v37, s71, v235
	v_med3_i32 v36, v36, s71, v235
	v_mul_f32_e32 v17, v5, v17
	v_mul_f32_e32 v16, v5, v16
	v_med3_i32 v38, v38, s71, v235
	v_lshlrev_b32_e32 v37, 8, v37
	v_lshlrev_b32_e32 v36, 16, v36
	v_med3_i32 v35, v35, s71, v235
	v_mul_f32_e32 v30, v5, v30
	v_rndne_f32_e32 v17, v17
	v_rndne_f32_e32 v16, v16
	v_mul_f32_e32 v15, v5, v15
	v_and_b32_e32 v36, 0xff0000, v36
	v_lshlrev_b32_e32 v35, 24, v35
	v_perm_b32 v34, v37, v38, s49
	v_med3_i32 v33, v33, s71, v235
	v_med3_i32 v32, v32, s71, v235
	v_rndne_f32_e32 v30, v30
	v_cvt_i32_f32_e32 v17, v17
	v_cvt_i32_f32_e32 v16, v16
	v_rndne_f32_e32 v15, v15
	v_mul_f32_e32 v13, v5, v13
	v_mul_f32_e32 v12, v5, v12
	v_or3_b32 v34, v34, v35, v36
	v_med3_i32 v35, v39, s71, v235
	v_lshlrev_b32_e32 v33, 8, v33
	v_lshlrev_b32_e32 v32, 16, v32
	v_med3_i32 v31, v31, s71, v235
	v_cvt_i32_f32_e32 v30, v30
	v_cvt_i32_f32_e32 v15, v15
	v_mul_f32_e32 v14, v5, v14
	v_rndne_f32_e32 v13, v13
	v_rndne_f32_e32 v12, v12
	v_mul_f32_e32 v11, v5, v11
	v_and_b32_e32 v33, 0xff00, v33
	v_and_b32_e32 v32, 0xff0000, v32
	v_perm_b32 v31, v31, v35, s48
	v_rndne_f32_e32 v14, v14
	v_cvt_i32_f32_e32 v13, v13
	v_cvt_i32_f32_e32 v12, v12
	v_rndne_f32_e32 v11, v11
	v_or3_b32 v35, v31, v33, v32
	v_cvt_i32_f32_e32 v31, v14
	v_cvt_i32_f32_e32 v11, v11
	v_med3_i32 v17, v17, s71, v235
	v_med3_i32 v16, v16, s71, v235
	v_mul_f32_e32 v9, v5, v9
	v_mul_f32_e32 v8, v5, v8
	v_med3_i32 v30, v30, s71, v235
	v_lshlrev_b32_e32 v17, 8, v17
	v_lshlrev_b32_e32 v16, 16, v16
	v_med3_i32 v15, v15, s71, v235
	v_mul_f32_e32 v10, v5, v10
	v_rndne_f32_e32 v9, v9
	v_rndne_f32_e32 v8, v8
	v_mul_f32_e32 v7, v5, v7
	v_and_b32_e32 v16, 0xff0000, v16
	v_lshlrev_b32_e32 v15, 24, v15
	v_perm_b32 v14, v17, v30, s49
	v_med3_i32 v13, v13, s71, v235
	v_med3_i32 v12, v12, s71, v235
	v_rndne_f32_e32 v10, v10
	v_cvt_i32_f32_e32 v9, v9
	v_cvt_i32_f32_e32 v8, v8
	v_rndne_f32_e32 v7, v7
	v_or3_b32 v14, v14, v15, v16
	v_med3_i32 v15, v31, s71, v235
	v_lshlrev_b32_e32 v13, 8, v13
	v_lshlrev_b32_e32 v12, 16, v12
	v_med3_i32 v11, v11, s71, v235
	v_cvt_i32_f32_e32 v10, v10
	v_cvt_i32_f32_e32 v7, v7
	v_mul_f32_e32 v4, v5, v4
	v_mul_f32_e32 v3, v5, v3
	v_and_b32_e32 v13, 0xff00, v13
	v_and_b32_e32 v12, 0xff0000, v12
	v_perm_b32 v11, v11, v15, s48
	v_mul_f32_e32 v6, v5, v6
	v_rndne_f32_e32 v4, v4
	v_rndne_f32_e32 v3, v3
	v_mul_f32_e32 v2, v5, v2
	v_or3_b32 v15, v11, v13, v12
	v_rndne_f32_e32 v6, v6
	v_cvt_i32_f32_e32 v11, v4
	v_cvt_i32_f32_e32 v3, v3
	v_rndne_f32_e32 v2, v2
	v_med3_i32 v9, v9, s71, v235
	v_med3_i32 v8, v8, s71, v235
	v_cvt_i32_f32_e32 v6, v6
	v_cvt_i32_f32_e32 v2, v2
	v_med3_i32 v10, v10, s71, v235
	v_lshlrev_b32_e32 v9, 8, v9
	v_lshlrev_b32_e32 v8, 16, v8
	v_med3_i32 v7, v7, s71, v235
	v_and_b32_e32 v8, 0xff0000, v8
	v_lshlrev_b32_e32 v7, 24, v7
	v_perm_b32 v4, v9, v10, s49
	v_or3_b32 v4, v4, v7, v8
	v_med3_i32 v7, v11, s71, v235
	v_med3_i32 v3, v3, s71, v235
	v_med3_i32 v6, v6, s71, v235
	v_lshlrev_b32_e32 v7, 8, v7
	v_lshlrev_b32_e32 v3, 16, v3
	v_med3_i32 v2, v2, s71, v235
	v_and_b32_e32 v7, 0xff00, v7
	v_and_b32_e32 v3, 0xff0000, v3
	v_perm_b32 v2, v2, v6, s48
	s_add_u32 s8, s8, s10
	v_or3_b32 v5, v2, v7, v3
	s_addc_u32 s9, s9, s11
	global_store_dwordx2 v[22:23], v[42:43], off offset:-1024
	global_store_dwordx2 v[22:23], v[34:35], off offset:-512
	global_store_dwordx2 v[22:23], v[14:15], off
	global_store_dwordx2 v[22:23], v[4:5], off offset:512
	v_lshl_add_u64 v[18:19], v[18:19], 0, s[12:13]
	v_lshl_add_u64 v[20:21], v[20:21], 0, s[14:15]
	v_lshl_add_u64 v[22:23], v[22:23], 0, s[0:1]
	s_waitcnt vmcnt(12)
	v_mov_b32_e32 v14, v56
	v_mov_b32_e32 v15, v57
	v_mov_b32_e32 v16, v58
	v_mov_b32_e32 v17, v59
	v_mov_b32_e32 v10, v60
	v_mov_b32_e32 v11, v61
	v_mov_b32_e32 v12, v62
	v_mov_b32_e32 v13, v63
	v_mov_b32_e32 v6, v64
	v_mov_b32_e32 v7, v65
	v_mov_b32_e32 v8, v66
	v_mov_b32_e32 v9, v67
	v_mov_b32_e32 v2, v68
	v_mov_b32_e32 v3, v69
	v_mov_b32_e32 v4, v70
	v_mov_b32_e32 v5, v71
	v_mov_b32_e32 v47, v72
	v_lshlrev_b32_e32 v46, 16, v14
	v_and_b32_e32 v45, 0xffff0000, v14
	v_max_f32_e64 v14, |v45|, |v45|
	v_max_f32_e64 v30, |v46|, |v46|
	v_lshlrev_b32_e32 v44, 16, v15
	v_and_b32_e32 v43, 0xffff0000, v15
	v_max_f32_e32 v14, v30, v14
	v_max_f32_e64 v15, |v43|, |v43|
	v_max_f32_e64 v30, |v44|, |v44|
	v_max_f32_e32 v15, v30, v15
	v_lshlrev_b32_e32 v42, 16, v16
	v_and_b32_e32 v41, 0xffff0000, v16
	v_max3_f32 v14, v14, 0, v15
	v_max_f32_e64 v15, |v41|, |v41|
	v_max_f32_e64 v16, |v42|, |v42|
	v_lshlrev_b32_e32 v40, 16, v17
	v_and_b32_e32 v39, 0xffff0000, v17
	v_max_f32_e32 v15, v16, v15
	v_max_f32_e64 v16, |v39|, |v39|
	v_max_f32_e64 v17, |v40|, |v40|
	v_max_f32_e32 v16, v17, v16
	v_lshlrev_b32_e32 v38, 16, v10
	v_and_b32_e32 v37, 0xffff0000, v10
	v_max3_f32 v14, v14, v15, v16
	v_max_f32_e64 v10, |v37|, |v37|
	v_max_f32_e64 v15, |v38|, |v38|
	v_lshlrev_b32_e32 v36, 16, v11
	v_and_b32_e32 v35, 0xffff0000, v11
	v_max_f32_e32 v10, v15, v10
	v_max_f32_e64 v11, |v35|, |v35|
	v_max_f32_e64 v15, |v36|, |v36|
	v_max_f32_e32 v11, v15, v11
	v_lshlrev_b32_e32 v34, 16, v12
	v_and_b32_e32 v33, 0xffff0000, v12
	v_max3_f32 v10, v14, v10, v11
	v_max_f32_e64 v11, |v33|, |v33|
	v_max_f32_e64 v12, |v34|, |v34|
	v_lshlrev_b32_e32 v32, 16, v13
	v_and_b32_e32 v31, 0xffff0000, v13
	v_max_f32_e32 v11, v12, v11
	v_max_f32_e64 v12, |v31|, |v31|
	v_max_f32_e64 v13, |v32|, |v32|
	v_max_f32_e32 v12, v13, v12
	v_lshlrev_b32_e32 v30, 16, v6
	v_and_b32_e32 v17, 0xffff0000, v6
	v_max3_f32 v10, v10, v11, v12
	v_max_f32_e64 v6, |v17|, |v17|
	v_max_f32_e64 v11, |v30|, |v30|
	v_lshlrev_b32_e32 v16, 16, v7
	v_and_b32_e32 v15, 0xffff0000, v7
	v_max_f32_e32 v6, v11, v6
	v_max_f32_e64 v7, |v15|, |v15|
	v_max_f32_e64 v11, |v16|, |v16|
	v_max_f32_e32 v7, v11, v7
	v_lshlrev_b32_e32 v14, 16, v8
	v_and_b32_e32 v13, 0xffff0000, v8
	v_max3_f32 v6, v10, v6, v7
	v_max_f32_e64 v7, |v13|, |v13|
	v_max_f32_e64 v8, |v14|, |v14|
	v_lshlrev_b32_e32 v12, 16, v9
	v_and_b32_e32 v11, 0xffff0000, v9
	v_max_f32_e32 v7, v8, v7
	v_max_f32_e64 v8, |v11|, |v11|
	v_max_f32_e64 v9, |v12|, |v12|
	v_max_f32_e32 v8, v9, v8
	v_lshlrev_b32_e32 v10, 16, v2
	v_and_b32_e32 v9, 0xffff0000, v2
	v_max3_f32 v6, v6, v7, v8
	v_max_f32_e64 v2, |v9|, |v9|
	v_max_f32_e64 v7, |v10|, |v10|
	v_max_f32_e32 v2, v7, v2
	v_lshlrev_b32_e32 v8, 16, v3
	v_and_b32_e32 v7, 0xffff0000, v3
	v_max_f32_e64 v3, |v7|, |v7|
	v_max_f32_e64 v48, |v8|, |v8|
	v_max_f32_e32 v3, v48, v3
	v_max3_f32 v48, v6, v2, v3
	v_lshlrev_b32_e32 v6, 16, v4
	v_and_b32_e32 v4, 0xffff0000, v4
	v_max_f32_e64 v2, |v4|, |v4|
	v_max_f32_e64 v3, |v6|, |v6|
	v_max_f32_e32 v49, v3, v2
	v_lshlrev_b32_e32 v3, 16, v5
	v_and_b32_e32 v2, 0xffff0000, v5
	v_max_f32_e64 v5, |v2|, |v2|
	v_max_f32_e64 v50, |v3|, |v3|
	v_max_f32_e32 v5, v50, v5
	v_max3_f32 v5, v48, v49, v5
	ds_bpermute_b32 v48, v24, v5
	s_waitcnt lgkmcnt(0)
	v_max_f32_e32 v48, v48, v48
	v_max_f32_e32 v5, v5, v48
	ds_bpermute_b32 v48, v24, v47
	ds_bpermute_b32 v49, v25, v5
	s_waitcnt lgkmcnt(1)
	v_add_f32_e32 v47, v47, v48
	s_waitcnt lgkmcnt(0)
	v_max_f32_e32 v48, v49, v49
	ds_bpermute_b32 v49, v25, v47
	v_max_f32_e32 v5, v5, v48
	ds_bpermute_b32 v48, v26, v5
	s_waitcnt lgkmcnt(1)
	v_add_f32_e32 v47, v47, v49
	ds_bpermute_b32 v49, v26, v47
	s_waitcnt lgkmcnt(1)
	v_max_f32_e32 v48, v48, v48
	v_max_f32_e32 v5, v5, v48
	ds_bpermute_b32 v48, v27, v5
	s_waitcnt lgkmcnt(1)
	v_add_f32_e32 v47, v47, v49
	ds_bpermute_b32 v49, v27, v47
	s_waitcnt lgkmcnt(1)
	v_max_f32_e32 v48, v48, v48
	v_max_f32_e32 v5, v5, v48
	ds_bpermute_b32 v48, v28, v5
	s_waitcnt lgkmcnt(1)
	v_add_f32_e32 v47, v47, v49
	ds_bpermute_b32 v49, v28, v47
	s_waitcnt lgkmcnt(1)
	v_max_f32_e32 v48, v48, v48
	v_max_f32_e32 v5, v5, v48
	s_waitcnt lgkmcnt(0)
	v_add_f32_e32 v47, v47, v49
	ds_bpermute_b32 v49, v29, v5
	ds_bpermute_b32 v48, v29, v47
	s_waitcnt lgkmcnt(1)
	v_max3_f32 v5, v5, v49, s73
	s_and_saveexec_b64 s[6:7], s[38:39]
	s_cbranch_execz .Lxqb_C1
	s_waitcnt lgkmcnt(0)
	v_add_f32_e32 v47, v47, v48
	v_fmamk_f32 v47, v47, 0x3a000000, v1
	v_mul_f32_e32 v48, 0x4f800000, v47
	v_cmp_gt_f32_e32 vcc, s70, v47
	s_nop 1
	v_cndmask_b32_e32 v47, v47, v48, vcc
	v_sqrt_f32_e32 v48, v47
	s_nop 0
	v_add_u32_e32 v49, -1, v48
	v_fma_f32 v51, -v49, v48, v47
	v_add_u32_e32 v50, 1, v48
	v_cmp_ge_f32_e64 s[40:41], 0, v51
	s_nop 1
	v_cndmask_b32_e64 v49, v48, v49, s[40:41]
	v_fma_f32 v48, -v50, v48, v47
	v_cmp_lt_f32_e64 s[40:41], 0, v48
	s_nop 1
	v_cndmask_b32_e64 v48, v49, v50, s[40:41]
	v_mul_f32_e32 v49, 0x37800000, v48
	v_cndmask_b32_e32 v48, v48, v49, vcc
	v_cmp_class_f32_e32 vcc, v47, v226
	s_nop 1
	v_cndmask_b32_e32 v47, v48, v47, vcc
	v_div_scale_f32 v48, s[16:17], v47, v47, 1.0
	v_rcp_f32_e32 v49, v48
	s_nop 0
	v_fma_f32 v50, -v48, v49, 1.0
	v_fmac_f32_e32 v49, v50, v49
	v_div_scale_f32 v50, vcc, 1.0, v47, 1.0
	v_mul_f32_e32 v51, v50, v49
	v_fma_f32 v52, -v48, v51, v50
	v_fmac_f32_e32 v51, v52, v49
	v_fma_f32 v48, -v48, v51, v50
	v_div_fmas_f32 v48, v48, v49, v51
	v_div_fixup_f32 v47, v48, v47, 1.0
	v_mul_f32_e32 v48, 0x3c010204, v5
	v_mul_f32_e32 v47, v48, v47
	global_store_dword v115, v47, s[8:9]
.Lxqb_C1:
	s_or_b64 exec, exec, s[6:7]
	v_div_scale_f32 v47, s[6:7], v5, v5, s47
	s_waitcnt lgkmcnt(0)
	v_rcp_f32_e32 v48, v47
	v_div_scale_f32 v49, vcc, s47, v5, s47
	s_add_i32 s22, s22, -1
	v_fma_f32 v50, -v47, v48, 1.0
	v_fmac_f32_e32 v48, v50, v48
	v_mul_f32_e32 v50, v49, v48
	v_fma_f32 v51, -v47, v50, v49
	v_fmac_f32_e32 v50, v51, v48
	v_fma_f32 v47, -v47, v50, v49
	v_div_fmas_f32 v47, v47, v48, v50
	v_div_fixup_f32 v5, v47, v5, s47
	v_mul_f32_e32 v45, v5, v45
	v_mul_f32_e32 v44, v5, v44
	v_mul_f32_e32 v46, v5, v46
	v_rndne_f32_e32 v45, v45
	v_rndne_f32_e32 v44, v44
	v_mul_f32_e32 v43, v5, v43
	v_rndne_f32_e32 v46, v46
	v_cvt_i32_f32_e32 v45, v45
	v_cvt_i32_f32_e32 v44, v44
	v_rndne_f32_e32 v43, v43
	v_mul_f32_e32 v41, v5, v41
	v_mul_f32_e32 v40, v5, v40
	v_cvt_i32_f32_e32 v46, v46
	v_cvt_i32_f32_e32 v43, v43
	v_mul_f32_e32 v42, v5, v42
	v_rndne_f32_e32 v41, v41
	v_rndne_f32_e32 v40, v40
	v_mul_f32_e32 v39, v5, v39
	v_rndne_f32_e32 v42, v42
	v_cvt_i32_f32_e32 v41, v41
	v_cvt_i32_f32_e32 v40, v40
	v_rndne_f32_e32 v39, v39
	v_cvt_i32_f32_e32 v47, v42
	v_cvt_i32_f32_e32 v39, v39
	v_med3_i32 v45, v45, s71, v235
	v_med3_i32 v44, v44, s71, v235
	v_mul_f32_e32 v37, v5, v37
	v_mul_f32_e32 v36, v5, v36
	v_med3_i32 v46, v46, s71, v235
	v_lshlrev_b32_e32 v45, 8, v45
	v_lshlrev_b32_e32 v44, 16, v44
	v_med3_i32 v43, v43, s71, v235
	v_mul_f32_e32 v38, v5, v38
	v_rndne_f32_e32 v37, v37
	v_rndne_f32_e32 v36, v36
	v_mul_f32_e32 v35, v5, v35
	v_and_b32_e32 v44, 0xff0000, v44
	v_lshlrev_b32_e32 v43, 24, v43
	v_perm_b32 v42, v45, v46, s49
	v_med3_i32 v41, v41, s71, v235
	v_med3_i32 v40, v40, s71, v235
	v_rndne_f32_e32 v38, v38
	v_cvt_i32_f32_e32 v37, v37
	v_cvt_i32_f32_e32 v36, v36
	v_rndne_f32_e32 v35, v35
	v_mul_f32_e32 v33, v5, v33
	v_mul_f32_e32 v32, v5, v32
	v_or3_b32 v42, v42, v43, v44
	v_med3_i32 v43, v47, s71, v235
	v_lshlrev_b32_e32 v41, 8, v41
	v_lshlrev_b32_e32 v40, 16, v40
	v_med3_i32 v39, v39, s71, v235
	v_cvt_i32_f32_e32 v38, v38
	v_cvt_i32_f32_e32 v35, v35
	v_mul_f32_e32 v34, v5, v34
	v_rndne_f32_e32 v33, v33
	v_rndne_f32_e32 v32, v32
	v_mul_f32_e32 v31, v5, v31
	v_and_b32_e32 v41, 0xff00, v41
	v_and_b32_e32 v40, 0xff0000, v40
	v_perm_b32 v39, v39, v43, s48
	v_rndne_f32_e32 v34, v34
	v_cvt_i32_f32_e32 v33, v33
	v_cvt_i32_f32_e32 v32, v32
	v_rndne_f32_e32 v31, v31
	v_or3_b32 v43, v39, v41, v40
	v_cvt_i32_f32_e32 v39, v34
	v_cvt_i32_f32_e32 v31, v31
	v_med3_i32 v37, v37, s71, v235
	v_med3_i32 v36, v36, s71, v235
	v_mul_f32_e32 v17, v5, v17
	v_mul_f32_e32 v16, v5, v16
	v_med3_i32 v38, v38, s71, v235
	v_lshlrev_b32_e32 v37, 8, v37
	v_lshlrev_b32_e32 v36, 16, v36
	v_med3_i32 v35, v35, s71, v235
	v_mul_f32_e32 v30, v5, v30
	v_rndne_f32_e32 v17, v17
	v_rndne_f32_e32 v16, v16
	v_mul_f32_e32 v15, v5, v15
	v_and_b32_e32 v36, 0xff0000, v36
	v_lshlrev_b32_e32 v35, 24, v35
	v_perm_b32 v34, v37, v38, s49
	v_med3_i32 v33, v33, s71, v235
	v_med3_i32 v32, v32, s71, v235
	v_rndne_f32_e32 v30, v30
	v_cvt_i32_f32_e32 v17, v17
	v_cvt_i32_f32_e32 v16, v16
	v_rndne_f32_e32 v15, v15
	v_mul_f32_e32 v13, v5, v13
	v_mul_f32_e32 v12, v5, v12
	v_or3_b32 v34, v34, v35, v36
	v_med3_i32 v35, v39, s71, v235
	v_lshlrev_b32_e32 v33, 8, v33
	v_lshlrev_b32_e32 v32, 16, v32
	v_med3_i32 v31, v31, s71, v235
	v_cvt_i32_f32_e32 v30, v30
	v_cvt_i32_f32_e32 v15, v15
	v_mul_f32_e32 v14, v5, v14
	v_rndne_f32_e32 v13, v13
	v_rndne_f32_e32 v12, v12
	v_mul_f32_e32 v11, v5, v11
	v_and_b32_e32 v33, 0xff00, v33
	v_and_b32_e32 v32, 0xff0000, v32
	v_perm_b32 v31, v31, v35, s48
	v_rndne_f32_e32 v14, v14
	v_cvt_i32_f32_e32 v13, v13
	v_cvt_i32_f32_e32 v12, v12
	v_rndne_f32_e32 v11, v11
	v_or3_b32 v35, v31, v33, v32
	v_cvt_i32_f32_e32 v31, v14
	v_cvt_i32_f32_e32 v11, v11
	v_med3_i32 v17, v17, s71, v235
	v_med3_i32 v16, v16, s71, v235
	v_mul_f32_e32 v9, v5, v9
	v_mul_f32_e32 v8, v5, v8
	v_med3_i32 v30, v30, s71, v235
	v_lshlrev_b32_e32 v17, 8, v17
	v_lshlrev_b32_e32 v16, 16, v16
	v_med3_i32 v15, v15, s71, v235
	v_mul_f32_e32 v10, v5, v10
	v_rndne_f32_e32 v9, v9
	v_rndne_f32_e32 v8, v8
	v_mul_f32_e32 v7, v5, v7
	v_and_b32_e32 v16, 0xff0000, v16
	v_lshlrev_b32_e32 v15, 24, v15
	v_perm_b32 v14, v17, v30, s49
	v_med3_i32 v13, v13, s71, v235
	v_med3_i32 v12, v12, s71, v235
	v_rndne_f32_e32 v10, v10
	v_cvt_i32_f32_e32 v9, v9
	v_cvt_i32_f32_e32 v8, v8
	v_rndne_f32_e32 v7, v7
	v_or3_b32 v14, v14, v15, v16
	v_med3_i32 v15, v31, s71, v235
	v_lshlrev_b32_e32 v13, 8, v13
	v_lshlrev_b32_e32 v12, 16, v12
	v_med3_i32 v11, v11, s71, v235
	v_cvt_i32_f32_e32 v10, v10
	v_cvt_i32_f32_e32 v7, v7
	v_mul_f32_e32 v4, v5, v4
	v_mul_f32_e32 v3, v5, v3
	v_and_b32_e32 v13, 0xff00, v13
	v_and_b32_e32 v12, 0xff0000, v12
	v_perm_b32 v11, v11, v15, s48
	v_mul_f32_e32 v6, v5, v6
	v_rndne_f32_e32 v4, v4
	v_rndne_f32_e32 v3, v3
	v_mul_f32_e32 v2, v5, v2
	v_or3_b32 v15, v11, v13, v12
	v_rndne_f32_e32 v6, v6
	v_cvt_i32_f32_e32 v11, v4
	v_cvt_i32_f32_e32 v3, v3
	v_rndne_f32_e32 v2, v2
	v_med3_i32 v9, v9, s71, v235
	v_med3_i32 v8, v8, s71, v235
	v_cvt_i32_f32_e32 v6, v6
	v_cvt_i32_f32_e32 v2, v2
	v_med3_i32 v10, v10, s71, v235
	v_lshlrev_b32_e32 v9, 8, v9
	v_lshlrev_b32_e32 v8, 16, v8
	v_med3_i32 v7, v7, s71, v235
	v_and_b32_e32 v8, 0xff0000, v8
	v_lshlrev_b32_e32 v7, 24, v7
	v_perm_b32 v4, v9, v10, s49
	v_or3_b32 v4, v4, v7, v8
	v_med3_i32 v7, v11, s71, v235
	v_med3_i32 v3, v3, s71, v235
	v_med3_i32 v6, v6, s71, v235
	v_lshlrev_b32_e32 v7, 8, v7
	v_lshlrev_b32_e32 v3, 16, v3
	v_med3_i32 v2, v2, s71, v235
	v_and_b32_e32 v7, 0xff00, v7
	v_and_b32_e32 v3, 0xff0000, v3
	v_perm_b32 v2, v2, v6, s48
	s_add_u32 s8, s8, s10
	v_or3_b32 v5, v2, v7, v3
	s_addc_u32 s9, s9, s11
	global_store_dwordx2 v[22:23], v[42:43], off offset:-1024
	global_store_dwordx2 v[22:23], v[34:35], off offset:-512
	global_store_dwordx2 v[22:23], v[14:15], off
	global_store_dwordx2 v[22:23], v[4:5], off offset:512
	v_lshl_add_u64 v[18:19], v[18:19], 0, s[12:13]
	v_lshl_add_u64 v[20:21], v[20:21], 0, s[14:15]
	v_lshl_add_u64 v[22:23], v[22:23], 0, s[0:1]
	s_waitcnt vmcnt(12)
	v_mov_b32_e32 v14, v74
	v_mov_b32_e32 v15, v75
	v_mov_b32_e32 v16, v76
	v_mov_b32_e32 v17, v77
	v_mov_b32_e32 v10, v78
	v_mov_b32_e32 v11, v79
	v_mov_b32_e32 v12, v80
	v_mov_b32_e32 v13, v81
	v_mov_b32_e32 v6, v82
	v_mov_b32_e32 v7, v83
	v_mov_b32_e32 v8, v84
	v_mov_b32_e32 v9, v85
	v_mov_b32_e32 v2, v86
	v_mov_b32_e32 v3, v87
	v_mov_b32_e32 v4, v88
	v_mov_b32_e32 v5, v89
	v_mov_b32_e32 v47, v90
	v_lshlrev_b32_e32 v46, 16, v14
	v_and_b32_e32 v45, 0xffff0000, v14
	v_max_f32_e64 v14, |v45|, |v45|
	v_max_f32_e64 v30, |v46|, |v46|
	v_lshlrev_b32_e32 v44, 16, v15
	v_and_b32_e32 v43, 0xffff0000, v15
	v_max_f32_e32 v14, v30, v14
	v_max_f32_e64 v15, |v43|, |v43|
	v_max_f32_e64 v30, |v44|, |v44|
	v_max_f32_e32 v15, v30, v15
	v_lshlrev_b32_e32 v42, 16, v16
	v_and_b32_e32 v41, 0xffff0000, v16
	v_max3_f32 v14, v14, 0, v15
	v_max_f32_e64 v15, |v41|, |v41|
	v_max_f32_e64 v16, |v42|, |v42|
	v_lshlrev_b32_e32 v40, 16, v17
	v_and_b32_e32 v39, 0xffff0000, v17
	v_max_f32_e32 v15, v16, v15
	v_max_f32_e64 v16, |v39|, |v39|
	v_max_f32_e64 v17, |v40|, |v40|
	v_max_f32_e32 v16, v17, v16
	v_lshlrev_b32_e32 v38, 16, v10
	v_and_b32_e32 v37, 0xffff0000, v10
	v_max3_f32 v14, v14, v15, v16
	v_max_f32_e64 v10, |v37|, |v37|
	v_max_f32_e64 v15, |v38|, |v38|
	v_lshlrev_b32_e32 v36, 16, v11
	v_and_b32_e32 v35, 0xffff0000, v11
	v_max_f32_e32 v10, v15, v10
	v_max_f32_e64 v11, |v35|, |v35|
	v_max_f32_e64 v15, |v36|, |v36|
	v_max_f32_e32 v11, v15, v11
	v_lshlrev_b32_e32 v34, 16, v12
	v_and_b32_e32 v33, 0xffff0000, v12
	v_max3_f32 v10, v14, v10, v11
	v_max_f32_e64 v11, |v33|, |v33|
	v_max_f32_e64 v12, |v34|, |v34|
	v_lshlrev_b32_e32 v32, 16, v13
	v_and_b32_e32 v31, 0xffff0000, v13
	v_max_f32_e32 v11, v12, v11
	v_max_f32_e64 v12, |v31|, |v31|
	v_max_f32_e64 v13, |v32|, |v32|
	v_max_f32_e32 v12, v13, v12
	v_lshlrev_b32_e32 v30, 16, v6
	v_and_b32_e32 v17, 0xffff0000, v6
	v_max3_f32 v10, v10, v11, v12
	v_max_f32_e64 v6, |v17|, |v17|
	v_max_f32_e64 v11, |v30|, |v30|
	v_lshlrev_b32_e32 v16, 16, v7
	v_and_b32_e32 v15, 0xffff0000, v7
	v_max_f32_e32 v6, v11, v6
	v_max_f32_e64 v7, |v15|, |v15|
	v_max_f32_e64 v11, |v16|, |v16|
	v_max_f32_e32 v7, v11, v7
	v_lshlrev_b32_e32 v14, 16, v8
	v_and_b32_e32 v13, 0xffff0000, v8
	v_max3_f32 v6, v10, v6, v7
	v_max_f32_e64 v7, |v13|, |v13|
	v_max_f32_e64 v8, |v14|, |v14|
	v_lshlrev_b32_e32 v12, 16, v9
	v_and_b32_e32 v11, 0xffff0000, v9
	v_max_f32_e32 v7, v8, v7
	v_max_f32_e64 v8, |v11|, |v11|
	v_max_f32_e64 v9, |v12|, |v12|
	v_max_f32_e32 v8, v9, v8
	v_lshlrev_b32_e32 v10, 16, v2
	v_and_b32_e32 v9, 0xffff0000, v2
	v_max3_f32 v6, v6, v7, v8
	v_max_f32_e64 v2, |v9|, |v9|
	v_max_f32_e64 v7, |v10|, |v10|
	v_max_f32_e32 v2, v7, v2
	v_lshlrev_b32_e32 v8, 16, v3
	v_and_b32_e32 v7, 0xffff0000, v3
	v_max_f32_e64 v3, |v7|, |v7|
	v_max_f32_e64 v48, |v8|, |v8|
	v_max_f32_e32 v3, v48, v3
	v_max3_f32 v48, v6, v2, v3
	v_lshlrev_b32_e32 v6, 16, v4
	v_and_b32_e32 v4, 0xffff0000, v4
	v_max_f32_e64 v2, |v4|, |v4|
	v_max_f32_e64 v3, |v6|, |v6|
	v_max_f32_e32 v49, v3, v2
	v_lshlrev_b32_e32 v3, 16, v5
	v_and_b32_e32 v2, 0xffff0000, v5
	v_max_f32_e64 v5, |v2|, |v2|
	v_max_f32_e64 v50, |v3|, |v3|
	v_max_f32_e32 v5, v50, v5
	v_max3_f32 v5, v48, v49, v5
	ds_bpermute_b32 v48, v24, v5
	s_waitcnt lgkmcnt(0)
	v_max_f32_e32 v48, v48, v48
	v_max_f32_e32 v5, v5, v48
	ds_bpermute_b32 v48, v24, v47
	ds_bpermute_b32 v49, v25, v5
	s_waitcnt lgkmcnt(1)
	v_add_f32_e32 v47, v47, v48
	s_waitcnt lgkmcnt(0)
	v_max_f32_e32 v48, v49, v49
	ds_bpermute_b32 v49, v25, v47
	v_max_f32_e32 v5, v5, v48
	ds_bpermute_b32 v48, v26, v5
	s_waitcnt lgkmcnt(1)
	v_add_f32_e32 v47, v47, v49
	ds_bpermute_b32 v49, v26, v47
	s_waitcnt lgkmcnt(1)
	v_max_f32_e32 v48, v48, v48
	v_max_f32_e32 v5, v5, v48
	ds_bpermute_b32 v48, v27, v5
	s_waitcnt lgkmcnt(1)
	v_add_f32_e32 v47, v47, v49
	ds_bpermute_b32 v49, v27, v47
	s_waitcnt lgkmcnt(1)
	v_max_f32_e32 v48, v48, v48
	v_max_f32_e32 v5, v5, v48
	ds_bpermute_b32 v48, v28, v5
	s_waitcnt lgkmcnt(1)
	v_add_f32_e32 v47, v47, v49
	ds_bpermute_b32 v49, v28, v47
	s_waitcnt lgkmcnt(1)
	v_max_f32_e32 v48, v48, v48
	v_max_f32_e32 v5, v5, v48
	s_waitcnt lgkmcnt(0)
	v_add_f32_e32 v47, v47, v49
	ds_bpermute_b32 v49, v29, v5
	ds_bpermute_b32 v48, v29, v47
	s_waitcnt lgkmcnt(1)
	v_max3_f32 v5, v5, v49, s73
	s_and_saveexec_b64 s[6:7], s[38:39]
	s_cbranch_execz .Lxqb_C2
	s_waitcnt lgkmcnt(0)
	v_add_f32_e32 v47, v47, v48
	v_fmamk_f32 v47, v47, 0x3a000000, v1
	v_mul_f32_e32 v48, 0x4f800000, v47
	v_cmp_gt_f32_e32 vcc, s70, v47
	s_nop 1
	v_cndmask_b32_e32 v47, v47, v48, vcc
	v_sqrt_f32_e32 v48, v47
	s_nop 0
	v_add_u32_e32 v49, -1, v48
	v_fma_f32 v51, -v49, v48, v47
	v_add_u32_e32 v50, 1, v48
	v_cmp_ge_f32_e64 s[40:41], 0, v51
	s_nop 1
	v_cndmask_b32_e64 v49, v48, v49, s[40:41]
	v_fma_f32 v48, -v50, v48, v47
	v_cmp_lt_f32_e64 s[40:41], 0, v48
	s_nop 1
	v_cndmask_b32_e64 v48, v49, v50, s[40:41]
	v_mul_f32_e32 v49, 0x37800000, v48
	v_cndmask_b32_e32 v48, v48, v49, vcc
	v_cmp_class_f32_e32 vcc, v47, v226
	s_nop 1
	v_cndmask_b32_e32 v47, v48, v47, vcc
	v_div_scale_f32 v48, s[16:17], v47, v47, 1.0
	v_rcp_f32_e32 v49, v48
	s_nop 0
	v_fma_f32 v50, -v48, v49, 1.0
	v_fmac_f32_e32 v49, v50, v49
	v_div_scale_f32 v50, vcc, 1.0, v47, 1.0
	v_mul_f32_e32 v51, v50, v49
	v_fma_f32 v52, -v48, v51, v50
	v_fmac_f32_e32 v51, v52, v49
	v_fma_f32 v48, -v48, v51, v50
	v_div_fmas_f32 v48, v48, v49, v51
	v_div_fixup_f32 v47, v48, v47, 1.0
	v_mul_f32_e32 v48, 0x3c010204, v5
	v_mul_f32_e32 v47, v48, v47
	global_store_dword v115, v47, s[8:9]
.Lxqb_C2:
	s_or_b64 exec, exec, s[6:7]
	v_div_scale_f32 v47, s[6:7], v5, v5, s47
	s_waitcnt lgkmcnt(0)
	v_rcp_f32_e32 v48, v47
	v_div_scale_f32 v49, vcc, s47, v5, s47
	s_add_i32 s22, s22, -1
	v_fma_f32 v50, -v47, v48, 1.0
	v_fmac_f32_e32 v48, v50, v48
	v_mul_f32_e32 v50, v49, v48
	v_fma_f32 v51, -v47, v50, v49
	v_fmac_f32_e32 v50, v51, v48
	v_fma_f32 v47, -v47, v50, v49
	v_div_fmas_f32 v47, v47, v48, v50
	v_div_fixup_f32 v5, v47, v5, s47
	v_mul_f32_e32 v45, v5, v45
	v_mul_f32_e32 v44, v5, v44
	v_mul_f32_e32 v46, v5, v46
	v_rndne_f32_e32 v45, v45
	v_rndne_f32_e32 v44, v44
	v_mul_f32_e32 v43, v5, v43
	v_rndne_f32_e32 v46, v46
	v_cvt_i32_f32_e32 v45, v45
	v_cvt_i32_f32_e32 v44, v44
	v_rndne_f32_e32 v43, v43
	v_mul_f32_e32 v41, v5, v41
	v_mul_f32_e32 v40, v5, v40
	v_cvt_i32_f32_e32 v46, v46
	v_cvt_i32_f32_e32 v43, v43
	v_mul_f32_e32 v42, v5, v42
	v_rndne_f32_e32 v41, v41
	v_rndne_f32_e32 v40, v40
	v_mul_f32_e32 v39, v5, v39
	v_rndne_f32_e32 v42, v42
	v_cvt_i32_f32_e32 v41, v41
	v_cvt_i32_f32_e32 v40, v40
	v_rndne_f32_e32 v39, v39
	v_cvt_i32_f32_e32 v47, v42
	v_cvt_i32_f32_e32 v39, v39
	v_med3_i32 v45, v45, s71, v235
	v_med3_i32 v44, v44, s71, v235
	v_mul_f32_e32 v37, v5, v37
	v_mul_f32_e32 v36, v5, v36
	v_med3_i32 v46, v46, s71, v235
	v_lshlrev_b32_e32 v45, 8, v45
	v_lshlrev_b32_e32 v44, 16, v44
	v_med3_i32 v43, v43, s71, v235
	v_mul_f32_e32 v38, v5, v38
	v_rndne_f32_e32 v37, v37
	v_rndne_f32_e32 v36, v36
	v_mul_f32_e32 v35, v5, v35
	v_and_b32_e32 v44, 0xff0000, v44
	v_lshlrev_b32_e32 v43, 24, v43
	v_perm_b32 v42, v45, v46, s49
	v_med3_i32 v41, v41, s71, v235
	v_med3_i32 v40, v40, s71, v235
	v_rndne_f32_e32 v38, v38
	v_cvt_i32_f32_e32 v37, v37
	v_cvt_i32_f32_e32 v36, v36
	v_rndne_f32_e32 v35, v35
	v_mul_f32_e32 v33, v5, v33
	v_mul_f32_e32 v32, v5, v32
	v_or3_b32 v42, v42, v43, v44
	v_med3_i32 v43, v47, s71, v235
	v_lshlrev_b32_e32 v41, 8, v41
	v_lshlrev_b32_e32 v40, 16, v40
	v_med3_i32 v39, v39, s71, v235
	v_cvt_i32_f32_e32 v38, v38
	v_cvt_i32_f32_e32 v35, v35
	v_mul_f32_e32 v34, v5, v34
	v_rndne_f32_e32 v33, v33
	v_rndne_f32_e32 v32, v32
	v_mul_f32_e32 v31, v5, v31
	v_and_b32_e32 v41, 0xff00, v41
	v_and_b32_e32 v40, 0xff0000, v40
	v_perm_b32 v39, v39, v43, s48
	v_rndne_f32_e32 v34, v34
	v_cvt_i32_f32_e32 v33, v33
	v_cvt_i32_f32_e32 v32, v32
	v_rndne_f32_e32 v31, v31
	v_or3_b32 v43, v39, v41, v40
	v_cvt_i32_f32_e32 v39, v34
	v_cvt_i32_f32_e32 v31, v31
	v_med3_i32 v37, v37, s71, v235
	v_med3_i32 v36, v36, s71, v235
	v_mul_f32_e32 v17, v5, v17
	v_mul_f32_e32 v16, v5, v16
	v_med3_i32 v38, v38, s71, v235
	v_lshlrev_b32_e32 v37, 8, v37
	v_lshlrev_b32_e32 v36, 16, v36
	v_med3_i32 v35, v35, s71, v235
	v_mul_f32_e32 v30, v5, v30
	v_rndne_f32_e32 v17, v17
	v_rndne_f32_e32 v16, v16
	v_mul_f32_e32 v15, v5, v15
	v_and_b32_e32 v36, 0xff0000, v36
	v_lshlrev_b32_e32 v35, 24, v35
	v_perm_b32 v34, v37, v38, s49
	v_med3_i32 v33, v33, s71, v235
	v_med3_i32 v32, v32, s71, v235
	v_rndne_f32_e32 v30, v30
	v_cvt_i32_f32_e32 v17, v17
	v_cvt_i32_f32_e32 v16, v16
	v_rndne_f32_e32 v15, v15
	v_mul_f32_e32 v13, v5, v13
	v_mul_f32_e32 v12, v5, v12
	v_or3_b32 v34, v34, v35, v36
	v_med3_i32 v35, v39, s71, v235
	v_lshlrev_b32_e32 v33, 8, v33
	v_lshlrev_b32_e32 v32, 16, v32
	v_med3_i32 v31, v31, s71, v235
	v_cvt_i32_f32_e32 v30, v30
	v_cvt_i32_f32_e32 v15, v15
	v_mul_f32_e32 v14, v5, v14
	v_rndne_f32_e32 v13, v13
	v_rndne_f32_e32 v12, v12
	v_mul_f32_e32 v11, v5, v11
	v_and_b32_e32 v33, 0xff00, v33
	v_and_b32_e32 v32, 0xff0000, v32
	v_perm_b32 v31, v31, v35, s48
	v_rndne_f32_e32 v14, v14
	v_cvt_i32_f32_e32 v13, v13
	v_cvt_i32_f32_e32 v12, v12
	v_rndne_f32_e32 v11, v11
	v_or3_b32 v35, v31, v33, v32
	v_cvt_i32_f32_e32 v31, v14
	v_cvt_i32_f32_e32 v11, v11
	v_med3_i32 v17, v17, s71, v235
	v_med3_i32 v16, v16, s71, v235
	v_mul_f32_e32 v9, v5, v9
	v_mul_f32_e32 v8, v5, v8
	v_med3_i32 v30, v30, s71, v235
	v_lshlrev_b32_e32 v17, 8, v17
	v_lshlrev_b32_e32 v16, 16, v16
	v_med3_i32 v15, v15, s71, v235
	v_mul_f32_e32 v10, v5, v10
	v_rndne_f32_e32 v9, v9
	v_rndne_f32_e32 v8, v8
	v_mul_f32_e32 v7, v5, v7
	v_and_b32_e32 v16, 0xff0000, v16
	v_lshlrev_b32_e32 v15, 24, v15
	v_perm_b32 v14, v17, v30, s49
	v_med3_i32 v13, v13, s71, v235
	v_med3_i32 v12, v12, s71, v235
	v_rndne_f32_e32 v10, v10
	v_cvt_i32_f32_e32 v9, v9
	v_cvt_i32_f32_e32 v8, v8
	v_rndne_f32_e32 v7, v7
	v_or3_b32 v14, v14, v15, v16
	v_med3_i32 v15, v31, s71, v235
	v_lshlrev_b32_e32 v13, 8, v13
	v_lshlrev_b32_e32 v12, 16, v12
	v_med3_i32 v11, v11, s71, v235
	v_cvt_i32_f32_e32 v10, v10
	v_cvt_i32_f32_e32 v7, v7
	v_mul_f32_e32 v4, v5, v4
	v_mul_f32_e32 v3, v5, v3
	v_and_b32_e32 v13, 0xff00, v13
	v_and_b32_e32 v12, 0xff0000, v12
	v_perm_b32 v11, v11, v15, s48
	v_mul_f32_e32 v6, v5, v6
	v_rndne_f32_e32 v4, v4
	v_rndne_f32_e32 v3, v3
	v_mul_f32_e32 v2, v5, v2
	v_or3_b32 v15, v11, v13, v12
	v_rndne_f32_e32 v6, v6
	v_cvt_i32_f32_e32 v11, v4
	v_cvt_i32_f32_e32 v3, v3
	v_rndne_f32_e32 v2, v2
	v_med3_i32 v9, v9, s71, v235
	v_med3_i32 v8, v8, s71, v235
	v_cvt_i32_f32_e32 v6, v6
	v_cvt_i32_f32_e32 v2, v2
	v_med3_i32 v10, v10, s71, v235
	v_lshlrev_b32_e32 v9, 8, v9
	v_lshlrev_b32_e32 v8, 16, v8
	v_med3_i32 v7, v7, s71, v235
	v_and_b32_e32 v8, 0xff0000, v8
	v_lshlrev_b32_e32 v7, 24, v7
	v_perm_b32 v4, v9, v10, s49
	v_or3_b32 v4, v4, v7, v8
	v_med3_i32 v7, v11, s71, v235
	v_med3_i32 v3, v3, s71, v235
	v_med3_i32 v6, v6, s71, v235
	v_lshlrev_b32_e32 v7, 8, v7
	v_lshlrev_b32_e32 v3, 16, v3
	v_med3_i32 v2, v2, s71, v235
	v_and_b32_e32 v7, 0xff00, v7
	v_and_b32_e32 v3, 0xff0000, v3
	v_perm_b32 v2, v2, v6, s48
	s_add_u32 s8, s8, s10
	v_or3_b32 v5, v2, v7, v3
	s_addc_u32 s9, s9, s11
	global_store_dwordx2 v[22:23], v[42:43], off offset:-1024
	global_store_dwordx2 v[22:23], v[34:35], off offset:-512
	global_store_dwordx2 v[22:23], v[14:15], off
	global_store_dwordx2 v[22:23], v[4:5], off offset:512
	v_lshl_add_u64 v[18:19], v[18:19], 0, s[12:13]
	v_lshl_add_u64 v[20:21], v[20:21], 0, s[14:15]
	v_lshl_add_u64 v[22:23], v[22:23], 0, s[0:1]
	s_waitcnt vmcnt(12)
	v_mov_b32_e32 v14, v92
	v_mov_b32_e32 v15, v93
	v_mov_b32_e32 v16, v94
	v_mov_b32_e32 v17, v95
	v_mov_b32_e32 v10, v96
	v_mov_b32_e32 v11, v97
	v_mov_b32_e32 v12, v98
	v_mov_b32_e32 v13, v99
	v_mov_b32_e32 v6, v100
	v_mov_b32_e32 v7, v101
	v_mov_b32_e32 v8, v102
	v_mov_b32_e32 v9, v103
	v_mov_b32_e32 v2, v104
	v_mov_b32_e32 v3, v105
	v_mov_b32_e32 v4, v106
	v_mov_b32_e32 v5, v107
	v_mov_b32_e32 v47, v108
	v_lshlrev_b32_e32 v46, 16, v14
	v_and_b32_e32 v45, 0xffff0000, v14
	v_max_f32_e64 v14, |v45|, |v45|
	v_max_f32_e64 v30, |v46|, |v46|
	v_lshlrev_b32_e32 v44, 16, v15
	v_and_b32_e32 v43, 0xffff0000, v15
	v_max_f32_e32 v14, v30, v14
	v_max_f32_e64 v15, |v43|, |v43|
	v_max_f32_e64 v30, |v44|, |v44|
	v_max_f32_e32 v15, v30, v15
	v_lshlrev_b32_e32 v42, 16, v16
	v_and_b32_e32 v41, 0xffff0000, v16
	v_max3_f32 v14, v14, 0, v15
	v_max_f32_e64 v15, |v41|, |v41|
	v_max_f32_e64 v16, |v42|, |v42|
	v_lshlrev_b32_e32 v40, 16, v17
	v_and_b32_e32 v39, 0xffff0000, v17
	v_max_f32_e32 v15, v16, v15
	v_max_f32_e64 v16, |v39|, |v39|
	v_max_f32_e64 v17, |v40|, |v40|
	v_max_f32_e32 v16, v17, v16
	v_lshlrev_b32_e32 v38, 16, v10
	v_and_b32_e32 v37, 0xffff0000, v10
	v_max3_f32 v14, v14, v15, v16
	v_max_f32_e64 v10, |v37|, |v37|
	v_max_f32_e64 v15, |v38|, |v38|
	v_lshlrev_b32_e32 v36, 16, v11
	v_and_b32_e32 v35, 0xffff0000, v11
	v_max_f32_e32 v10, v15, v10
	v_max_f32_e64 v11, |v35|, |v35|
	v_max_f32_e64 v15, |v36|, |v36|
	v_max_f32_e32 v11, v15, v11
	v_lshlrev_b32_e32 v34, 16, v12
	v_and_b32_e32 v33, 0xffff0000, v12
	v_max3_f32 v10, v14, v10, v11
	v_max_f32_e64 v11, |v33|, |v33|
	v_max_f32_e64 v12, |v34|, |v34|
	v_lshlrev_b32_e32 v32, 16, v13
	v_and_b32_e32 v31, 0xffff0000, v13
	v_max_f32_e32 v11, v12, v11
	v_max_f32_e64 v12, |v31|, |v31|
	v_max_f32_e64 v13, |v32|, |v32|
	v_max_f32_e32 v12, v13, v12
	v_lshlrev_b32_e32 v30, 16, v6
	v_and_b32_e32 v17, 0xffff0000, v6
	v_max3_f32 v10, v10, v11, v12
	v_max_f32_e64 v6, |v17|, |v17|
	v_max_f32_e64 v11, |v30|, |v30|
	v_lshlrev_b32_e32 v16, 16, v7
	v_and_b32_e32 v15, 0xffff0000, v7
	v_max_f32_e32 v6, v11, v6
	v_max_f32_e64 v7, |v15|, |v15|
	v_max_f32_e64 v11, |v16|, |v16|
	v_max_f32_e32 v7, v11, v7
	v_lshlrev_b32_e32 v14, 16, v8
	v_and_b32_e32 v13, 0xffff0000, v8
	v_max3_f32 v6, v10, v6, v7
	v_max_f32_e64 v7, |v13|, |v13|
	v_max_f32_e64 v8, |v14|, |v14|
	v_lshlrev_b32_e32 v12, 16, v9
	v_and_b32_e32 v11, 0xffff0000, v9
	v_max_f32_e32 v7, v8, v7
	v_max_f32_e64 v8, |v11|, |v11|
	v_max_f32_e64 v9, |v12|, |v12|
	v_max_f32_e32 v8, v9, v8
	v_lshlrev_b32_e32 v10, 16, v2
	v_and_b32_e32 v9, 0xffff0000, v2
	v_max3_f32 v6, v6, v7, v8
	v_max_f32_e64 v2, |v9|, |v9|
	v_max_f32_e64 v7, |v10|, |v10|
	v_max_f32_e32 v2, v7, v2
	v_lshlrev_b32_e32 v8, 16, v3
	v_and_b32_e32 v7, 0xffff0000, v3
	v_max_f32_e64 v3, |v7|, |v7|
	v_max_f32_e64 v48, |v8|, |v8|
	v_max_f32_e32 v3, v48, v3
	v_max3_f32 v48, v6, v2, v3
	v_lshlrev_b32_e32 v6, 16, v4
	v_and_b32_e32 v4, 0xffff0000, v4
	v_max_f32_e64 v2, |v4|, |v4|
	v_max_f32_e64 v3, |v6|, |v6|
	v_max_f32_e32 v49, v3, v2
	v_lshlrev_b32_e32 v3, 16, v5
	v_and_b32_e32 v2, 0xffff0000, v5
	v_max_f32_e64 v5, |v2|, |v2|
	v_max_f32_e64 v50, |v3|, |v3|
	v_max_f32_e32 v5, v50, v5
	v_max3_f32 v5, v48, v49, v5
	ds_bpermute_b32 v48, v24, v5
	s_waitcnt lgkmcnt(0)
	v_max_f32_e32 v48, v48, v48
	v_max_f32_e32 v5, v5, v48
	ds_bpermute_b32 v48, v24, v47
	ds_bpermute_b32 v49, v25, v5
	s_waitcnt lgkmcnt(1)
	v_add_f32_e32 v47, v47, v48
	s_waitcnt lgkmcnt(0)
	v_max_f32_e32 v48, v49, v49
	ds_bpermute_b32 v49, v25, v47
	v_max_f32_e32 v5, v5, v48
	ds_bpermute_b32 v48, v26, v5
	s_waitcnt lgkmcnt(1)
	v_add_f32_e32 v47, v47, v49
	ds_bpermute_b32 v49, v26, v47
	s_waitcnt lgkmcnt(1)
	v_max_f32_e32 v48, v48, v48
	v_max_f32_e32 v5, v5, v48
	ds_bpermute_b32 v48, v27, v5
	s_waitcnt lgkmcnt(1)
	v_add_f32_e32 v47, v47, v49
	ds_bpermute_b32 v49, v27, v47
	s_waitcnt lgkmcnt(1)
	v_max_f32_e32 v48, v48, v48
	v_max_f32_e32 v5, v5, v48
	ds_bpermute_b32 v48, v28, v5
	s_waitcnt lgkmcnt(1)
	v_add_f32_e32 v47, v47, v49
	ds_bpermute_b32 v49, v28, v47
	s_waitcnt lgkmcnt(1)
	v_max_f32_e32 v48, v48, v48
	v_max_f32_e32 v5, v5, v48
	s_waitcnt lgkmcnt(0)
	v_add_f32_e32 v47, v47, v49
	ds_bpermute_b32 v49, v29, v5
	ds_bpermute_b32 v48, v29, v47
	s_waitcnt lgkmcnt(1)
	v_max3_f32 v5, v5, v49, s73
	s_and_saveexec_b64 s[6:7], s[38:39]
	s_cbranch_execz .Lxqb_C3
	s_waitcnt lgkmcnt(0)
	v_add_f32_e32 v47, v47, v48
	v_fmamk_f32 v47, v47, 0x3a000000, v1
	v_mul_f32_e32 v48, 0x4f800000, v47
	v_cmp_gt_f32_e32 vcc, s70, v47
	s_nop 1
	v_cndmask_b32_e32 v47, v47, v48, vcc
	v_sqrt_f32_e32 v48, v47
	s_nop 0
	v_add_u32_e32 v49, -1, v48
	v_fma_f32 v51, -v49, v48, v47
	v_add_u32_e32 v50, 1, v48
	v_cmp_ge_f32_e64 s[40:41], 0, v51
	s_nop 1
	v_cndmask_b32_e64 v49, v48, v49, s[40:41]
	v_fma_f32 v48, -v50, v48, v47
	v_cmp_lt_f32_e64 s[40:41], 0, v48
	s_nop 1
	v_cndmask_b32_e64 v48, v49, v50, s[40:41]
	v_mul_f32_e32 v49, 0x37800000, v48
	v_cndmask_b32_e32 v48, v48, v49, vcc
	v_cmp_class_f32_e32 vcc, v47, v226
	s_nop 1
	v_cndmask_b32_e32 v47, v48, v47, vcc
	v_div_scale_f32 v48, s[16:17], v47, v47, 1.0
	v_rcp_f32_e32 v49, v48
	s_nop 0
	v_fma_f32 v50, -v48, v49, 1.0
	v_fmac_f32_e32 v49, v50, v49
	v_div_scale_f32 v50, vcc, 1.0, v47, 1.0
	v_mul_f32_e32 v51, v50, v49
	v_fma_f32 v52, -v48, v51, v50
	v_fmac_f32_e32 v51, v52, v49
	v_fma_f32 v48, -v48, v51, v50
	v_div_fmas_f32 v48, v48, v49, v51
	v_div_fixup_f32 v47, v48, v47, 1.0
	v_mul_f32_e32 v48, 0x3c010204, v5
	v_mul_f32_e32 v47, v48, v47
	global_store_dword v115, v47, s[8:9]
.Lxqb_C3:
	s_or_b64 exec, exec, s[6:7]
	v_div_scale_f32 v47, s[6:7], v5, v5, s47
	s_waitcnt lgkmcnt(0)
	v_rcp_f32_e32 v48, v47
	v_div_scale_f32 v49, vcc, s47, v5, s47
	s_add_i32 s22, s22, -1
	v_fma_f32 v50, -v47, v48, 1.0
	v_fmac_f32_e32 v48, v50, v48
	v_mul_f32_e32 v50, v49, v48
	v_fma_f32 v51, -v47, v50, v49
	v_fmac_f32_e32 v50, v51, v48
	v_fma_f32 v47, -v47, v50, v49
	v_div_fmas_f32 v47, v47, v48, v50
	v_div_fixup_f32 v5, v47, v5, s47
	v_mul_f32_e32 v45, v5, v45
	v_mul_f32_e32 v44, v5, v44
	v_mul_f32_e32 v46, v5, v46
	v_rndne_f32_e32 v45, v45
	v_rndne_f32_e32 v44, v44
	v_mul_f32_e32 v43, v5, v43
	v_rndne_f32_e32 v46, v46
	v_cvt_i32_f32_e32 v45, v45
	v_cvt_i32_f32_e32 v44, v44
	v_rndne_f32_e32 v43, v43
	v_mul_f32_e32 v41, v5, v41
	v_mul_f32_e32 v40, v5, v40
	v_cvt_i32_f32_e32 v46, v46
	v_cvt_i32_f32_e32 v43, v43
	v_mul_f32_e32 v42, v5, v42
	v_rndne_f32_e32 v41, v41
	v_rndne_f32_e32 v40, v40
	v_mul_f32_e32 v39, v5, v39
	v_rndne_f32_e32 v42, v42
	v_cvt_i32_f32_e32 v41, v41
	v_cvt_i32_f32_e32 v40, v40
	v_rndne_f32_e32 v39, v39
	v_cvt_i32_f32_e32 v47, v42
	v_cvt_i32_f32_e32 v39, v39
	v_med3_i32 v45, v45, s71, v235
	v_med3_i32 v44, v44, s71, v235
	v_mul_f32_e32 v37, v5, v37
	v_mul_f32_e32 v36, v5, v36
	v_med3_i32 v46, v46, s71, v235
	v_lshlrev_b32_e32 v45, 8, v45
	v_lshlrev_b32_e32 v44, 16, v44
	v_med3_i32 v43, v43, s71, v235
	v_mul_f32_e32 v38, v5, v38
	v_rndne_f32_e32 v37, v37
	v_rndne_f32_e32 v36, v36
	v_mul_f32_e32 v35, v5, v35
	v_and_b32_e32 v44, 0xff0000, v44
	v_lshlrev_b32_e32 v43, 24, v43
	v_perm_b32 v42, v45, v46, s49
	v_med3_i32 v41, v41, s71, v235
	v_med3_i32 v40, v40, s71, v235
	v_rndne_f32_e32 v38, v38
	v_cvt_i32_f32_e32 v37, v37
	v_cvt_i32_f32_e32 v36, v36
	v_rndne_f32_e32 v35, v35
	v_mul_f32_e32 v33, v5, v33
	v_mul_f32_e32 v32, v5, v32
	v_or3_b32 v42, v42, v43, v44
	v_med3_i32 v43, v47, s71, v235
	v_lshlrev_b32_e32 v41, 8, v41
	v_lshlrev_b32_e32 v40, 16, v40
	v_med3_i32 v39, v39, s71, v235
	v_cvt_i32_f32_e32 v38, v38
	v_cvt_i32_f32_e32 v35, v35
	v_mul_f32_e32 v34, v5, v34
	v_rndne_f32_e32 v33, v33
	v_rndne_f32_e32 v32, v32
	v_mul_f32_e32 v31, v5, v31
	v_and_b32_e32 v41, 0xff00, v41
	v_and_b32_e32 v40, 0xff0000, v40
	v_perm_b32 v39, v39, v43, s48
	v_rndne_f32_e32 v34, v34
	v_cvt_i32_f32_e32 v33, v33
	v_cvt_i32_f32_e32 v32, v32
	v_rndne_f32_e32 v31, v31
	v_or3_b32 v43, v39, v41, v40
	v_cvt_i32_f32_e32 v39, v34
	v_cvt_i32_f32_e32 v31, v31
	v_med3_i32 v37, v37, s71, v235
	v_med3_i32 v36, v36, s71, v235
	v_mul_f32_e32 v17, v5, v17
	v_mul_f32_e32 v16, v5, v16
	v_med3_i32 v38, v38, s71, v235
	v_lshlrev_b32_e32 v37, 8, v37
	v_lshlrev_b32_e32 v36, 16, v36
	v_med3_i32 v35, v35, s71, v235
	v_mul_f32_e32 v30, v5, v30
	v_rndne_f32_e32 v17, v17
	v_rndne_f32_e32 v16, v16
	v_mul_f32_e32 v15, v5, v15
	v_and_b32_e32 v36, 0xff0000, v36
	v_lshlrev_b32_e32 v35, 24, v35
	v_perm_b32 v34, v37, v38, s49
	v_med3_i32 v33, v33, s71, v235
	v_med3_i32 v32, v32, s71, v235
	v_rndne_f32_e32 v30, v30
	v_cvt_i32_f32_e32 v17, v17
	v_cvt_i32_f32_e32 v16, v16
	v_rndne_f32_e32 v15, v15
	v_mul_f32_e32 v13, v5, v13
	v_mul_f32_e32 v12, v5, v12
	v_or3_b32 v34, v34, v35, v36
	v_med3_i32 v35, v39, s71, v235
	v_lshlrev_b32_e32 v33, 8, v33
	v_lshlrev_b32_e32 v32, 16, v32
	v_med3_i32 v31, v31, s71, v235
	v_cvt_i32_f32_e32 v30, v30
	v_cvt_i32_f32_e32 v15, v15
	v_mul_f32_e32 v14, v5, v14
	v_rndne_f32_e32 v13, v13
	v_rndne_f32_e32 v12, v12
	v_mul_f32_e32 v11, v5, v11
	v_and_b32_e32 v33, 0xff00, v33
	v_and_b32_e32 v32, 0xff0000, v32
	v_perm_b32 v31, v31, v35, s48
	v_rndne_f32_e32 v14, v14
	v_cvt_i32_f32_e32 v13, v13
	v_cvt_i32_f32_e32 v12, v12
	v_rndne_f32_e32 v11, v11
	v_or3_b32 v35, v31, v33, v32
	v_cvt_i32_f32_e32 v31, v14
	v_cvt_i32_f32_e32 v11, v11
	v_med3_i32 v17, v17, s71, v235
	v_med3_i32 v16, v16, s71, v235
	v_mul_f32_e32 v9, v5, v9
	v_mul_f32_e32 v8, v5, v8
	v_med3_i32 v30, v30, s71, v235
	v_lshlrev_b32_e32 v17, 8, v17
	v_lshlrev_b32_e32 v16, 16, v16
	v_med3_i32 v15, v15, s71, v235
	v_mul_f32_e32 v10, v5, v10
	v_rndne_f32_e32 v9, v9
	v_rndne_f32_e32 v8, v8
	v_mul_f32_e32 v7, v5, v7
	v_and_b32_e32 v16, 0xff0000, v16
	v_lshlrev_b32_e32 v15, 24, v15
	v_perm_b32 v14, v17, v30, s49
	v_med3_i32 v13, v13, s71, v235
	v_med3_i32 v12, v12, s71, v235
	v_rndne_f32_e32 v10, v10
	v_cvt_i32_f32_e32 v9, v9
	v_cvt_i32_f32_e32 v8, v8
	v_rndne_f32_e32 v7, v7
	v_or3_b32 v14, v14, v15, v16
	v_med3_i32 v15, v31, s71, v235
	v_lshlrev_b32_e32 v13, 8, v13
	v_lshlrev_b32_e32 v12, 16, v12
	v_med3_i32 v11, v11, s71, v235
	v_cvt_i32_f32_e32 v10, v10
	v_cvt_i32_f32_e32 v7, v7
	v_mul_f32_e32 v4, v5, v4
	v_mul_f32_e32 v3, v5, v3
	v_and_b32_e32 v13, 0xff00, v13
	v_and_b32_e32 v12, 0xff0000, v12
	v_perm_b32 v11, v11, v15, s48
	v_mul_f32_e32 v6, v5, v6
	v_rndne_f32_e32 v4, v4
	v_rndne_f32_e32 v3, v3
	v_mul_f32_e32 v2, v5, v2
	v_or3_b32 v15, v11, v13, v12
	v_rndne_f32_e32 v6, v6
	v_cvt_i32_f32_e32 v11, v4
	v_cvt_i32_f32_e32 v3, v3
	v_rndne_f32_e32 v2, v2
	v_med3_i32 v9, v9, s71, v235
	v_med3_i32 v8, v8, s71, v235
	v_cvt_i32_f32_e32 v6, v6
	v_cvt_i32_f32_e32 v2, v2
	v_med3_i32 v10, v10, s71, v235
	v_lshlrev_b32_e32 v9, 8, v9
	v_lshlrev_b32_e32 v8, 16, v8
	v_med3_i32 v7, v7, s71, v235
	v_and_b32_e32 v8, 0xff0000, v8
	v_lshlrev_b32_e32 v7, 24, v7
	v_perm_b32 v4, v9, v10, s49
	v_or3_b32 v4, v4, v7, v8
	v_med3_i32 v7, v11, s71, v235
	v_med3_i32 v3, v3, s71, v235
	v_med3_i32 v6, v6, s71, v235
	v_lshlrev_b32_e32 v7, 8, v7
	v_lshlrev_b32_e32 v3, 16, v3
	v_med3_i32 v2, v2, s71, v235
	v_and_b32_e32 v7, 0xff00, v7
	v_and_b32_e32 v3, 0xff0000, v3
	v_perm_b32 v2, v2, v6, s48
	s_add_u32 s8, s8, s10
	v_or3_b32 v5, v2, v7, v3
	s_addc_u32 s9, s9, s11
	global_store_dwordx2 v[22:23], v[42:43], off offset:-1024
	global_store_dwordx2 v[22:23], v[34:35], off offset:-512
	global_store_dwordx2 v[22:23], v[14:15], off
	global_store_dwordx2 v[22:23], v[4:5], off offset:512
	v_lshl_add_u64 v[18:19], v[18:19], 0, s[12:13]
	v_lshl_add_u64 v[20:21], v[20:21], 0, s[14:15]
	v_lshl_add_u64 v[22:23], v[22:23], 0, s[0:1]
	s_cmp_lt_i32 s22, 4
	s_cbranch_scc0 .Lxqb_top
	s_cmp_eq_u32 s22, 0
	s_cbranch_scc1 .LBB0_1042
	s_branch .LBB0_1038
